# v18 with the three waits at each K-loop stage head (vmcnt(8), lgkmcnt(0), duplicate lgkmcnt(0)) merged into one s_waitcnt
# baseline (speedup 1.0000x reference)
.LBB0_285:
	ds_read_b128 v[154:157], v151
	ds_read_b128 v[158:161], v151 offset:1024
	ds_read_b128 v[164:167], v151 offset:2048
	ds_read_b128 v[168:171], v151 offset:3072
	ds_read_b128 v[172:175], v152
	ds_read_b128 v[176:179], v152 offset:1024
	ds_read_b128 v[180:183], v152 offset:2048
	ds_read_b128 v[184:187], v152 offset:3072
	s_add_u32 s36, s34, 0xfff80080
	s_addc_u32 s37, s35, -1
	s_cmp_eq_u32 s53, 28
	s_cselect_b32 s39, s16, s37
	s_cselect_b32 s38, s17, s36
	s_cselect_b32 s37, s18, s25
	s_cselect_b32 s36, s19, s23
	v_lshl_add_u64 v[146:147], s[34:35], 0, v[138:139]
	s_add_i32 m0, s31, 0xc000
	ds_read_b128 v[188:191], v153
	ds_read_b128 v[192:195], v153 offset:1024
	ds_read_b128 v[196:199], v153 offset:2048
	ds_read_b128 v[200:203], v153 offset:3072
	ds_read_b128 v[204:207], v153 offset:4096
	ds_read_b128 v[208:211], v153 offset:5120
	ds_read_b128 v[212:215], v153 offset:6144
	ds_read_b128 v[216:219], v153 offset:7168
	global_load_lds_dwordx4 v[146:147], off
	v_lshl_add_u64 v[146:147], s[34:35], 0, v[140:141]
	s_add_i32 m0, s31, 0xe000
	s_nop 0
	global_load_lds_dwordx4 v[146:147], off
	s_waitcnt vmcnt(8) lgkmcnt(0)
	v_mfma_f32_16x16x32_bf16 v[126:129], v[154:157], v[188:191], v[126:129]
	v_mfma_f32_16x16x32_bf16 v[122:125], v[164:167], v[188:191], v[122:125]
	v_mfma_f32_16x16x32_bf16 v[110:113], v[154:157], v[196:199], v[110:113]
	v_mfma_f32_16x16x32_bf16 v[106:109], v[164:167], v[196:199], v[106:109]
	s_barrier
	s_setprio 1
	v_mfma_f32_16x16x32_bf16 v[94:97], v[154:157], v[204:207], v[94:97]
	v_mfma_f32_16x16x32_bf16 v[90:93], v[164:167], v[204:207], v[90:93]
	v_mfma_f32_16x16x32_bf16 v[78:81], v[154:157], v[212:215], v[78:81]
	v_mfma_f32_16x16x32_bf16 v[74:77], v[164:167], v[212:215], v[74:77]
	v_mfma_f32_16x16x32_bf16 v[126:129], v[158:161], v[192:195], v[126:129]
	v_mfma_f32_16x16x32_bf16 v[122:125], v[168:171], v[192:195], v[122:125]
	v_mfma_f32_16x16x32_bf16 v[110:113], v[158:161], v[200:203], v[110:113]
	v_mfma_f32_16x16x32_bf16 v[106:109], v[168:171], v[200:203], v[106:109]
	v_mfma_f32_16x16x32_bf16 v[94:97], v[158:161], v[208:211], v[94:97]
	v_mfma_f32_16x16x32_bf16 v[90:93], v[168:171], v[208:211], v[90:93]
	v_mfma_f32_16x16x32_bf16 v[78:81], v[158:161], v[216:219], v[78:81]
	v_mfma_f32_16x16x32_bf16 v[74:77], v[168:171], v[216:219], v[74:77]
	v_mfma_f32_16x16x32_bf16 v[118:121], v[172:175], v[188:191], v[118:121]
	v_mfma_f32_16x16x32_bf16 v[114:117], v[180:183], v[188:191], v[114:117]
	v_mfma_f32_16x16x32_bf16 v[102:105], v[172:175], v[196:199], v[102:105]
	v_mfma_f32_16x16x32_bf16 v[98:101], v[180:183], v[196:199], v[98:101]
	v_mfma_f32_16x16x32_bf16 v[86:89], v[172:175], v[204:207], v[86:89]
	v_mfma_f32_16x16x32_bf16 v[82:85], v[180:183], v[204:207], v[82:85]
	v_mfma_f32_16x16x32_bf16 v[70:73], v[172:175], v[212:215], v[70:73]
	v_mfma_f32_16x16x32_bf16 v[66:69], v[180:183], v[212:215], v[66:69]
	v_mfma_f32_16x16x32_bf16 v[118:121], v[176:179], v[192:195], v[118:121]
	v_mfma_f32_16x16x32_bf16 v[114:117], v[184:187], v[192:195], v[114:117]
	v_mfma_f32_16x16x32_bf16 v[102:105], v[176:179], v[200:203], v[102:105]
	v_mfma_f32_16x16x32_bf16 v[98:101], v[184:187], v[200:203], v[98:101]
	v_mfma_f32_16x16x32_bf16 v[86:89], v[176:179], v[208:211], v[86:89]
	v_mfma_f32_16x16x32_bf16 v[82:85], v[184:187], v[208:211], v[82:85]
	v_mfma_f32_16x16x32_bf16 v[70:73], v[176:179], v[216:219], v[70:73]
	v_mfma_f32_16x16x32_bf16 v[66:69], v[184:187], v[216:219], v[66:69]
	s_setprio 0
	s_barrier
	s_add_i32 s54, s15, s44
	v_lshl_add_u64 v[146:147], s[36:37], 0, v[134:135]
	s_mov_b32 m0, s54
	ds_read_b128 v[188:191], v153 offset:16384
	ds_read_b128 v[192:195], v153 offset:17408
	ds_read_b128 v[196:199], v153 offset:18432
	ds_read_b128 v[200:203], v153 offset:19456
	ds_read_b128 v[204:207], v153 offset:20480
	ds_read_b128 v[208:211], v153 offset:21504
	ds_read_b128 v[212:215], v153 offset:22528
	ds_read_b128 v[216:219], v153 offset:23552
	global_load_lds_dwordx4 v[146:147], off
	s_add_i32 m0, s54, 0x2000
	s_add_u32 s54, s36, 0x80000
	v_lshl_add_u64 v[220:221], s[36:37], 0, v[130:131]
	s_addc_u32 s55, s37, 0
	s_add_i32 s56, s51, s44
	global_load_lds_dwordx4 v[220:221], off
	v_lshl_add_u64 v[222:223], s[54:55], 0, v[134:135]
	s_mov_b32 m0, s56
	v_lshl_add_u64 v[224:225], s[38:39], 0, v[132:133]
	global_load_lds_dwordx4 v[222:223], off
	v_lshl_add_u64 v[222:223], s[54:55], 0, v[130:131]
	s_add_i32 m0, s56, 0x2000
	s_nop 0
	global_load_lds_dwordx4 v[222:223], off
	v_lshl_add_u64 v[222:223], s[38:39], 0, v[136:137]
	s_mov_b32 m0, s31
	s_nop 0
	global_load_lds_dwordx4 v[222:223], off
	s_mov_b32 m0, s47
	s_nop 0
	global_load_lds_dwordx4 v[224:225], off
	s_waitcnt vmcnt(8) lgkmcnt(0)
	v_mfma_f32_16x16x32_bf16 v[62:65], v[154:157], v[188:191], v[62:65]
	v_mfma_f32_16x16x32_bf16 v[58:61], v[164:167], v[188:191], v[58:61]
	v_mfma_f32_16x16x32_bf16 v[46:49], v[154:157], v[196:199], v[46:49]
	v_mfma_f32_16x16x32_bf16 v[42:45], v[164:167], v[196:199], v[42:45]
	s_barrier
	s_setprio 1
	v_mfma_f32_16x16x32_bf16 v[30:33], v[154:157], v[204:207], v[30:33]
	v_mfma_f32_16x16x32_bf16 v[26:29], v[164:167], v[204:207], v[26:29]
	v_mfma_f32_16x16x32_bf16 v[14:17], v[154:157], v[212:215], v[14:17]
	v_mfma_f32_16x16x32_bf16 v[10:13], v[164:167], v[212:215], v[10:13]
	v_mfma_f32_16x16x32_bf16 v[62:65], v[158:161], v[192:195], v[62:65]
	v_mfma_f32_16x16x32_bf16 v[58:61], v[168:171], v[192:195], v[58:61]
	v_mfma_f32_16x16x32_bf16 v[46:49], v[158:161], v[200:203], v[46:49]
	v_mfma_f32_16x16x32_bf16 v[42:45], v[168:171], v[200:203], v[42:45]
	v_mfma_f32_16x16x32_bf16 v[30:33], v[158:161], v[208:211], v[30:33]
	v_mfma_f32_16x16x32_bf16 v[26:29], v[168:171], v[208:211], v[26:29]
	v_mfma_f32_16x16x32_bf16 v[14:17], v[158:161], v[216:219], v[14:17]
	v_mfma_f32_16x16x32_bf16 v[10:13], v[168:171], v[216:219], v[10:13]
	v_mfma_f32_16x16x32_bf16 v[54:57], v[172:175], v[188:191], v[54:57]
	v_mfma_f32_16x16x32_bf16 v[50:53], v[180:183], v[188:191], v[50:53]
	v_mfma_f32_16x16x32_bf16 v[38:41], v[172:175], v[196:199], v[38:41]
	v_mfma_f32_16x16x32_bf16 v[34:37], v[180:183], v[196:199], v[34:37]
	v_mfma_f32_16x16x32_bf16 v[22:25], v[172:175], v[204:207], v[22:25]
	v_mfma_f32_16x16x32_bf16 v[18:21], v[180:183], v[204:207], v[18:21]
	v_mfma_f32_16x16x32_bf16 v[6:9], v[172:175], v[212:215], v[6:9]
	v_mfma_f32_16x16x32_bf16 v[2:5], v[180:183], v[212:215], v[2:5]
	v_mfma_f32_16x16x32_bf16 v[54:57], v[176:179], v[192:195], v[54:57]
	v_mfma_f32_16x16x32_bf16 v[50:53], v[184:187], v[192:195], v[50:53]
	v_mfma_f32_16x16x32_bf16 v[38:41], v[176:179], v[200:203], v[38:41]
	v_mfma_f32_16x16x32_bf16 v[34:37], v[184:187], v[200:203], v[34:37]
	v_mfma_f32_16x16x32_bf16 v[22:25], v[176:179], v[208:211], v[22:25]
	v_mfma_f32_16x16x32_bf16 v[18:21], v[184:187], v[208:211], v[18:21]
	v_mfma_f32_16x16x32_bf16 v[6:9], v[176:179], v[216:219], v[6:9]
	v_mfma_f32_16x16x32_bf16 v[2:5], v[184:187], v[216:219], v[2:5]
	s_setprio 0
	s_barrier
	s_add_i32 s54, 0, 0x18000
	v_add_u32_e32 v163, s54, v149
	s_add_i32 s55, 0, 0x1c000
	ds_read_b128 v[154:157], v163
	ds_read_b128 v[158:161], v163 offset:1024
	ds_read_b128 v[164:167], v163 offset:2048
	ds_read_b128 v[168:171], v163 offset:3072
	v_add_u32_e32 v163, s55, v149
	ds_read_b128 v[172:175], v163
	ds_read_b128 v[176:179], v163 offset:1024
	ds_read_b128 v[180:183], v163 offset:2048
	ds_read_b128 v[184:187], v163 offset:3072
	s_add_u32 s38, s38, 0x80000
	s_addc_u32 s39, s39, 0
	s_mov_b32 m0, s48
	v_lshl_add_u64 v[226:227], s[38:39], 0, v[136:137]
	ds_read_b128 v[188:191], v153 offset:32768
	ds_read_b128 v[192:195], v153 offset:33792
	ds_read_b128 v[196:199], v153 offset:34816
	ds_read_b128 v[200:203], v153 offset:35840
	ds_read_b128 v[204:207], v153 offset:36864
	ds_read_b128 v[208:211], v153 offset:37888
	ds_read_b128 v[212:215], v153 offset:38912
	ds_read_b128 v[216:219], v153 offset:39936
	global_load_lds_dwordx4 v[226:227], off
	v_lshl_add_u64 v[226:227], s[38:39], 0, v[132:133]
	s_mov_b32 m0, s49
	s_nop 0
	global_load_lds_dwordx4 v[226:227], off
	s_waitcnt vmcnt(8) lgkmcnt(0)
	v_mfma_f32_16x16x32_bf16 v[126:129], v[154:157], v[188:191], v[126:129]
	v_mfma_f32_16x16x32_bf16 v[122:125], v[164:167], v[188:191], v[122:125]
	v_mfma_f32_16x16x32_bf16 v[110:113], v[154:157], v[196:199], v[110:113]
	v_mfma_f32_16x16x32_bf16 v[106:109], v[164:167], v[196:199], v[106:109]
	s_barrier
	s_setprio 1
	v_mfma_f32_16x16x32_bf16 v[94:97], v[154:157], v[204:207], v[94:97]
	v_mfma_f32_16x16x32_bf16 v[90:93], v[164:167], v[204:207], v[90:93]
	v_mfma_f32_16x16x32_bf16 v[78:81], v[154:157], v[212:215], v[78:81]
	v_mfma_f32_16x16x32_bf16 v[74:77], v[164:167], v[212:215], v[74:77]
	v_mfma_f32_16x16x32_bf16 v[126:129], v[158:161], v[192:195], v[126:129]
	v_mfma_f32_16x16x32_bf16 v[122:125], v[168:171], v[192:195], v[122:125]
	v_mfma_f32_16x16x32_bf16 v[110:113], v[158:161], v[200:203], v[110:113]
	v_mfma_f32_16x16x32_bf16 v[106:109], v[168:171], v[200:203], v[106:109]
	v_mfma_f32_16x16x32_bf16 v[94:97], v[158:161], v[208:211], v[94:97]
	v_mfma_f32_16x16x32_bf16 v[90:93], v[168:171], v[208:211], v[90:93]
	v_mfma_f32_16x16x32_bf16 v[78:81], v[158:161], v[216:219], v[78:81]
	v_mfma_f32_16x16x32_bf16 v[74:77], v[168:171], v[216:219], v[74:77]
	v_mfma_f32_16x16x32_bf16 v[118:121], v[172:175], v[188:191], v[118:121]
	v_mfma_f32_16x16x32_bf16 v[114:117], v[180:183], v[188:191], v[114:117]
	v_mfma_f32_16x16x32_bf16 v[102:105], v[172:175], v[196:199], v[102:105]
	v_mfma_f32_16x16x32_bf16 v[98:101], v[180:183], v[196:199], v[98:101]
	v_mfma_f32_16x16x32_bf16 v[86:89], v[172:175], v[204:207], v[86:89]
	v_mfma_f32_16x16x32_bf16 v[82:85], v[180:183], v[204:207], v[82:85]
	v_mfma_f32_16x16x32_bf16 v[70:73], v[172:175], v[212:215], v[70:73]
	v_mfma_f32_16x16x32_bf16 v[66:69], v[180:183], v[212:215], v[66:69]
	v_mfma_f32_16x16x32_bf16 v[118:121], v[176:179], v[192:195], v[118:121]
	v_mfma_f32_16x16x32_bf16 v[114:117], v[184:187], v[192:195], v[114:117]
	v_mfma_f32_16x16x32_bf16 v[102:105], v[176:179], v[200:203], v[102:105]
	v_mfma_f32_16x16x32_bf16 v[98:101], v[184:187], v[200:203], v[98:101]
	v_mfma_f32_16x16x32_bf16 v[86:89], v[176:179], v[208:211], v[86:89]
	v_mfma_f32_16x16x32_bf16 v[82:85], v[184:187], v[208:211], v[82:85]
	v_mfma_f32_16x16x32_bf16 v[70:73], v[176:179], v[216:219], v[70:73]
	v_mfma_f32_16x16x32_bf16 v[66:69], v[184:187], v[216:219], v[66:69]
	s_setprio 0
	s_barrier
	s_add_i32 s38, s54, s44
	v_lshl_add_u64 v[146:147], v[146:147], 0, s[10:11]
	s_mov_b32 m0, s38
	ds_read_b128 v[188:191], v153 offset:49152
	ds_read_b128 v[192:195], v153 offset:50176
	ds_read_b128 v[196:199], v153 offset:51200
	ds_read_b128 v[200:203], v153 offset:52224
	ds_read_b128 v[204:207], v153 offset:53248
	ds_read_b128 v[208:211], v153 offset:54272
	ds_read_b128 v[212:215], v153 offset:55296
	ds_read_b128 v[216:219], v153 offset:56320
	global_load_lds_dwordx4 v[146:147], off
	s_add_i32 m0, s38, 0x2000
	s_add_u32 s36, s36, 0x80080
	v_lshl_add_u64 v[146:147], v[220:221], 0, s[10:11]
	s_addc_u32 s37, s37, 0
	s_add_i32 s38, s55, s44
	global_load_lds_dwordx4 v[146:147], off
	v_lshl_add_u64 v[146:147], s[36:37], 0, v[134:135]
	s_mov_b32 m0, s38
	s_nop 0
	global_load_lds_dwordx4 v[146:147], off
	v_lshl_add_u64 v[146:147], s[36:37], 0, v[130:131]
	s_add_i32 m0, s38, 0x2000
	s_nop 0
	global_load_lds_dwordx4 v[146:147], off
	v_lshl_add_u64 v[146:147], v[222:223], 0, s[10:11]
	s_mov_b32 m0, s20
	s_nop 0
	global_load_lds_dwordx4 v[146:147], off
	v_lshl_add_u64 v[146:147], v[224:225], 0, s[10:11]
	s_mov_b32 m0, s21
	s_nop 0
	global_load_lds_dwordx4 v[146:147], off
	s_waitcnt vmcnt(8) lgkmcnt(0)
	v_mfma_f32_16x16x32_bf16 v[62:65], v[154:157], v[188:191], v[62:65]
	v_mfma_f32_16x16x32_bf16 v[58:61], v[164:167], v[188:191], v[58:61]
	v_mfma_f32_16x16x32_bf16 v[46:49], v[154:157], v[196:199], v[46:49]
	v_mfma_f32_16x16x32_bf16 v[42:45], v[164:167], v[196:199], v[42:45]
	s_barrier
	s_setprio 1
	v_mfma_f32_16x16x32_bf16 v[30:33], v[154:157], v[204:207], v[30:33]
	v_mfma_f32_16x16x32_bf16 v[26:29], v[164:167], v[204:207], v[26:29]
	v_mfma_f32_16x16x32_bf16 v[14:17], v[154:157], v[212:215], v[14:17]
	v_mfma_f32_16x16x32_bf16 v[10:13], v[164:167], v[212:215], v[10:13]
	v_mfma_f32_16x16x32_bf16 v[62:65], v[158:161], v[192:195], v[62:65]
	v_mfma_f32_16x16x32_bf16 v[58:61], v[168:171], v[192:195], v[58:61]
	v_mfma_f32_16x16x32_bf16 v[46:49], v[158:161], v[200:203], v[46:49]
	v_mfma_f32_16x16x32_bf16 v[42:45], v[168:171], v[200:203], v[42:45]
	v_mfma_f32_16x16x32_bf16 v[30:33], v[158:161], v[208:211], v[30:33]
	v_mfma_f32_16x16x32_bf16 v[26:29], v[168:171], v[208:211], v[26:29]
	v_mfma_f32_16x16x32_bf16 v[14:17], v[158:161], v[216:219], v[14:17]
	v_mfma_f32_16x16x32_bf16 v[10:13], v[168:171], v[216:219], v[10:13]
	v_mfma_f32_16x16x32_bf16 v[54:57], v[172:175], v[188:191], v[54:57]
	v_mfma_f32_16x16x32_bf16 v[50:53], v[180:183], v[188:191], v[50:53]
	v_mfma_f32_16x16x32_bf16 v[38:41], v[172:175], v[196:199], v[38:41]
	v_mfma_f32_16x16x32_bf16 v[34:37], v[180:183], v[196:199], v[34:37]
	v_mfma_f32_16x16x32_bf16 v[22:25], v[172:175], v[204:207], v[22:25]
	v_mfma_f32_16x16x32_bf16 v[18:21], v[180:183], v[204:207], v[18:21]
	v_mfma_f32_16x16x32_bf16 v[6:9], v[172:175], v[212:215], v[6:9]
	v_mfma_f32_16x16x32_bf16 v[2:5], v[180:183], v[212:215], v[2:5]
	v_mfma_f32_16x16x32_bf16 v[54:57], v[176:179], v[192:195], v[54:57]
	v_mfma_f32_16x16x32_bf16 v[50:53], v[184:187], v[192:195], v[50:53]
	v_mfma_f32_16x16x32_bf16 v[38:41], v[176:179], v[200:203], v[38:41]
	v_mfma_f32_16x16x32_bf16 v[34:37], v[184:187], v[200:203], v[34:37]
	v_mfma_f32_16x16x32_bf16 v[22:25], v[176:179], v[208:211], v[22:25]
	v_mfma_f32_16x16x32_bf16 v[18:21], v[184:187], v[208:211], v[18:21]
	v_mfma_f32_16x16x32_bf16 v[6:9], v[176:179], v[216:219], v[6:9]
	v_mfma_f32_16x16x32_bf16 v[2:5], v[184:187], v[216:219], v[2:5]
	s_setprio 0
	s_barrier
	s_add_i32 s53, s53, 2
	s_add_u32 s34, s34, 0x100
	s_addc_u32 s35, s35, 0
	s_add_u32 s23, s23, 0x100
	s_addc_u32 s25, s25, 0
	s_cmp_gt_u32 s53, 29
	s_cbranch_scc0 .LBB0_285
	s_and_b64 vcc, exec, s[12:13]
	s_cbranch_vccz .LBB0_288
	s_barrier

.LBB0_356:
	ds_read_b128 v[134:137], v213
	ds_read_b128 v[138:141], v213 offset:1024
	ds_read_b128 v[142:145], v213 offset:2048
	ds_read_b128 v[178:181], v213 offset:3072
	ds_read_b128 v[182:185], v214
	ds_read_b128 v[186:189], v214 offset:1024
	ds_read_b128 v[190:193], v214 offset:2048
	ds_read_b128 v[194:197], v214 offset:3072
	s_add_u32 s36, s34, 0x100
	s_addc_u32 s37, s35, 0
	s_add_u32 s16, s3, s34
	s_addc_u32 s17, s14, s35
	s_cmpk_eq_i32 s15, 0x54
	s_cselect_b32 s41, s27, s17
	s_cselect_b32 s17, 0, s36
	s_cselect_b32 s40, s26, s16
	s_cselect_b32 s16, 0, s37
	s_add_u32 s38, s8, s17
	s_addc_u32 s39, s9, s16
	s_mov_b32 m0, s63
	v_lshl_add_u64 v[244:245], v[130:131], 0, s[34:35]
	ds_read_b128 v[198:201], v215
	ds_read_b128 v[202:205], v215 offset:1024
	ds_read_b128 v[206:209], v215 offset:2048
	ds_read_b128 v[224:227], v215 offset:3072
	ds_read_b128 v[228:231], v215 offset:4096
	ds_read_b128 v[232:235], v215 offset:5120
	ds_read_b128 v[236:239], v215 offset:6144
	ds_read_b128 v[240:243], v215 offset:7168
	global_load_lds_dwordx4 v[244:245], off
	v_lshl_add_u64 v[244:245], v[132:133], 0, s[34:35]
	s_mov_b32 m0, s64
	s_nop 0
	global_load_lds_dwordx4 v[244:245], off
	s_waitcnt vmcnt(8) lgkmcnt(0)
	v_mfma_f32_16x16x32_bf16 v[86:89], v[134:137], v[198:201], v[86:89]
	v_mfma_f32_16x16x32_bf16 v[82:85], v[142:145], v[198:201], v[82:85]
	v_mfma_f32_16x16x32_bf16 v[110:113], v[134:137], v[206:209], v[110:113]
	v_mfma_f32_16x16x32_bf16 v[106:109], v[142:145], v[206:209], v[106:109]
	s_barrier
	s_setprio 1
	v_mfma_f32_16x16x32_bf16 v[118:121], v[134:137], v[228:231], v[118:121]
	v_mfma_f32_16x16x32_bf16 v[114:117], v[142:145], v[228:231], v[114:117]
	v_mfma_f32_16x16x32_bf16 v[126:129], v[134:137], v[236:239], v[126:129]
	v_mfma_f32_16x16x32_bf16 v[122:125], v[142:145], v[236:239], v[122:125]
	v_mfma_f32_16x16x32_bf16 v[86:89], v[138:141], v[202:205], v[86:89]
	v_mfma_f32_16x16x32_bf16 v[82:85], v[178:181], v[202:205], v[82:85]
	v_mfma_f32_16x16x32_bf16 v[110:113], v[138:141], v[224:227], v[110:113]
	v_mfma_f32_16x16x32_bf16 v[106:109], v[178:181], v[224:227], v[106:109]
	v_mfma_f32_16x16x32_bf16 v[118:121], v[138:141], v[232:235], v[118:121]
	v_mfma_f32_16x16x32_bf16 v[114:117], v[178:181], v[232:235], v[114:117]
	v_mfma_f32_16x16x32_bf16 v[126:129], v[138:141], v[240:243], v[126:129]
	v_mfma_f32_16x16x32_bf16 v[122:125], v[178:181], v[240:243], v[122:125]
	v_mfma_f32_16x16x32_bf16 v[26:29], v[182:185], v[198:201], v[26:29]
	v_mfma_f32_16x16x32_bf16 v[30:33], v[190:193], v[198:201], v[30:33]
	v_mfma_f32_16x16x32_bf16 v[42:45], v[182:185], v[206:209], v[42:45]
	v_mfma_f32_16x16x32_bf16 v[50:53], v[190:193], v[206:209], v[50:53]
	v_mfma_f32_16x16x32_bf16 v[66:69], v[182:185], v[228:231], v[66:69]
	v_mfma_f32_16x16x32_bf16 v[70:73], v[190:193], v[228:231], v[70:73]
	v_mfma_f32_16x16x32_bf16 v[90:93], v[182:185], v[236:239], v[90:93]
	v_mfma_f32_16x16x32_bf16 v[94:97], v[190:193], v[236:239], v[94:97]
	v_mfma_f32_16x16x32_bf16 v[26:29], v[186:189], v[202:205], v[26:29]
	v_mfma_f32_16x16x32_bf16 v[30:33], v[194:197], v[202:205], v[30:33]
	v_mfma_f32_16x16x32_bf16 v[42:45], v[186:189], v[224:227], v[42:45]
	v_mfma_f32_16x16x32_bf16 v[50:53], v[194:197], v[224:227], v[50:53]
	v_mfma_f32_16x16x32_bf16 v[66:69], v[186:189], v[232:235], v[66:69]
	v_mfma_f32_16x16x32_bf16 v[70:73], v[194:197], v[232:235], v[70:73]
	v_mfma_f32_16x16x32_bf16 v[90:93], v[186:189], v[240:243], v[90:93]
	v_mfma_f32_16x16x32_bf16 v[94:97], v[194:197], v[240:243], v[94:97]
	s_setprio 0
	s_barrier
	s_mov_b32 m0, s65
	v_lshl_add_u64 v[244:245], s[38:39], 0, v[150:151]
	s_add_u32 s16, s38, 0x160000
	ds_read_b128 v[198:201], v215 offset:16384
	ds_read_b128 v[202:205], v215 offset:17408
	ds_read_b128 v[206:209], v215 offset:18432
	ds_read_b128 v[224:227], v215 offset:19456
	ds_read_b128 v[228:231], v215 offset:20480
	ds_read_b128 v[232:235], v215 offset:21504
	ds_read_b128 v[236:239], v215 offset:22528
	ds_read_b128 v[240:243], v215 offset:23552
	global_load_lds_dwordx4 v[244:245], off
	v_lshl_add_u64 v[246:247], s[38:39], 0, v[146:147]
	s_mov_b32 m0, s66
	s_addc_u32 s17, s39, 0
	global_load_lds_dwordx4 v[246:247], off
	v_lshl_add_u64 v[248:249], s[16:17], 0, v[150:151]
	s_mov_b32 m0, s67
	v_lshl_add_u64 v[250:251], s[40:41], 0, v[148:149]
	global_load_lds_dwordx4 v[248:249], off
	v_lshl_add_u64 v[248:249], s[16:17], 0, v[146:147]
	s_mov_b32 m0, s68
	s_nop 0
	global_load_lds_dwordx4 v[248:249], off
	v_lshl_add_u64 v[248:249], s[40:41], 0, v[152:153]
	s_mov_b32 m0, s51
	s_nop 0
	global_load_lds_dwordx4 v[248:249], off
	s_mov_b32 m0, s52
	s_nop 0
	global_load_lds_dwordx4 v[250:251], off
	s_waitcnt vmcnt(8) lgkmcnt(0)
	v_mfma_f32_16x16x32_bf16 v[102:105], v[134:137], v[198:201], v[102:105]
	v_mfma_f32_16x16x32_bf16 v[98:101], v[142:145], v[198:201], v[98:101]
	v_mfma_f32_16x16x32_bf16 v[62:65], v[134:137], v[206:209], v[62:65]
	v_mfma_f32_16x16x32_bf16 v[58:61], v[142:145], v[206:209], v[58:61]
	s_barrier
	s_setprio 1
	v_mfma_f32_16x16x32_bf16 v[38:41], v[134:137], v[228:231], v[38:41]
	v_mfma_f32_16x16x32_bf16 v[34:37], v[142:145], v[228:231], v[34:37]
	v_mfma_f32_16x16x32_bf16 v[14:17], v[134:137], v[236:239], v[14:17]
	v_mfma_f32_16x16x32_bf16 v[10:13], v[142:145], v[236:239], v[10:13]
	v_mfma_f32_16x16x32_bf16 v[102:105], v[138:141], v[202:205], v[102:105]
	v_mfma_f32_16x16x32_bf16 v[98:101], v[178:181], v[202:205], v[98:101]
	v_mfma_f32_16x16x32_bf16 v[62:65], v[138:141], v[224:227], v[62:65]
	v_mfma_f32_16x16x32_bf16 v[58:61], v[178:181], v[224:227], v[58:61]
	v_mfma_f32_16x16x32_bf16 v[38:41], v[138:141], v[232:235], v[38:41]
	v_mfma_f32_16x16x32_bf16 v[34:37], v[178:181], v[232:235], v[34:37]
	v_mfma_f32_16x16x32_bf16 v[14:17], v[138:141], v[240:243], v[14:17]
	v_mfma_f32_16x16x32_bf16 v[10:13], v[178:181], v[240:243], v[10:13]
	v_mfma_f32_16x16x32_bf16 v[78:81], v[182:185], v[198:201], v[78:81]
	v_mfma_f32_16x16x32_bf16 v[74:77], v[190:193], v[198:201], v[74:77]
	v_mfma_f32_16x16x32_bf16 v[54:57], v[182:185], v[206:209], v[54:57]
	v_mfma_f32_16x16x32_bf16 v[46:49], v[190:193], v[206:209], v[46:49]
	v_mfma_f32_16x16x32_bf16 v[22:25], v[182:185], v[228:231], v[22:25]
	v_mfma_f32_16x16x32_bf16 v[18:21], v[190:193], v[228:231], v[18:21]
	v_mfma_f32_16x16x32_bf16 v[6:9], v[182:185], v[236:239], v[6:9]
	v_mfma_f32_16x16x32_bf16 v[2:5], v[190:193], v[236:239], v[2:5]
	v_mfma_f32_16x16x32_bf16 v[78:81], v[186:189], v[202:205], v[78:81]
	v_mfma_f32_16x16x32_bf16 v[74:77], v[194:197], v[202:205], v[74:77]
	v_mfma_f32_16x16x32_bf16 v[54:57], v[186:189], v[224:227], v[54:57]
	v_mfma_f32_16x16x32_bf16 v[46:49], v[194:197], v[224:227], v[46:49]
	v_mfma_f32_16x16x32_bf16 v[22:25], v[186:189], v[232:235], v[22:25]
	v_mfma_f32_16x16x32_bf16 v[18:21], v[194:197], v[232:235], v[18:21]
	v_mfma_f32_16x16x32_bf16 v[6:9], v[186:189], v[240:243], v[6:9]
	v_mfma_f32_16x16x32_bf16 v[2:5], v[194:197], v[240:243], v[2:5]
	s_setprio 0
	s_barrier
	ds_read_b128 v[134:137], v219
	ds_read_b128 v[138:141], v219 offset:1024
	ds_read_b128 v[142:145], v219 offset:2048
	ds_read_b128 v[178:181], v219 offset:3072
	ds_read_b128 v[182:185], v220
	ds_read_b128 v[186:189], v220 offset:1024
	ds_read_b128 v[190:193], v220 offset:2048
	ds_read_b128 v[194:197], v220 offset:3072
	s_add_u32 s16, s40, 0x160000
	s_addc_u32 s17, s41, 0
	s_mov_b32 m0, s53
	v_lshl_add_u64 v[252:253], s[16:17], 0, v[152:153]
	ds_read_b128 v[198:201], v215 offset:32768
	ds_read_b128 v[202:205], v215 offset:33792
	ds_read_b128 v[206:209], v215 offset:34816
	ds_read_b128 v[224:227], v215 offset:35840
	ds_read_b128 v[228:231], v215 offset:36864
	ds_read_b128 v[232:235], v215 offset:37888
	ds_read_b128 v[236:239], v215 offset:38912
	ds_read_b128 v[240:243], v215 offset:39936
	global_load_lds_dwordx4 v[252:253], off
	v_lshl_add_u64 v[252:253], s[16:17], 0, v[148:149]
	s_mov_b32 m0, s54
	s_nop 0
	global_load_lds_dwordx4 v[252:253], off
	s_waitcnt vmcnt(8) lgkmcnt(0)
	v_mfma_f32_16x16x32_bf16 v[86:89], v[134:137], v[198:201], v[86:89]
	v_mfma_f32_16x16x32_bf16 v[82:85], v[142:145], v[198:201], v[82:85]
	v_mfma_f32_16x16x32_bf16 v[110:113], v[134:137], v[206:209], v[110:113]
	v_mfma_f32_16x16x32_bf16 v[106:109], v[142:145], v[206:209], v[106:109]
	s_barrier
	s_setprio 1
	v_mfma_f32_16x16x32_bf16 v[118:121], v[134:137], v[228:231], v[118:121]
	v_mfma_f32_16x16x32_bf16 v[114:117], v[142:145], v[228:231], v[114:117]
	v_mfma_f32_16x16x32_bf16 v[126:129], v[134:137], v[236:239], v[126:129]
	v_mfma_f32_16x16x32_bf16 v[122:125], v[142:145], v[236:239], v[122:125]
	v_mfma_f32_16x16x32_bf16 v[86:89], v[138:141], v[202:205], v[86:89]
	v_mfma_f32_16x16x32_bf16 v[82:85], v[178:181], v[202:205], v[82:85]
	v_mfma_f32_16x16x32_bf16 v[110:113], v[138:141], v[224:227], v[110:113]
	v_mfma_f32_16x16x32_bf16 v[106:109], v[178:181], v[224:227], v[106:109]
	v_mfma_f32_16x16x32_bf16 v[118:121], v[138:141], v[232:235], v[118:121]
	v_mfma_f32_16x16x32_bf16 v[114:117], v[178:181], v[232:235], v[114:117]
	v_mfma_f32_16x16x32_bf16 v[126:129], v[138:141], v[240:243], v[126:129]
	v_mfma_f32_16x16x32_bf16 v[122:125], v[178:181], v[240:243], v[122:125]
	v_mfma_f32_16x16x32_bf16 v[26:29], v[182:185], v[198:201], v[26:29]
	v_mfma_f32_16x16x32_bf16 v[30:33], v[190:193], v[198:201], v[30:33]
	v_mfma_f32_16x16x32_bf16 v[42:45], v[182:185], v[206:209], v[42:45]
	v_mfma_f32_16x16x32_bf16 v[50:53], v[190:193], v[206:209], v[50:53]
	v_mfma_f32_16x16x32_bf16 v[66:69], v[182:185], v[228:231], v[66:69]
	v_mfma_f32_16x16x32_bf16 v[70:73], v[190:193], v[228:231], v[70:73]
	v_mfma_f32_16x16x32_bf16 v[90:93], v[182:185], v[236:239], v[90:93]
	v_mfma_f32_16x16x32_bf16 v[94:97], v[190:193], v[236:239], v[94:97]
	v_mfma_f32_16x16x32_bf16 v[26:29], v[186:189], v[202:205], v[26:29]
	v_mfma_f32_16x16x32_bf16 v[30:33], v[194:197], v[202:205], v[30:33]
	v_mfma_f32_16x16x32_bf16 v[42:45], v[186:189], v[224:227], v[42:45]
	v_mfma_f32_16x16x32_bf16 v[50:53], v[194:197], v[224:227], v[50:53]
	v_mfma_f32_16x16x32_bf16 v[66:69], v[186:189], v[232:235], v[66:69]
	v_mfma_f32_16x16x32_bf16 v[70:73], v[194:197], v[232:235], v[70:73]
	v_mfma_f32_16x16x32_bf16 v[90:93], v[186:189], v[240:243], v[90:93]
	v_mfma_f32_16x16x32_bf16 v[94:97], v[194:197], v[240:243], v[94:97]
	s_setprio 0
	s_barrier
	s_mov_b32 m0, s69
	v_lshl_add_u64 v[244:245], v[244:245], 0, s[22:23]
	s_add_u32 s16, s38, 0x160080
	ds_read_b128 v[198:201], v215 offset:49152
	ds_read_b128 v[202:205], v215 offset:50176
	ds_read_b128 v[206:209], v215 offset:51200
	ds_read_b128 v[224:227], v215 offset:52224
	ds_read_b128 v[228:231], v215 offset:53248
	ds_read_b128 v[232:235], v215 offset:54272
	ds_read_b128 v[236:239], v215 offset:55296
	ds_read_b128 v[240:243], v215 offset:56320
	global_load_lds_dwordx4 v[244:245], off
	v_lshl_add_u64 v[244:245], v[246:247], 0, s[22:23]
	s_mov_b32 m0, s73
	s_addc_u32 s17, s39, 0
	global_load_lds_dwordx4 v[244:245], off
	v_lshl_add_u64 v[244:245], s[16:17], 0, v[150:151]
	s_mov_b32 m0, s74
	s_nop 0
	global_load_lds_dwordx4 v[244:245], off
	v_lshl_add_u64 v[244:245], s[16:17], 0, v[146:147]
	s_mov_b32 m0, s75
	s_nop 0
	global_load_lds_dwordx4 v[244:245], off
	v_lshl_add_u64 v[244:245], v[248:249], 0, s[22:23]
	s_mov_b32 m0, s60
	s_nop 0
	global_load_lds_dwordx4 v[244:245], off
	v_lshl_add_u64 v[244:245], v[250:251], 0, s[22:23]
	s_mov_b32 m0, s61
	s_nop 0
	global_load_lds_dwordx4 v[244:245], off
	s_waitcnt vmcnt(8) lgkmcnt(0)
	v_mfma_f32_16x16x32_bf16 v[102:105], v[134:137], v[198:201], v[102:105]
	v_mfma_f32_16x16x32_bf16 v[98:101], v[142:145], v[198:201], v[98:101]
	v_mfma_f32_16x16x32_bf16 v[62:65], v[134:137], v[206:209], v[62:65]
	v_mfma_f32_16x16x32_bf16 v[58:61], v[142:145], v[206:209], v[58:61]
	s_barrier
	s_setprio 1
	v_mfma_f32_16x16x32_bf16 v[38:41], v[134:137], v[228:231], v[38:41]
	v_mfma_f32_16x16x32_bf16 v[34:37], v[142:145], v[228:231], v[34:37]
	v_mfma_f32_16x16x32_bf16 v[14:17], v[134:137], v[236:239], v[14:17]
	v_mfma_f32_16x16x32_bf16 v[10:13], v[142:145], v[236:239], v[10:13]
	v_mfma_f32_16x16x32_bf16 v[102:105], v[138:141], v[202:205], v[102:105]
	v_mfma_f32_16x16x32_bf16 v[98:101], v[178:181], v[202:205], v[98:101]
	v_mfma_f32_16x16x32_bf16 v[62:65], v[138:141], v[224:227], v[62:65]
	v_mfma_f32_16x16x32_bf16 v[58:61], v[178:181], v[224:227], v[58:61]
	v_mfma_f32_16x16x32_bf16 v[38:41], v[138:141], v[232:235], v[38:41]
	v_mfma_f32_16x16x32_bf16 v[34:37], v[178:181], v[232:235], v[34:37]
	v_mfma_f32_16x16x32_bf16 v[14:17], v[138:141], v[240:243], v[14:17]
	v_mfma_f32_16x16x32_bf16 v[10:13], v[178:181], v[240:243], v[10:13]
	v_mfma_f32_16x16x32_bf16 v[78:81], v[182:185], v[198:201], v[78:81]
	v_mfma_f32_16x16x32_bf16 v[74:77], v[190:193], v[198:201], v[74:77]
	v_mfma_f32_16x16x32_bf16 v[54:57], v[182:185], v[206:209], v[54:57]
	v_mfma_f32_16x16x32_bf16 v[46:49], v[190:193], v[206:209], v[46:49]
	v_mfma_f32_16x16x32_bf16 v[22:25], v[182:185], v[228:231], v[22:25]
	v_mfma_f32_16x16x32_bf16 v[18:21], v[190:193], v[228:231], v[18:21]
	v_mfma_f32_16x16x32_bf16 v[6:9], v[182:185], v[236:239], v[6:9]
	v_mfma_f32_16x16x32_bf16 v[2:5], v[190:193], v[236:239], v[2:5]
	v_mfma_f32_16x16x32_bf16 v[78:81], v[186:189], v[202:205], v[78:81]
	v_mfma_f32_16x16x32_bf16 v[74:77], v[194:197], v[202:205], v[74:77]
	v_mfma_f32_16x16x32_bf16 v[54:57], v[186:189], v[224:227], v[54:57]
	v_mfma_f32_16x16x32_bf16 v[46:49], v[194:197], v[224:227], v[46:49]
	v_mfma_f32_16x16x32_bf16 v[22:25], v[186:189], v[232:235], v[22:25]
	v_mfma_f32_16x16x32_bf16 v[18:21], v[194:197], v[232:235], v[18:21]
	v_mfma_f32_16x16x32_bf16 v[6:9], v[186:189], v[240:243], v[6:9]
	v_mfma_f32_16x16x32_bf16 v[2:5], v[194:197], v[240:243], v[2:5]
	s_setprio 0
	s_barrier
	s_add_i32 s15, s15, 2
	s_cmpk_gt_u32 s15, 0x55
	s_mov_b64 s[34:35], s[36:37]
	s_cbranch_scc0 .LBB0_356
	s_and_b64 vcc, exec, s[24:25]
	s_cbranch_vccz .LBB0_359
	s_barrier

.LBB0_466:
	ds_read_b128 v[130:133], v170
	ds_read_b128 v[134:137], v170 offset:1024
	ds_read_b128 v[164:167], v170 offset:2048
	ds_read_b128 v[174:177], v170 offset:3072
	ds_read_b128 v[178:181], v171
	ds_read_b128 v[182:185], v171 offset:1024
	ds_read_b128 v[186:189], v171 offset:2048
	ds_read_b128 v[190:193], v171 offset:3072
	s_add_u32 s19, s42, 0xfff80080
	s_addc_u32 s20, s43, -1
	s_cmp_eq_u32 s18, 28
	s_cselect_b32 s47, s3, s20
	s_cselect_b32 s46, s7, s19
	s_cselect_b32 s45, s14, s17
	s_cselect_b32 s44, s15, s16
	v_lshl_add_u64 v[168:169], s[42:43], 0, v[154:155]
	s_add_i32 m0, s41, 0xc000
	ds_read_b128 v[194:197], v172
	ds_read_b128 v[198:201], v172 offset:1024
	ds_read_b128 v[202:205], v172 offset:2048
	ds_read_b128 v[206:209], v172 offset:3072
	ds_read_b128 v[210:213], v172 offset:4096
	ds_read_b128 v[214:217], v172 offset:5120
	ds_read_b128 v[218:221], v172 offset:6144
	ds_read_b128 v[222:225], v172 offset:7168
	global_load_lds_dwordx4 v[168:169], off
	v_lshl_add_u64 v[168:169], s[42:43], 0, v[156:157]
	s_add_i32 m0, s41, 0xe000
	s_nop 0
	global_load_lds_dwordx4 v[168:169], off
	s_waitcnt vmcnt(8) lgkmcnt(0)
	v_mfma_f32_16x16x32_bf16 v[126:129], v[130:133], v[194:197], v[126:129]
	v_mfma_f32_16x16x32_bf16 v[122:125], v[164:167], v[194:197], v[122:125]
	v_mfma_f32_16x16x32_bf16 v[110:113], v[130:133], v[202:205], v[110:113]
	v_mfma_f32_16x16x32_bf16 v[106:109], v[164:167], v[202:205], v[106:109]
	s_barrier
	s_setprio 1
	v_mfma_f32_16x16x32_bf16 v[94:97], v[130:133], v[210:213], v[94:97]
	v_mfma_f32_16x16x32_bf16 v[90:93], v[164:167], v[210:213], v[90:93]
	v_mfma_f32_16x16x32_bf16 v[78:81], v[130:133], v[218:221], v[78:81]
	v_mfma_f32_16x16x32_bf16 v[74:77], v[164:167], v[218:221], v[74:77]
	v_mfma_f32_16x16x32_bf16 v[126:129], v[134:137], v[198:201], v[126:129]
	v_mfma_f32_16x16x32_bf16 v[122:125], v[174:177], v[198:201], v[122:125]
	v_mfma_f32_16x16x32_bf16 v[110:113], v[134:137], v[206:209], v[110:113]
	v_mfma_f32_16x16x32_bf16 v[106:109], v[174:177], v[206:209], v[106:109]
	v_mfma_f32_16x16x32_bf16 v[94:97], v[134:137], v[214:217], v[94:97]
	v_mfma_f32_16x16x32_bf16 v[90:93], v[174:177], v[214:217], v[90:93]
	v_mfma_f32_16x16x32_bf16 v[78:81], v[134:137], v[222:225], v[78:81]
	v_mfma_f32_16x16x32_bf16 v[74:77], v[174:177], v[222:225], v[74:77]
	v_mfma_f32_16x16x32_bf16 v[118:121], v[178:181], v[194:197], v[118:121]
	v_mfma_f32_16x16x32_bf16 v[114:117], v[186:189], v[194:197], v[114:117]
	v_mfma_f32_16x16x32_bf16 v[102:105], v[178:181], v[202:205], v[102:105]
	v_mfma_f32_16x16x32_bf16 v[98:101], v[186:189], v[202:205], v[98:101]
	v_mfma_f32_16x16x32_bf16 v[86:89], v[178:181], v[210:213], v[86:89]
	v_mfma_f32_16x16x32_bf16 v[82:85], v[186:189], v[210:213], v[82:85]
	v_mfma_f32_16x16x32_bf16 v[70:73], v[178:181], v[218:221], v[70:73]
	v_mfma_f32_16x16x32_bf16 v[66:69], v[186:189], v[218:221], v[66:69]
	v_mfma_f32_16x16x32_bf16 v[118:121], v[182:185], v[198:201], v[118:121]
	v_mfma_f32_16x16x32_bf16 v[114:117], v[190:193], v[198:201], v[114:117]
	v_mfma_f32_16x16x32_bf16 v[102:105], v[182:185], v[206:209], v[102:105]
	v_mfma_f32_16x16x32_bf16 v[98:101], v[190:193], v[206:209], v[98:101]
	v_mfma_f32_16x16x32_bf16 v[86:89], v[182:185], v[214:217], v[86:89]
	v_mfma_f32_16x16x32_bf16 v[82:85], v[190:193], v[214:217], v[82:85]
	v_mfma_f32_16x16x32_bf16 v[70:73], v[182:185], v[222:225], v[70:73]
	v_mfma_f32_16x16x32_bf16 v[66:69], v[190:193], v[222:225], v[66:69]
	s_setprio 0
	s_barrier
	s_add_i32 s19, s75, s52
	v_lshl_add_u64 v[168:169], s[44:45], 0, v[140:141]
	s_mov_b32 m0, s19
	ds_read_b128 v[194:197], v172 offset:16384
	ds_read_b128 v[198:201], v172 offset:17408
	ds_read_b128 v[202:205], v172 offset:18432
	ds_read_b128 v[206:209], v172 offset:19456
	ds_read_b128 v[210:213], v172 offset:20480
	ds_read_b128 v[214:217], v172 offset:21504
	ds_read_b128 v[218:221], v172 offset:22528
	ds_read_b128 v[222:225], v172 offset:23552
	global_load_lds_dwordx4 v[168:169], off
	s_add_i32 m0, s19, 0x2000
	s_add_u32 s20, s44, 0x80000
	v_lshl_add_u64 v[226:227], s[44:45], 0, v[144:145]
	s_addc_u32 s21, s45, 0
	s_add_i32 s19, s76, s52
	global_load_lds_dwordx4 v[226:227], off
	v_lshl_add_u64 v[228:229], s[20:21], 0, v[140:141]
	s_mov_b32 m0, s19
	v_lshl_add_u64 v[230:231], s[46:47], 0, v[142:143]
	global_load_lds_dwordx4 v[228:229], off
	v_lshl_add_u64 v[228:229], s[20:21], 0, v[144:145]
	s_add_i32 m0, s19, 0x2000
	s_nop 0
	global_load_lds_dwordx4 v[228:229], off
	v_lshl_add_u64 v[228:229], s[46:47], 0, v[138:139]
	s_mov_b32 m0, s41
	s_nop 0
	global_load_lds_dwordx4 v[228:229], off
	s_mov_b32 m0, s53
	s_nop 0
	global_load_lds_dwordx4 v[230:231], off
	s_waitcnt vmcnt(8) lgkmcnt(0)
	v_mfma_f32_16x16x32_bf16 v[62:65], v[130:133], v[194:197], v[62:65]
	v_mfma_f32_16x16x32_bf16 v[58:61], v[164:167], v[194:197], v[58:61]
	v_mfma_f32_16x16x32_bf16 v[46:49], v[130:133], v[202:205], v[46:49]
	v_mfma_f32_16x16x32_bf16 v[42:45], v[164:167], v[202:205], v[42:45]
	s_barrier
	s_setprio 1
	v_mfma_f32_16x16x32_bf16 v[30:33], v[130:133], v[210:213], v[30:33]
	v_mfma_f32_16x16x32_bf16 v[26:29], v[164:167], v[210:213], v[26:29]
	v_mfma_f32_16x16x32_bf16 v[14:17], v[130:133], v[218:221], v[14:17]
	v_mfma_f32_16x16x32_bf16 v[10:13], v[164:167], v[218:221], v[10:13]
	v_mfma_f32_16x16x32_bf16 v[62:65], v[134:137], v[198:201], v[62:65]
	v_mfma_f32_16x16x32_bf16 v[58:61], v[174:177], v[198:201], v[58:61]
	v_mfma_f32_16x16x32_bf16 v[46:49], v[134:137], v[206:209], v[46:49]
	v_mfma_f32_16x16x32_bf16 v[42:45], v[174:177], v[206:209], v[42:45]
	v_mfma_f32_16x16x32_bf16 v[30:33], v[134:137], v[214:217], v[30:33]
	v_mfma_f32_16x16x32_bf16 v[26:29], v[174:177], v[214:217], v[26:29]
	v_mfma_f32_16x16x32_bf16 v[14:17], v[134:137], v[222:225], v[14:17]
	v_mfma_f32_16x16x32_bf16 v[10:13], v[174:177], v[222:225], v[10:13]
	v_mfma_f32_16x16x32_bf16 v[54:57], v[178:181], v[194:197], v[54:57]
	v_mfma_f32_16x16x32_bf16 v[50:53], v[186:189], v[194:197], v[50:53]
	v_mfma_f32_16x16x32_bf16 v[38:41], v[178:181], v[202:205], v[38:41]
	v_mfma_f32_16x16x32_bf16 v[34:37], v[186:189], v[202:205], v[34:37]
	v_mfma_f32_16x16x32_bf16 v[22:25], v[178:181], v[210:213], v[22:25]
	v_mfma_f32_16x16x32_bf16 v[18:21], v[186:189], v[210:213], v[18:21]
	v_mfma_f32_16x16x32_bf16 v[6:9], v[178:181], v[218:221], v[6:9]
	v_mfma_f32_16x16x32_bf16 v[2:5], v[186:189], v[218:221], v[2:5]
	v_mfma_f32_16x16x32_bf16 v[54:57], v[182:185], v[198:201], v[54:57]
	v_mfma_f32_16x16x32_bf16 v[50:53], v[190:193], v[198:201], v[50:53]
	v_mfma_f32_16x16x32_bf16 v[38:41], v[182:185], v[206:209], v[38:41]
	v_mfma_f32_16x16x32_bf16 v[34:37], v[190:193], v[206:209], v[34:37]
	v_mfma_f32_16x16x32_bf16 v[22:25], v[182:185], v[214:217], v[22:25]
	v_mfma_f32_16x16x32_bf16 v[18:21], v[190:193], v[214:217], v[18:21]
	v_mfma_f32_16x16x32_bf16 v[6:9], v[182:185], v[222:225], v[6:9]
	v_mfma_f32_16x16x32_bf16 v[2:5], v[190:193], v[222:225], v[2:5]
	s_setprio 0
	s_barrier
	s_add_i32 s19, 0, 0x18000
	v_add_u32_e32 v146, s19, v163
	s_add_i32 s31, 0, 0x1c000
	ds_read_b128 v[130:133], v146
	ds_read_b128 v[134:137], v146 offset:1024
	ds_read_b128 v[164:167], v146 offset:2048
	ds_read_b128 v[174:177], v146 offset:3072
	v_add_u32_e32 v146, s31, v163
	ds_read_b128 v[178:181], v146
	ds_read_b128 v[182:185], v146 offset:1024
	ds_read_b128 v[186:189], v146 offset:2048
	ds_read_b128 v[190:193], v146 offset:3072
	s_add_u32 s20, s46, 0x80000
	s_addc_u32 s21, s47, 0
	s_mov_b32 m0, s54
	v_lshl_add_u64 v[232:233], s[20:21], 0, v[138:139]
	ds_read_b128 v[194:197], v172 offset:32768
	ds_read_b128 v[198:201], v172 offset:33792
	ds_read_b128 v[202:205], v172 offset:34816
	ds_read_b128 v[206:209], v172 offset:35840
	ds_read_b128 v[210:213], v172 offset:36864
	ds_read_b128 v[214:217], v172 offset:37888
	ds_read_b128 v[218:221], v172 offset:38912
	ds_read_b128 v[222:225], v172 offset:39936
	global_load_lds_dwordx4 v[232:233], off
	v_lshl_add_u64 v[232:233], s[20:21], 0, v[142:143]
	s_mov_b32 m0, s55
	s_nop 0
	global_load_lds_dwordx4 v[232:233], off
	s_waitcnt vmcnt(8) lgkmcnt(0)
	v_mfma_f32_16x16x32_bf16 v[126:129], v[130:133], v[194:197], v[126:129]
	v_mfma_f32_16x16x32_bf16 v[122:125], v[164:167], v[194:197], v[122:125]
	v_mfma_f32_16x16x32_bf16 v[110:113], v[130:133], v[202:205], v[110:113]
	v_mfma_f32_16x16x32_bf16 v[106:109], v[164:167], v[202:205], v[106:109]
	s_barrier
	s_setprio 1
	v_mfma_f32_16x16x32_bf16 v[94:97], v[130:133], v[210:213], v[94:97]
	v_mfma_f32_16x16x32_bf16 v[90:93], v[164:167], v[210:213], v[90:93]
	v_mfma_f32_16x16x32_bf16 v[78:81], v[130:133], v[218:221], v[78:81]
	v_mfma_f32_16x16x32_bf16 v[74:77], v[164:167], v[218:221], v[74:77]
	v_mfma_f32_16x16x32_bf16 v[126:129], v[134:137], v[198:201], v[126:129]
	v_mfma_f32_16x16x32_bf16 v[122:125], v[174:177], v[198:201], v[122:125]
	v_mfma_f32_16x16x32_bf16 v[110:113], v[134:137], v[206:209], v[110:113]
	v_mfma_f32_16x16x32_bf16 v[106:109], v[174:177], v[206:209], v[106:109]
	v_mfma_f32_16x16x32_bf16 v[94:97], v[134:137], v[214:217], v[94:97]
	v_mfma_f32_16x16x32_bf16 v[90:93], v[174:177], v[214:217], v[90:93]
	v_mfma_f32_16x16x32_bf16 v[78:81], v[134:137], v[222:225], v[78:81]
	v_mfma_f32_16x16x32_bf16 v[74:77], v[174:177], v[222:225], v[74:77]
	v_mfma_f32_16x16x32_bf16 v[118:121], v[178:181], v[194:197], v[118:121]
	v_mfma_f32_16x16x32_bf16 v[114:117], v[186:189], v[194:197], v[114:117]
	v_mfma_f32_16x16x32_bf16 v[102:105], v[178:181], v[202:205], v[102:105]
	v_mfma_f32_16x16x32_bf16 v[98:101], v[186:189], v[202:205], v[98:101]
	v_mfma_f32_16x16x32_bf16 v[86:89], v[178:181], v[210:213], v[86:89]
	v_mfma_f32_16x16x32_bf16 v[82:85], v[186:189], v[210:213], v[82:85]
	v_mfma_f32_16x16x32_bf16 v[70:73], v[178:181], v[218:221], v[70:73]
	v_mfma_f32_16x16x32_bf16 v[66:69], v[186:189], v[218:221], v[66:69]
	v_mfma_f32_16x16x32_bf16 v[118:121], v[182:185], v[198:201], v[118:121]
	v_mfma_f32_16x16x32_bf16 v[114:117], v[190:193], v[198:201], v[114:117]
	v_mfma_f32_16x16x32_bf16 v[102:105], v[182:185], v[206:209], v[102:105]
	v_mfma_f32_16x16x32_bf16 v[98:101], v[190:193], v[206:209], v[98:101]
	v_mfma_f32_16x16x32_bf16 v[86:89], v[182:185], v[214:217], v[86:89]
	v_mfma_f32_16x16x32_bf16 v[82:85], v[190:193], v[214:217], v[82:85]
	v_mfma_f32_16x16x32_bf16 v[70:73], v[182:185], v[222:225], v[70:73]
	v_mfma_f32_16x16x32_bf16 v[66:69], v[190:193], v[222:225], v[66:69]
	s_setprio 0
	s_barrier
	s_add_i32 s19, s19, s52
	v_lshl_add_u64 v[168:169], v[168:169], 0, s[10:11]
	s_mov_b32 m0, s19
	ds_read_b128 v[194:197], v172 offset:49152
	ds_read_b128 v[198:201], v172 offset:50176
	ds_read_b128 v[202:205], v172 offset:51200
	ds_read_b128 v[206:209], v172 offset:52224
	ds_read_b128 v[210:213], v172 offset:53248
	ds_read_b128 v[214:217], v172 offset:54272
	ds_read_b128 v[218:221], v172 offset:55296
	ds_read_b128 v[222:225], v172 offset:56320
	global_load_lds_dwordx4 v[168:169], off
	s_add_i32 m0, s19, 0x2000
	s_add_u32 s20, s44, 0x80080
	v_lshl_add_u64 v[168:169], v[226:227], 0, s[10:11]
	s_addc_u32 s21, s45, 0
	s_add_i32 s19, s31, s52
	global_load_lds_dwordx4 v[168:169], off
	v_lshl_add_u64 v[168:169], s[20:21], 0, v[140:141]
	s_mov_b32 m0, s19
	s_nop 0
	global_load_lds_dwordx4 v[168:169], off
	v_lshl_add_u64 v[168:169], s[20:21], 0, v[144:145]
	s_add_i32 m0, s19, 0x2000
	s_nop 0
	global_load_lds_dwordx4 v[168:169], off
	v_lshl_add_u64 v[168:169], v[228:229], 0, s[10:11]
	s_mov_b32 m0, s67
	s_nop 0
	global_load_lds_dwordx4 v[168:169], off
	v_lshl_add_u64 v[168:169], v[230:231], 0, s[10:11]
	s_mov_b32 m0, s68
	s_nop 0
	global_load_lds_dwordx4 v[168:169], off
	s_waitcnt vmcnt(8) lgkmcnt(0)
	v_mfma_f32_16x16x32_bf16 v[62:65], v[130:133], v[194:197], v[62:65]
	v_mfma_f32_16x16x32_bf16 v[58:61], v[164:167], v[194:197], v[58:61]
	v_mfma_f32_16x16x32_bf16 v[46:49], v[130:133], v[202:205], v[46:49]
	v_mfma_f32_16x16x32_bf16 v[42:45], v[164:167], v[202:205], v[42:45]
	s_barrier
	s_setprio 1
	v_mfma_f32_16x16x32_bf16 v[30:33], v[130:133], v[210:213], v[30:33]
	v_mfma_f32_16x16x32_bf16 v[26:29], v[164:167], v[210:213], v[26:29]
	v_mfma_f32_16x16x32_bf16 v[14:17], v[130:133], v[218:221], v[14:17]
	v_mfma_f32_16x16x32_bf16 v[10:13], v[164:167], v[218:221], v[10:13]
	v_mfma_f32_16x16x32_bf16 v[62:65], v[134:137], v[198:201], v[62:65]
	v_mfma_f32_16x16x32_bf16 v[58:61], v[174:177], v[198:201], v[58:61]
	v_mfma_f32_16x16x32_bf16 v[46:49], v[134:137], v[206:209], v[46:49]
	v_mfma_f32_16x16x32_bf16 v[42:45], v[174:177], v[206:209], v[42:45]
	v_mfma_f32_16x16x32_bf16 v[30:33], v[134:137], v[214:217], v[30:33]
	v_mfma_f32_16x16x32_bf16 v[26:29], v[174:177], v[214:217], v[26:29]
	v_mfma_f32_16x16x32_bf16 v[14:17], v[134:137], v[222:225], v[14:17]
	v_mfma_f32_16x16x32_bf16 v[10:13], v[174:177], v[222:225], v[10:13]
	v_mfma_f32_16x16x32_bf16 v[54:57], v[178:181], v[194:197], v[54:57]
	v_mfma_f32_16x16x32_bf16 v[50:53], v[186:189], v[194:197], v[50:53]
	v_mfma_f32_16x16x32_bf16 v[38:41], v[178:181], v[202:205], v[38:41]
	v_mfma_f32_16x16x32_bf16 v[34:37], v[186:189], v[202:205], v[34:37]
	v_mfma_f32_16x16x32_bf16 v[22:25], v[178:181], v[210:213], v[22:25]
	v_mfma_f32_16x16x32_bf16 v[18:21], v[186:189], v[210:213], v[18:21]
	v_mfma_f32_16x16x32_bf16 v[6:9], v[178:181], v[218:221], v[6:9]
	v_mfma_f32_16x16x32_bf16 v[2:5], v[186:189], v[218:221], v[2:5]
	v_mfma_f32_16x16x32_bf16 v[54:57], v[182:185], v[198:201], v[54:57]
	v_mfma_f32_16x16x32_bf16 v[50:53], v[190:193], v[198:201], v[50:53]
	v_mfma_f32_16x16x32_bf16 v[38:41], v[182:185], v[206:209], v[38:41]
	v_mfma_f32_16x16x32_bf16 v[34:37], v[190:193], v[206:209], v[34:37]
	v_mfma_f32_16x16x32_bf16 v[22:25], v[182:185], v[214:217], v[22:25]
	v_mfma_f32_16x16x32_bf16 v[18:21], v[190:193], v[214:217], v[18:21]
	v_mfma_f32_16x16x32_bf16 v[6:9], v[182:185], v[222:225], v[6:9]
	v_mfma_f32_16x16x32_bf16 v[2:5], v[190:193], v[222:225], v[2:5]
	s_setprio 0
	s_barrier
	s_add_i32 s18, s18, 2
	s_add_u32 s42, s42, 0x100
	s_addc_u32 s43, s43, 0
	s_add_u32 s16, s16, 0x100
	s_addc_u32 s17, s17, 0
	s_cmp_gt_u32 s18, 29
	s_cbranch_scc0 .LBB0_466
	s_and_b64 vcc, exec, s[12:13]
	s_cbranch_vccz .LBB0_469
	s_barrier

.LBB0_699:
	ds_read_b128 v[134:137], v214
	ds_read_b128 v[138:141], v214 offset:1024
	ds_read_b128 v[142:145], v214 offset:2048
	ds_read_b128 v[178:181], v214 offset:3072
	ds_read_b128 v[182:185], v215
	ds_read_b128 v[186:189], v215 offset:1024
	ds_read_b128 v[190:193], v215 offset:2048
	ds_read_b128 v[194:197], v215 offset:3072
	s_add_u32 s40, s38, 0x100
	s_addc_u32 s41, s39, 0
	s_add_u32 s18, s15, s38
	s_addc_u32 s19, s16, s39
	s_cmp_eq_u32 s17, 60
	s_cselect_b32 s45, s3, s19
	s_cselect_b32 s19, 0, s40
	s_cselect_b32 s44, s14, s18
	s_cselect_b32 s18, 0, s41
	s_add_u32 s42, s10, s19
	s_addc_u32 s43, s11, s18
	s_mov_b32 m0, s66
	v_lshl_add_u64 v[244:245], v[130:131], 0, s[38:39]
	ds_read_b128 v[198:201], v216
	ds_read_b128 v[202:205], v216 offset:1024
	ds_read_b128 v[206:209], v216 offset:2048
	ds_read_b128 v[224:227], v216 offset:3072
	ds_read_b128 v[228:231], v216 offset:4096
	ds_read_b128 v[232:235], v216 offset:5120
	ds_read_b128 v[236:239], v216 offset:6144
	ds_read_b128 v[240:243], v216 offset:7168
	global_load_lds_dwordx4 v[244:245], off
	v_lshl_add_u64 v[244:245], v[132:133], 0, s[38:39]
	s_mov_b32 m0, s67
	s_nop 0
	global_load_lds_dwordx4 v[244:245], off
	s_waitcnt vmcnt(8) lgkmcnt(0)
	v_mfma_f32_16x16x32_bf16 v[82:85], v[134:137], v[198:201], v[82:85]
	v_mfma_f32_16x16x32_bf16 v[78:81], v[142:145], v[198:201], v[78:81]
	v_mfma_f32_16x16x32_bf16 v[110:113], v[134:137], v[206:209], v[110:113]
	v_mfma_f32_16x16x32_bf16 v[106:109], v[142:145], v[206:209], v[106:109]
	s_barrier
	s_setprio 1
	v_mfma_f32_16x16x32_bf16 v[118:121], v[134:137], v[228:231], v[118:121]
	v_mfma_f32_16x16x32_bf16 v[114:117], v[142:145], v[228:231], v[114:117]
	v_mfma_f32_16x16x32_bf16 v[126:129], v[134:137], v[236:239], v[126:129]
	v_mfma_f32_16x16x32_bf16 v[122:125], v[142:145], v[236:239], v[122:125]
	v_mfma_f32_16x16x32_bf16 v[82:85], v[138:141], v[202:205], v[82:85]
	v_mfma_f32_16x16x32_bf16 v[78:81], v[178:181], v[202:205], v[78:81]
	v_mfma_f32_16x16x32_bf16 v[110:113], v[138:141], v[224:227], v[110:113]
	v_mfma_f32_16x16x32_bf16 v[106:109], v[178:181], v[224:227], v[106:109]
	v_mfma_f32_16x16x32_bf16 v[118:121], v[138:141], v[232:235], v[118:121]
	v_mfma_f32_16x16x32_bf16 v[114:117], v[178:181], v[232:235], v[114:117]
	v_mfma_f32_16x16x32_bf16 v[126:129], v[138:141], v[240:243], v[126:129]
	v_mfma_f32_16x16x32_bf16 v[122:125], v[178:181], v[240:243], v[122:125]
	v_mfma_f32_16x16x32_bf16 v[22:25], v[182:185], v[198:201], v[22:25]
	v_mfma_f32_16x16x32_bf16 v[26:29], v[190:193], v[198:201], v[26:29]
	v_mfma_f32_16x16x32_bf16 v[42:45], v[182:185], v[206:209], v[42:45]
	v_mfma_f32_16x16x32_bf16 v[46:49], v[190:193], v[206:209], v[46:49]
	v_mfma_f32_16x16x32_bf16 v[62:65], v[182:185], v[228:231], v[62:65]
	v_mfma_f32_16x16x32_bf16 v[70:73], v[190:193], v[228:231], v[70:73]
	v_mfma_f32_16x16x32_bf16 v[90:93], v[182:185], v[236:239], v[90:93]
	v_mfma_f32_16x16x32_bf16 v[94:97], v[190:193], v[236:239], v[94:97]
	v_mfma_f32_16x16x32_bf16 v[22:25], v[186:189], v[202:205], v[22:25]
	v_mfma_f32_16x16x32_bf16 v[26:29], v[194:197], v[202:205], v[26:29]
	v_mfma_f32_16x16x32_bf16 v[42:45], v[186:189], v[224:227], v[42:45]
	v_mfma_f32_16x16x32_bf16 v[46:49], v[194:197], v[224:227], v[46:49]
	v_mfma_f32_16x16x32_bf16 v[62:65], v[186:189], v[232:235], v[62:65]
	v_mfma_f32_16x16x32_bf16 v[70:73], v[194:197], v[232:235], v[70:73]
	v_mfma_f32_16x16x32_bf16 v[90:93], v[186:189], v[240:243], v[90:93]
	v_mfma_f32_16x16x32_bf16 v[94:97], v[194:197], v[240:243], v[94:97]
	s_setprio 0
	s_barrier
	s_mov_b32 m0, s68
	v_lshl_add_u64 v[244:245], s[42:43], 0, v[150:151]
	s_add_u32 s18, s42, 0x100000
	ds_read_b128 v[198:201], v216 offset:16384
	ds_read_b128 v[202:205], v216 offset:17408
	ds_read_b128 v[206:209], v216 offset:18432
	ds_read_b128 v[224:227], v216 offset:19456
	ds_read_b128 v[228:231], v216 offset:20480
	ds_read_b128 v[232:235], v216 offset:21504
	ds_read_b128 v[236:239], v216 offset:22528
	ds_read_b128 v[240:243], v216 offset:23552
	global_load_lds_dwordx4 v[244:245], off
	v_lshl_add_u64 v[246:247], s[42:43], 0, v[146:147]
	s_mov_b32 m0, s69
	s_addc_u32 s19, s43, 0
	global_load_lds_dwordx4 v[246:247], off
	v_lshl_add_u64 v[248:249], s[18:19], 0, v[150:151]
	s_mov_b32 m0, s73
	v_lshl_add_u64 v[250:251], s[44:45], 0, v[148:149]
	global_load_lds_dwordx4 v[248:249], off
	v_lshl_add_u64 v[248:249], s[18:19], 0, v[146:147]
	s_mov_b32 m0, s74
	s_nop 0
	global_load_lds_dwordx4 v[248:249], off
	v_lshl_add_u64 v[248:249], s[44:45], 0, v[152:153]
	s_mov_b32 m0, s9
	s_nop 0
	global_load_lds_dwordx4 v[248:249], off
	s_mov_b32 m0, s55
	s_nop 0
	global_load_lds_dwordx4 v[250:251], off
	s_waitcnt vmcnt(8) lgkmcnt(0)
	v_mfma_f32_16x16x32_bf16 v[102:105], v[134:137], v[198:201], v[102:105]
	v_mfma_f32_16x16x32_bf16 v[98:101], v[142:145], v[198:201], v[98:101]
	v_mfma_f32_16x16x32_bf16 v[66:69], v[134:137], v[206:209], v[66:69]
	v_mfma_f32_16x16x32_bf16 v[58:61], v[142:145], v[206:209], v[58:61]
	s_barrier
	s_setprio 1
	v_mfma_f32_16x16x32_bf16 v[38:41], v[134:137], v[228:231], v[38:41]
	v_mfma_f32_16x16x32_bf16 v[34:37], v[142:145], v[228:231], v[34:37]
	v_mfma_f32_16x16x32_bf16 v[14:17], v[134:137], v[236:239], v[14:17]
	v_mfma_f32_16x16x32_bf16 v[10:13], v[142:145], v[236:239], v[10:13]
	v_mfma_f32_16x16x32_bf16 v[102:105], v[138:141], v[202:205], v[102:105]
	v_mfma_f32_16x16x32_bf16 v[98:101], v[178:181], v[202:205], v[98:101]
	v_mfma_f32_16x16x32_bf16 v[66:69], v[138:141], v[224:227], v[66:69]
	v_mfma_f32_16x16x32_bf16 v[58:61], v[178:181], v[224:227], v[58:61]
	v_mfma_f32_16x16x32_bf16 v[38:41], v[138:141], v[232:235], v[38:41]
	v_mfma_f32_16x16x32_bf16 v[34:37], v[178:181], v[232:235], v[34:37]
	v_mfma_f32_16x16x32_bf16 v[14:17], v[138:141], v[240:243], v[14:17]
	v_mfma_f32_16x16x32_bf16 v[10:13], v[178:181], v[240:243], v[10:13]
	v_mfma_f32_16x16x32_bf16 v[86:89], v[182:185], v[198:201], v[86:89]
	v_mfma_f32_16x16x32_bf16 v[74:77], v[190:193], v[198:201], v[74:77]
	v_mfma_f32_16x16x32_bf16 v[54:57], v[182:185], v[206:209], v[54:57]
	v_mfma_f32_16x16x32_bf16 v[50:53], v[190:193], v[206:209], v[50:53]
	v_mfma_f32_16x16x32_bf16 v[30:33], v[182:185], v[228:231], v[30:33]
	v_mfma_f32_16x16x32_bf16 v[18:21], v[190:193], v[228:231], v[18:21]
	v_mfma_f32_16x16x32_bf16 v[6:9], v[182:185], v[236:239], v[6:9]
	v_mfma_f32_16x16x32_bf16 v[2:5], v[190:193], v[236:239], v[2:5]
	v_mfma_f32_16x16x32_bf16 v[86:89], v[186:189], v[202:205], v[86:89]
	v_mfma_f32_16x16x32_bf16 v[74:77], v[194:197], v[202:205], v[74:77]
	v_mfma_f32_16x16x32_bf16 v[54:57], v[186:189], v[224:227], v[54:57]
	v_mfma_f32_16x16x32_bf16 v[50:53], v[194:197], v[224:227], v[50:53]
	v_mfma_f32_16x16x32_bf16 v[30:33], v[186:189], v[232:235], v[30:33]
	v_mfma_f32_16x16x32_bf16 v[18:21], v[194:197], v[232:235], v[18:21]
	v_mfma_f32_16x16x32_bf16 v[6:9], v[186:189], v[240:243], v[6:9]
	v_mfma_f32_16x16x32_bf16 v[2:5], v[194:197], v[240:243], v[2:5]
	s_setprio 0
	s_barrier
	s_add_i32 s20, 0, 0x1c000
	v_add_u32_e32 v194, s20, v212
	ds_read_b128 v[134:137], v220
	ds_read_b128 v[138:141], v220 offset:1024
	ds_read_b128 v[142:145], v220 offset:2048
	ds_read_b128 v[178:181], v220 offset:3072
	ds_read_b128 v[182:185], v194
	ds_read_b128 v[186:189], v194 offset:1024
	ds_read_b128 v[190:193], v194 offset:2048
	ds_read_b128 v[194:197], v194 offset:3072
	s_add_u32 s18, s44, 0x100000
	s_addc_u32 s19, s45, 0
	s_mov_b32 m0, s56
	v_lshl_add_u64 v[252:253], s[18:19], 0, v[152:153]
	ds_read_b128 v[198:201], v216 offset:32768
	ds_read_b128 v[202:205], v216 offset:33792
	ds_read_b128 v[206:209], v216 offset:34816
	ds_read_b128 v[224:227], v216 offset:35840
	ds_read_b128 v[228:231], v216 offset:36864
	ds_read_b128 v[232:235], v216 offset:37888
	ds_read_b128 v[236:239], v216 offset:38912
	ds_read_b128 v[240:243], v216 offset:39936
	global_load_lds_dwordx4 v[252:253], off
	v_lshl_add_u64 v[252:253], s[18:19], 0, v[148:149]
	s_mov_b32 m0, s57
	s_nop 0
	global_load_lds_dwordx4 v[252:253], off
	s_waitcnt vmcnt(8) lgkmcnt(0)
	v_mfma_f32_16x16x32_bf16 v[82:85], v[134:137], v[198:201], v[82:85]
	v_mfma_f32_16x16x32_bf16 v[78:81], v[142:145], v[198:201], v[78:81]
	v_mfma_f32_16x16x32_bf16 v[110:113], v[134:137], v[206:209], v[110:113]
	v_mfma_f32_16x16x32_bf16 v[106:109], v[142:145], v[206:209], v[106:109]
	s_barrier
	s_setprio 1
	v_mfma_f32_16x16x32_bf16 v[118:121], v[134:137], v[228:231], v[118:121]
	v_mfma_f32_16x16x32_bf16 v[114:117], v[142:145], v[228:231], v[114:117]
	v_mfma_f32_16x16x32_bf16 v[126:129], v[134:137], v[236:239], v[126:129]
	v_mfma_f32_16x16x32_bf16 v[122:125], v[142:145], v[236:239], v[122:125]
	v_mfma_f32_16x16x32_bf16 v[82:85], v[138:141], v[202:205], v[82:85]
	v_mfma_f32_16x16x32_bf16 v[78:81], v[178:181], v[202:205], v[78:81]
	v_mfma_f32_16x16x32_bf16 v[110:113], v[138:141], v[224:227], v[110:113]
	v_mfma_f32_16x16x32_bf16 v[106:109], v[178:181], v[224:227], v[106:109]
	v_mfma_f32_16x16x32_bf16 v[118:121], v[138:141], v[232:235], v[118:121]
	v_mfma_f32_16x16x32_bf16 v[114:117], v[178:181], v[232:235], v[114:117]
	v_mfma_f32_16x16x32_bf16 v[126:129], v[138:141], v[240:243], v[126:129]
	v_mfma_f32_16x16x32_bf16 v[122:125], v[178:181], v[240:243], v[122:125]
	v_mfma_f32_16x16x32_bf16 v[22:25], v[182:185], v[198:201], v[22:25]
	v_mfma_f32_16x16x32_bf16 v[26:29], v[190:193], v[198:201], v[26:29]
	v_mfma_f32_16x16x32_bf16 v[42:45], v[182:185], v[206:209], v[42:45]
	v_mfma_f32_16x16x32_bf16 v[46:49], v[190:193], v[206:209], v[46:49]
	v_mfma_f32_16x16x32_bf16 v[62:65], v[182:185], v[228:231], v[62:65]
	v_mfma_f32_16x16x32_bf16 v[70:73], v[190:193], v[228:231], v[70:73]
	v_mfma_f32_16x16x32_bf16 v[90:93], v[182:185], v[236:239], v[90:93]
	v_mfma_f32_16x16x32_bf16 v[94:97], v[190:193], v[236:239], v[94:97]
	v_mfma_f32_16x16x32_bf16 v[22:25], v[186:189], v[202:205], v[22:25]
	v_mfma_f32_16x16x32_bf16 v[26:29], v[194:197], v[202:205], v[26:29]
	v_mfma_f32_16x16x32_bf16 v[42:45], v[186:189], v[224:227], v[42:45]
	v_mfma_f32_16x16x32_bf16 v[46:49], v[194:197], v[224:227], v[46:49]
	v_mfma_f32_16x16x32_bf16 v[62:65], v[186:189], v[232:235], v[62:65]
	v_mfma_f32_16x16x32_bf16 v[70:73], v[194:197], v[232:235], v[70:73]
	v_mfma_f32_16x16x32_bf16 v[90:93], v[186:189], v[240:243], v[90:93]
	v_mfma_f32_16x16x32_bf16 v[94:97], v[194:197], v[240:243], v[94:97]
	s_setprio 0
	s_barrier
	s_add_i32 s18, s75, s54
	v_lshl_add_u64 v[244:245], v[244:245], 0, s[26:27]
	s_mov_b32 m0, s18
	ds_read_b128 v[198:201], v216 offset:49152
	ds_read_b128 v[202:205], v216 offset:50176
	ds_read_b128 v[206:209], v216 offset:51200
	ds_read_b128 v[224:227], v216 offset:52224
	ds_read_b128 v[228:231], v216 offset:53248
	ds_read_b128 v[232:235], v216 offset:54272
	ds_read_b128 v[236:239], v216 offset:55296
	ds_read_b128 v[240:243], v216 offset:56320
	global_load_lds_dwordx4 v[244:245], off
	s_add_i32 m0, s18, 0x2000
	s_add_u32 s18, s42, 0x100080
	v_lshl_add_u64 v[244:245], v[246:247], 0, s[26:27]
	s_addc_u32 s19, s43, 0
	s_add_i32 s20, s20, s54
	global_load_lds_dwordx4 v[244:245], off
	v_lshl_add_u64 v[244:245], s[18:19], 0, v[150:151]
	s_mov_b32 m0, s20
	s_nop 0
	global_load_lds_dwordx4 v[244:245], off
	v_lshl_add_u64 v[244:245], s[18:19], 0, v[146:147]
	s_add_i32 m0, s20, 0x2000
	s_nop 0
	global_load_lds_dwordx4 v[244:245], off
	v_lshl_add_u64 v[244:245], v[248:249], 0, s[26:27]
	s_mov_b32 m0, s63
	s_nop 0
	global_load_lds_dwordx4 v[244:245], off
	v_lshl_add_u64 v[244:245], v[250:251], 0, s[26:27]
	s_mov_b32 m0, s64
	s_nop 0
	global_load_lds_dwordx4 v[244:245], off
	s_waitcnt vmcnt(8) lgkmcnt(0)
	v_mfma_f32_16x16x32_bf16 v[102:105], v[134:137], v[198:201], v[102:105]
	v_mfma_f32_16x16x32_bf16 v[98:101], v[142:145], v[198:201], v[98:101]
	v_mfma_f32_16x16x32_bf16 v[66:69], v[134:137], v[206:209], v[66:69]
	v_mfma_f32_16x16x32_bf16 v[58:61], v[142:145], v[206:209], v[58:61]
	s_barrier
	s_setprio 1
	v_mfma_f32_16x16x32_bf16 v[38:41], v[134:137], v[228:231], v[38:41]
	v_mfma_f32_16x16x32_bf16 v[34:37], v[142:145], v[228:231], v[34:37]
	v_mfma_f32_16x16x32_bf16 v[14:17], v[134:137], v[236:239], v[14:17]
	v_mfma_f32_16x16x32_bf16 v[10:13], v[142:145], v[236:239], v[10:13]
	v_mfma_f32_16x16x32_bf16 v[102:105], v[138:141], v[202:205], v[102:105]
	v_mfma_f32_16x16x32_bf16 v[98:101], v[178:181], v[202:205], v[98:101]
	v_mfma_f32_16x16x32_bf16 v[66:69], v[138:141], v[224:227], v[66:69]
	v_mfma_f32_16x16x32_bf16 v[58:61], v[178:181], v[224:227], v[58:61]
	v_mfma_f32_16x16x32_bf16 v[38:41], v[138:141], v[232:235], v[38:41]
	v_mfma_f32_16x16x32_bf16 v[34:37], v[178:181], v[232:235], v[34:37]
	v_mfma_f32_16x16x32_bf16 v[14:17], v[138:141], v[240:243], v[14:17]
	v_mfma_f32_16x16x32_bf16 v[10:13], v[178:181], v[240:243], v[10:13]
	v_mfma_f32_16x16x32_bf16 v[86:89], v[182:185], v[198:201], v[86:89]
	v_mfma_f32_16x16x32_bf16 v[74:77], v[190:193], v[198:201], v[74:77]
	v_mfma_f32_16x16x32_bf16 v[54:57], v[182:185], v[206:209], v[54:57]
	v_mfma_f32_16x16x32_bf16 v[50:53], v[190:193], v[206:209], v[50:53]
	v_mfma_f32_16x16x32_bf16 v[30:33], v[182:185], v[228:231], v[30:33]
	v_mfma_f32_16x16x32_bf16 v[18:21], v[190:193], v[228:231], v[18:21]
	v_mfma_f32_16x16x32_bf16 v[6:9], v[182:185], v[236:239], v[6:9]
	v_mfma_f32_16x16x32_bf16 v[2:5], v[190:193], v[236:239], v[2:5]
	v_mfma_f32_16x16x32_bf16 v[86:89], v[186:189], v[202:205], v[86:89]
	v_mfma_f32_16x16x32_bf16 v[74:77], v[194:197], v[202:205], v[74:77]
	v_mfma_f32_16x16x32_bf16 v[54:57], v[186:189], v[224:227], v[54:57]
	v_mfma_f32_16x16x32_bf16 v[50:53], v[194:197], v[224:227], v[50:53]
	v_mfma_f32_16x16x32_bf16 v[30:33], v[186:189], v[232:235], v[30:33]
	v_mfma_f32_16x16x32_bf16 v[18:21], v[194:197], v[232:235], v[18:21]
	v_mfma_f32_16x16x32_bf16 v[6:9], v[186:189], v[240:243], v[6:9]
	v_mfma_f32_16x16x32_bf16 v[2:5], v[194:197], v[240:243], v[2:5]
	s_setprio 0
	s_barrier
	s_add_i32 s17, s17, 2
	s_cmp_gt_u32 s17, 61
	s_mov_b64 s[38:39], s[40:41]
	s_cbranch_scc0 .LBB0_699
	s_and_b64 vcc, exec, s[28:29]
	s_cbranch_vccz .LBB0_702
	s_barrier

.LBB0_877:
	ds_read_b128 v[130:133], v220
	ds_read_b128 v[134:137], v220 offset:1024
	ds_read_b128 v[138:141], v220 offset:2048
	ds_read_b128 v[142:145], v220 offset:3072
	ds_read_b128 v[184:187], v224
	ds_read_b128 v[188:191], v224 offset:1024
	ds_read_b128 v[192:195], v224 offset:2048
	ds_read_b128 v[196:199], v224 offset:3072
	s_add_u32 s14, s36, 0xffea0080
	s_addc_u32 s15, s37, -1
	s_cmpk_eq_i32 s3, 0x54
	s_cselect_b32 s43, s29, s15
	s_cselect_b32 s42, s28, s14
	s_cselect_b32 s41, s9, s39
	s_cselect_b32 s40, s8, s38
	s_mov_b32 m0, s50
	v_lshl_add_u64 v[244:245], s[36:37], 0, v[178:179]
	ds_read_b128 v[200:203], v221
	ds_read_b128 v[204:207], v221 offset:1024
	ds_read_b128 v[208:211], v221 offset:2048
	ds_read_b128 v[212:215], v221 offset:3072
	ds_read_b128 v[228:231], v221 offset:4096
	ds_read_b128 v[232:235], v221 offset:5120
	ds_read_b128 v[236:239], v221 offset:6144
	ds_read_b128 v[240:243], v221 offset:7168
	global_load_lds_dwordx4 v[244:245], off
	v_lshl_add_u64 v[244:245], s[36:37], 0, v[180:181]
	s_mov_b32 m0, s51
	s_nop 0
	global_load_lds_dwordx4 v[244:245], off
	s_waitcnt vmcnt(8) lgkmcnt(0)
	v_mfma_f32_16x16x32_bf16 v[30:33], v[130:133], v[200:203], v[30:33]
	v_mfma_f32_16x16x32_bf16 v[26:29], v[138:141], v[200:203], v[26:29]
	v_mfma_f32_16x16x32_bf16 v[46:49], v[130:133], v[208:211], v[46:49]
	v_mfma_f32_16x16x32_bf16 v[42:45], v[138:141], v[208:211], v[42:45]
	s_barrier
	s_setprio 1
	v_mfma_f32_16x16x32_bf16 v[62:65], v[130:133], v[228:231], v[62:65]
	v_mfma_f32_16x16x32_bf16 v[58:61], v[138:141], v[228:231], v[58:61]
	v_mfma_f32_16x16x32_bf16 v[94:97], v[130:133], v[236:239], v[94:97]
	v_mfma_f32_16x16x32_bf16 v[90:93], v[138:141], v[236:239], v[90:93]
	v_mfma_f32_16x16x32_bf16 v[30:33], v[134:137], v[204:207], v[30:33]
	v_mfma_f32_16x16x32_bf16 v[26:29], v[142:145], v[204:207], v[26:29]
	v_mfma_f32_16x16x32_bf16 v[46:49], v[134:137], v[212:215], v[46:49]
	v_mfma_f32_16x16x32_bf16 v[42:45], v[142:145], v[212:215], v[42:45]
	v_mfma_f32_16x16x32_bf16 v[62:65], v[134:137], v[232:235], v[62:65]
	v_mfma_f32_16x16x32_bf16 v[58:61], v[142:145], v[232:235], v[58:61]
	v_mfma_f32_16x16x32_bf16 v[94:97], v[134:137], v[240:243], v[94:97]
	v_mfma_f32_16x16x32_bf16 v[90:93], v[142:145], v[240:243], v[90:93]
	v_mfma_f32_16x16x32_bf16 v[2:5], v[184:187], v[200:203], v[2:5]
	v_mfma_f32_16x16x32_bf16 v[6:9], v[192:195], v[200:203], v[6:9]
	v_mfma_f32_16x16x32_bf16 v[10:13], v[184:187], v[208:211], v[10:13]
	v_mfma_f32_16x16x32_bf16 v[14:17], v[192:195], v[208:211], v[14:17]
	v_mfma_f32_16x16x32_bf16 v[18:21], v[184:187], v[228:231], v[18:21]
	v_mfma_f32_16x16x32_bf16 v[22:25], v[192:195], v[228:231], v[22:25]
	v_mfma_f32_16x16x32_bf16 v[34:37], v[184:187], v[236:239], v[34:37]
	v_mfma_f32_16x16x32_bf16 v[38:41], v[192:195], v[236:239], v[38:41]
	v_mfma_f32_16x16x32_bf16 v[2:5], v[188:191], v[204:207], v[2:5]
	v_mfma_f32_16x16x32_bf16 v[6:9], v[196:199], v[204:207], v[6:9]
	v_mfma_f32_16x16x32_bf16 v[10:13], v[188:191], v[212:215], v[10:13]
	v_mfma_f32_16x16x32_bf16 v[14:17], v[196:199], v[212:215], v[14:17]
	v_mfma_f32_16x16x32_bf16 v[18:21], v[188:191], v[232:235], v[18:21]
	v_mfma_f32_16x16x32_bf16 v[22:25], v[196:199], v[232:235], v[22:25]
	v_mfma_f32_16x16x32_bf16 v[34:37], v[188:191], v[240:243], v[34:37]
	v_mfma_f32_16x16x32_bf16 v[38:41], v[196:199], v[240:243], v[38:41]
	s_setprio 0
	s_barrier
	s_mov_b32 m0, s52
	v_lshl_add_u64 v[244:245], s[40:41], 0, v[150:151]
	s_add_u32 s14, s40, 0x160000
	ds_read_b128 v[200:203], v221 offset:16384
	ds_read_b128 v[204:207], v221 offset:17408
	ds_read_b128 v[208:211], v221 offset:18432
	ds_read_b128 v[212:215], v221 offset:19456
	ds_read_b128 v[228:231], v221 offset:20480
	ds_read_b128 v[232:235], v221 offset:21504
	ds_read_b128 v[236:239], v221 offset:22528
	ds_read_b128 v[240:243], v221 offset:23552
	global_load_lds_dwordx4 v[244:245], off
	v_lshl_add_u64 v[246:247], s[40:41], 0, v[146:147]
	s_mov_b32 m0, s53
	s_addc_u32 s15, s41, 0
	global_load_lds_dwordx4 v[246:247], off
	v_lshl_add_u64 v[248:249], s[14:15], 0, v[150:151]
	s_mov_b32 m0, s54
	v_lshl_add_u64 v[250:251], s[42:43], 0, v[148:149]
	global_load_lds_dwordx4 v[248:249], off
	v_lshl_add_u64 v[248:249], s[14:15], 0, v[146:147]
	s_mov_b32 m0, s55
	s_nop 0
	global_load_lds_dwordx4 v[248:249], off
	v_lshl_add_u64 v[248:249], s[42:43], 0, v[152:153]
	s_mov_b32 m0, s61
	s_nop 0
	global_load_lds_dwordx4 v[248:249], off
	s_mov_b32 m0, s62
	s_nop 0
	global_load_lds_dwordx4 v[250:251], off
	s_waitcnt vmcnt(8) lgkmcnt(0)
	v_mfma_f32_16x16x32_bf16 v[114:117], v[130:133], v[200:203], v[114:117]
	v_mfma_f32_16x16x32_bf16 v[110:113], v[138:141], v[200:203], v[110:113]
	v_mfma_f32_16x16x32_bf16 v[126:129], v[130:133], v[208:211], v[126:129]
	v_mfma_f32_16x16x32_bf16 v[122:125], v[138:141], v[208:211], v[122:125]
	s_barrier
	s_setprio 1
	v_mfma_f32_16x16x32_bf16 v[118:121], v[130:133], v[228:231], v[118:121]
	v_mfma_f32_16x16x32_bf16 v[106:109], v[138:141], v[228:231], v[106:109]
	v_mfma_f32_16x16x32_bf16 v[78:81], v[130:133], v[236:239], v[78:81]
	v_mfma_f32_16x16x32_bf16 v[74:77], v[138:141], v[236:239], v[74:77]
	v_mfma_f32_16x16x32_bf16 v[114:117], v[134:137], v[204:207], v[114:117]
	v_mfma_f32_16x16x32_bf16 v[110:113], v[142:145], v[204:207], v[110:113]
	v_mfma_f32_16x16x32_bf16 v[126:129], v[134:137], v[212:215], v[126:129]
	v_mfma_f32_16x16x32_bf16 v[122:125], v[142:145], v[212:215], v[122:125]
	v_mfma_f32_16x16x32_bf16 v[118:121], v[134:137], v[232:235], v[118:121]
	v_mfma_f32_16x16x32_bf16 v[106:109], v[142:145], v[232:235], v[106:109]
	v_mfma_f32_16x16x32_bf16 v[78:81], v[134:137], v[240:243], v[78:81]
	v_mfma_f32_16x16x32_bf16 v[74:77], v[142:145], v[240:243], v[74:77]
	v_mfma_f32_16x16x32_bf16 v[50:53], v[184:187], v[200:203], v[50:53]
	v_mfma_f32_16x16x32_bf16 v[54:57], v[192:195], v[200:203], v[54:57]
	v_mfma_f32_16x16x32_bf16 v[82:85], v[184:187], v[208:211], v[82:85]
	v_mfma_f32_16x16x32_bf16 v[86:89], v[192:195], v[208:211], v[86:89]
	v_mfma_f32_16x16x32_bf16 v[102:105], v[184:187], v[228:231], v[102:105]
	v_mfma_f32_16x16x32_bf16 v[98:101], v[192:195], v[228:231], v[98:101]
	v_mfma_f32_16x16x32_bf16 v[70:73], v[184:187], v[236:239], v[70:73]
	v_mfma_f32_16x16x32_bf16 v[66:69], v[192:195], v[236:239], v[66:69]
	v_mfma_f32_16x16x32_bf16 v[50:53], v[188:191], v[204:207], v[50:53]
	v_mfma_f32_16x16x32_bf16 v[54:57], v[196:199], v[204:207], v[54:57]
	v_mfma_f32_16x16x32_bf16 v[82:85], v[188:191], v[212:215], v[82:85]
	v_mfma_f32_16x16x32_bf16 v[86:89], v[196:199], v[212:215], v[86:89]
	v_mfma_f32_16x16x32_bf16 v[102:105], v[188:191], v[232:235], v[102:105]
	v_mfma_f32_16x16x32_bf16 v[98:101], v[196:199], v[232:235], v[98:101]
	v_mfma_f32_16x16x32_bf16 v[70:73], v[188:191], v[240:243], v[70:73]
	v_mfma_f32_16x16x32_bf16 v[66:69], v[196:199], v[240:243], v[66:69]
	s_setprio 0
	s_barrier
	v_add_u32_e32 v196, s74, v218
	ds_read_b128 v[130:133], v225
	ds_read_b128 v[134:137], v225 offset:1024
	ds_read_b128 v[138:141], v225 offset:2048
	ds_read_b128 v[142:145], v225 offset:3072
	ds_read_b128 v[184:187], v196
	ds_read_b128 v[188:191], v196 offset:1024
	ds_read_b128 v[192:195], v196 offset:2048
	ds_read_b128 v[196:199], v196 offset:3072
	s_add_u32 s14, s42, 0x160000
	s_addc_u32 s15, s43, 0
	s_mov_b32 m0, s63
	v_lshl_add_u64 v[252:253], s[14:15], 0, v[152:153]
	ds_read_b128 v[200:203], v221 offset:32768
	ds_read_b128 v[204:207], v221 offset:33792
	ds_read_b128 v[208:211], v221 offset:34816
	ds_read_b128 v[212:215], v221 offset:35840
	ds_read_b128 v[228:231], v221 offset:36864
	ds_read_b128 v[232:235], v221 offset:37888
	ds_read_b128 v[236:239], v221 offset:38912
	ds_read_b128 v[240:243], v221 offset:39936
	global_load_lds_dwordx4 v[252:253], off
	v_lshl_add_u64 v[252:253], s[14:15], 0, v[148:149]
	s_mov_b32 m0, s64
	s_nop 0
	global_load_lds_dwordx4 v[252:253], off
	s_waitcnt vmcnt(8) lgkmcnt(0)
	v_mfma_f32_16x16x32_bf16 v[30:33], v[130:133], v[200:203], v[30:33]
	v_mfma_f32_16x16x32_bf16 v[26:29], v[138:141], v[200:203], v[26:29]
	v_mfma_f32_16x16x32_bf16 v[46:49], v[130:133], v[208:211], v[46:49]
	v_mfma_f32_16x16x32_bf16 v[42:45], v[138:141], v[208:211], v[42:45]
	s_barrier
	s_setprio 1
	v_mfma_f32_16x16x32_bf16 v[62:65], v[130:133], v[228:231], v[62:65]
	v_mfma_f32_16x16x32_bf16 v[58:61], v[138:141], v[228:231], v[58:61]
	v_mfma_f32_16x16x32_bf16 v[94:97], v[130:133], v[236:239], v[94:97]
	v_mfma_f32_16x16x32_bf16 v[90:93], v[138:141], v[236:239], v[90:93]
	v_mfma_f32_16x16x32_bf16 v[30:33], v[134:137], v[204:207], v[30:33]
	v_mfma_f32_16x16x32_bf16 v[26:29], v[142:145], v[204:207], v[26:29]
	v_mfma_f32_16x16x32_bf16 v[46:49], v[134:137], v[212:215], v[46:49]
	v_mfma_f32_16x16x32_bf16 v[42:45], v[142:145], v[212:215], v[42:45]
	v_mfma_f32_16x16x32_bf16 v[62:65], v[134:137], v[232:235], v[62:65]
	v_mfma_f32_16x16x32_bf16 v[58:61], v[142:145], v[232:235], v[58:61]
	v_mfma_f32_16x16x32_bf16 v[94:97], v[134:137], v[240:243], v[94:97]
	v_mfma_f32_16x16x32_bf16 v[90:93], v[142:145], v[240:243], v[90:93]
	v_mfma_f32_16x16x32_bf16 v[2:5], v[184:187], v[200:203], v[2:5]
	v_mfma_f32_16x16x32_bf16 v[6:9], v[192:195], v[200:203], v[6:9]
	v_mfma_f32_16x16x32_bf16 v[10:13], v[184:187], v[208:211], v[10:13]
	v_mfma_f32_16x16x32_bf16 v[14:17], v[192:195], v[208:211], v[14:17]
	v_mfma_f32_16x16x32_bf16 v[18:21], v[184:187], v[228:231], v[18:21]
	v_mfma_f32_16x16x32_bf16 v[22:25], v[192:195], v[228:231], v[22:25]
	v_mfma_f32_16x16x32_bf16 v[34:37], v[184:187], v[236:239], v[34:37]
	v_mfma_f32_16x16x32_bf16 v[38:41], v[192:195], v[236:239], v[38:41]
	v_mfma_f32_16x16x32_bf16 v[2:5], v[188:191], v[204:207], v[2:5]
	v_mfma_f32_16x16x32_bf16 v[6:9], v[196:199], v[204:207], v[6:9]
	v_mfma_f32_16x16x32_bf16 v[10:13], v[188:191], v[212:215], v[10:13]
	v_mfma_f32_16x16x32_bf16 v[14:17], v[196:199], v[212:215], v[14:17]
	v_mfma_f32_16x16x32_bf16 v[18:21], v[188:191], v[232:235], v[18:21]
	v_mfma_f32_16x16x32_bf16 v[22:25], v[196:199], v[232:235], v[22:25]
	v_mfma_f32_16x16x32_bf16 v[34:37], v[188:191], v[240:243], v[34:37]
	v_mfma_f32_16x16x32_bf16 v[38:41], v[196:199], v[240:243], v[38:41]
	s_setprio 0
	s_barrier
	s_mov_b32 m0, s75
	v_lshl_add_u64 v[244:245], v[244:245], 0, s[22:23]
	s_add_u32 s14, s40, 0x160080
	ds_read_b128 v[200:203], v221 offset:49152
	ds_read_b128 v[204:207], v221 offset:50176
	ds_read_b128 v[208:211], v221 offset:51200
	ds_read_b128 v[212:215], v221 offset:52224
	ds_read_b128 v[228:231], v221 offset:53248
	ds_read_b128 v[232:235], v221 offset:54272
	ds_read_b128 v[236:239], v221 offset:55296
	ds_read_b128 v[240:243], v221 offset:56320
	global_load_lds_dwordx4 v[244:245], off
	v_lshl_add_u64 v[244:245], v[246:247], 0, s[22:23]
	s_mov_b32 m0, s76
	s_addc_u32 s15, s41, 0
	global_load_lds_dwordx4 v[244:245], off
	v_lshl_add_u64 v[244:245], s[14:15], 0, v[150:151]
	s_mov_b32 m0, s77
	s_nop 0
	global_load_lds_dwordx4 v[244:245], off
	v_lshl_add_u64 v[244:245], s[14:15], 0, v[146:147]
	s_mov_b32 m0, s78
	s_nop 0
	global_load_lds_dwordx4 v[244:245], off
	v_lshl_add_u64 v[244:245], v[248:249], 0, s[22:23]
	s_mov_b32 m0, s68
	s_nop 0
	global_load_lds_dwordx4 v[244:245], off
	v_lshl_add_u64 v[244:245], v[250:251], 0, s[22:23]
	s_mov_b32 m0, s69
	s_nop 0
	global_load_lds_dwordx4 v[244:245], off
	s_waitcnt vmcnt(8) lgkmcnt(0)
	v_mfma_f32_16x16x32_bf16 v[114:117], v[130:133], v[200:203], v[114:117]
	v_mfma_f32_16x16x32_bf16 v[110:113], v[138:141], v[200:203], v[110:113]
	v_mfma_f32_16x16x32_bf16 v[126:129], v[130:133], v[208:211], v[126:129]
	v_mfma_f32_16x16x32_bf16 v[122:125], v[138:141], v[208:211], v[122:125]
	s_barrier
	s_setprio 1
	v_mfma_f32_16x16x32_bf16 v[118:121], v[130:133], v[228:231], v[118:121]
	v_mfma_f32_16x16x32_bf16 v[106:109], v[138:141], v[228:231], v[106:109]
	v_mfma_f32_16x16x32_bf16 v[78:81], v[130:133], v[236:239], v[78:81]
	v_mfma_f32_16x16x32_bf16 v[74:77], v[138:141], v[236:239], v[74:77]
	v_mfma_f32_16x16x32_bf16 v[114:117], v[134:137], v[204:207], v[114:117]
	v_mfma_f32_16x16x32_bf16 v[110:113], v[142:145], v[204:207], v[110:113]
	v_mfma_f32_16x16x32_bf16 v[126:129], v[134:137], v[212:215], v[126:129]
	v_mfma_f32_16x16x32_bf16 v[122:125], v[142:145], v[212:215], v[122:125]
	v_mfma_f32_16x16x32_bf16 v[118:121], v[134:137], v[232:235], v[118:121]
	v_mfma_f32_16x16x32_bf16 v[106:109], v[142:145], v[232:235], v[106:109]
	v_mfma_f32_16x16x32_bf16 v[78:81], v[134:137], v[240:243], v[78:81]
	v_mfma_f32_16x16x32_bf16 v[74:77], v[142:145], v[240:243], v[74:77]
	v_mfma_f32_16x16x32_bf16 v[50:53], v[184:187], v[200:203], v[50:53]
	v_mfma_f32_16x16x32_bf16 v[54:57], v[192:195], v[200:203], v[54:57]
	v_mfma_f32_16x16x32_bf16 v[82:85], v[184:187], v[208:211], v[82:85]
	v_mfma_f32_16x16x32_bf16 v[86:89], v[192:195], v[208:211], v[86:89]
	v_mfma_f32_16x16x32_bf16 v[102:105], v[184:187], v[228:231], v[102:105]
	v_mfma_f32_16x16x32_bf16 v[98:101], v[192:195], v[228:231], v[98:101]
	v_mfma_f32_16x16x32_bf16 v[70:73], v[184:187], v[236:239], v[70:73]
	v_mfma_f32_16x16x32_bf16 v[66:69], v[192:195], v[236:239], v[66:69]
	v_mfma_f32_16x16x32_bf16 v[50:53], v[188:191], v[204:207], v[50:53]
	v_mfma_f32_16x16x32_bf16 v[54:57], v[196:199], v[204:207], v[54:57]
	v_mfma_f32_16x16x32_bf16 v[82:85], v[188:191], v[212:215], v[82:85]
	v_mfma_f32_16x16x32_bf16 v[86:89], v[196:199], v[212:215], v[86:89]
	v_mfma_f32_16x16x32_bf16 v[102:105], v[188:191], v[232:235], v[102:105]
	v_mfma_f32_16x16x32_bf16 v[98:101], v[196:199], v[232:235], v[98:101]
	v_mfma_f32_16x16x32_bf16 v[70:73], v[188:191], v[240:243], v[70:73]
	v_mfma_f32_16x16x32_bf16 v[66:69], v[196:199], v[240:243], v[66:69]
	s_setprio 0
	s_barrier
	s_add_i32 s3, s3, 2
	s_add_u32 s36, s36, 0x100
	s_addc_u32 s37, s37, 0
	s_add_u32 s38, s38, 0x100
	s_addc_u32 s39, s39, 0
	s_cmpk_gt_u32 s3, 0x55
	s_cbranch_scc0 .LBB0_877
	s_and_b64 vcc, exec, s[24:25]
	s_cbranch_vccz .LBB0_880
	s_barrier

.LBB0_986:
	ds_read_b128 v[130:133], v172
	ds_read_b128 v[134:137], v172 offset:1024
	ds_read_b128 v[138:141], v172 offset:2048
	ds_read_b128 v[142:145], v172 offset:3072
	ds_read_b128 v[166:169], v173
	ds_read_b128 v[176:179], v173 offset:1024
	ds_read_b128 v[180:183], v173 offset:2048
	ds_read_b128 v[184:187], v173 offset:3072
	s_add_u32 s20, s52, 0xfff80080
	s_addc_u32 s21, s53, -1
	s_cmp_eq_u32 s19, 28
	s_cselect_b32 s57, s3, s21
	s_cselect_b32 s56, s14, s20
	s_cselect_b32 s55, s15, s18
	s_cselect_b32 s54, s16, s17
	v_lshl_add_u64 v[220:221], s[52:53], 0, v[156:157]
	s_add_i32 m0, s65, 0xc000
	ds_read_b128 v[188:191], v174
	ds_read_b128 v[192:195], v174 offset:1024
	ds_read_b128 v[196:199], v174 offset:2048
	ds_read_b128 v[200:203], v174 offset:3072
	ds_read_b128 v[204:207], v174 offset:4096
	ds_read_b128 v[208:211], v174 offset:5120
	ds_read_b128 v[212:215], v174 offset:6144
	ds_read_b128 v[216:219], v174 offset:7168
	global_load_lds_dwordx4 v[220:221], off
	v_lshl_add_u64 v[220:221], s[52:53], 0, v[158:159]
	s_add_i32 m0, s65, 0xe000
	s_nop 0
	global_load_lds_dwordx4 v[220:221], off
	s_waitcnt vmcnt(8) lgkmcnt(0)
	v_mfma_f32_16x16x32_bf16 v[126:129], v[130:133], v[188:191], v[126:129]
	v_mfma_f32_16x16x32_bf16 v[122:125], v[138:141], v[188:191], v[122:125]
	v_mfma_f32_16x16x32_bf16 v[110:113], v[130:133], v[196:199], v[110:113]
	v_mfma_f32_16x16x32_bf16 v[106:109], v[138:141], v[196:199], v[106:109]
	s_barrier
	s_setprio 1
	v_mfma_f32_16x16x32_bf16 v[94:97], v[130:133], v[204:207], v[94:97]
	v_mfma_f32_16x16x32_bf16 v[90:93], v[138:141], v[204:207], v[90:93]
	v_mfma_f32_16x16x32_bf16 v[78:81], v[130:133], v[212:215], v[78:81]
	v_mfma_f32_16x16x32_bf16 v[74:77], v[138:141], v[212:215], v[74:77]
	v_mfma_f32_16x16x32_bf16 v[126:129], v[134:137], v[192:195], v[126:129]
	v_mfma_f32_16x16x32_bf16 v[122:125], v[142:145], v[192:195], v[122:125]
	v_mfma_f32_16x16x32_bf16 v[110:113], v[134:137], v[200:203], v[110:113]
	v_mfma_f32_16x16x32_bf16 v[106:109], v[142:145], v[200:203], v[106:109]
	v_mfma_f32_16x16x32_bf16 v[94:97], v[134:137], v[208:211], v[94:97]
	v_mfma_f32_16x16x32_bf16 v[90:93], v[142:145], v[208:211], v[90:93]
	v_mfma_f32_16x16x32_bf16 v[78:81], v[134:137], v[216:219], v[78:81]
	v_mfma_f32_16x16x32_bf16 v[74:77], v[142:145], v[216:219], v[74:77]
	v_mfma_f32_16x16x32_bf16 v[118:121], v[166:169], v[188:191], v[118:121]
	v_mfma_f32_16x16x32_bf16 v[114:117], v[180:183], v[188:191], v[114:117]
	v_mfma_f32_16x16x32_bf16 v[102:105], v[166:169], v[196:199], v[102:105]
	v_mfma_f32_16x16x32_bf16 v[98:101], v[180:183], v[196:199], v[98:101]
	v_mfma_f32_16x16x32_bf16 v[86:89], v[166:169], v[204:207], v[86:89]
	v_mfma_f32_16x16x32_bf16 v[82:85], v[180:183], v[204:207], v[82:85]
	v_mfma_f32_16x16x32_bf16 v[70:73], v[166:169], v[212:215], v[70:73]
	v_mfma_f32_16x16x32_bf16 v[66:69], v[180:183], v[212:215], v[66:69]
	v_mfma_f32_16x16x32_bf16 v[118:121], v[176:179], v[192:195], v[118:121]
	v_mfma_f32_16x16x32_bf16 v[114:117], v[184:187], v[192:195], v[114:117]
	v_mfma_f32_16x16x32_bf16 v[102:105], v[176:179], v[200:203], v[102:105]
	v_mfma_f32_16x16x32_bf16 v[98:101], v[184:187], v[200:203], v[98:101]
	v_mfma_f32_16x16x32_bf16 v[86:89], v[176:179], v[208:211], v[86:89]
	v_mfma_f32_16x16x32_bf16 v[82:85], v[184:187], v[208:211], v[82:85]
	v_mfma_f32_16x16x32_bf16 v[70:73], v[176:179], v[216:219], v[70:73]
	v_mfma_f32_16x16x32_bf16 v[66:69], v[184:187], v[216:219], v[66:69]
	s_setprio 0
	s_barrier
	s_add_i32 s20, s77, s64
	v_lshl_add_u64 v[220:221], s[54:55], 0, v[146:147]
	s_mov_b32 m0, s20
	ds_read_b128 v[188:191], v174 offset:16384
	ds_read_b128 v[192:195], v174 offset:17408
	ds_read_b128 v[196:199], v174 offset:18432
	ds_read_b128 v[200:203], v174 offset:19456
	ds_read_b128 v[204:207], v174 offset:20480
	ds_read_b128 v[208:211], v174 offset:21504
	ds_read_b128 v[212:215], v174 offset:22528
	ds_read_b128 v[216:219], v174 offset:23552
	global_load_lds_dwordx4 v[220:221], off
	s_add_i32 m0, s20, 0x2000
	s_add_u32 s20, s54, 0x80000
	v_lshl_add_u64 v[222:223], s[54:55], 0, v[148:149]
	s_addc_u32 s21, s55, 0
	s_add_i32 s43, s78, s64
	global_load_lds_dwordx4 v[222:223], off
	v_lshl_add_u64 v[224:225], s[20:21], 0, v[146:147]
	s_mov_b32 m0, s43
	v_lshl_add_u64 v[226:227], s[56:57], 0, v[148:149]
	global_load_lds_dwordx4 v[224:225], off
	v_lshl_add_u64 v[224:225], s[20:21], 0, v[148:149]
	s_add_i32 m0, s43, 0x2000
	s_nop 0
	global_load_lds_dwordx4 v[224:225], off
	v_lshl_add_u64 v[224:225], s[56:57], 0, v[146:147]
	s_mov_b32 m0, s65
	s_nop 0
	global_load_lds_dwordx4 v[224:225], off
	s_mov_b32 m0, s66
	s_nop 0
	global_load_lds_dwordx4 v[226:227], off
	s_waitcnt vmcnt(8) lgkmcnt(0)
	v_mfma_f32_16x16x32_bf16 v[62:65], v[130:133], v[188:191], v[62:65]
	v_mfma_f32_16x16x32_bf16 v[58:61], v[138:141], v[188:191], v[58:61]
	v_mfma_f32_16x16x32_bf16 v[46:49], v[130:133], v[196:199], v[46:49]
	v_mfma_f32_16x16x32_bf16 v[42:45], v[138:141], v[196:199], v[42:45]
	s_barrier
	s_setprio 1
	v_mfma_f32_16x16x32_bf16 v[30:33], v[130:133], v[204:207], v[30:33]
	v_mfma_f32_16x16x32_bf16 v[26:29], v[138:141], v[204:207], v[26:29]
	v_mfma_f32_16x16x32_bf16 v[14:17], v[130:133], v[212:215], v[14:17]
	v_mfma_f32_16x16x32_bf16 v[10:13], v[138:141], v[212:215], v[10:13]
	v_mfma_f32_16x16x32_bf16 v[62:65], v[134:137], v[192:195], v[62:65]
	v_mfma_f32_16x16x32_bf16 v[58:61], v[142:145], v[192:195], v[58:61]
	v_mfma_f32_16x16x32_bf16 v[46:49], v[134:137], v[200:203], v[46:49]
	v_mfma_f32_16x16x32_bf16 v[42:45], v[142:145], v[200:203], v[42:45]
	v_mfma_f32_16x16x32_bf16 v[30:33], v[134:137], v[208:211], v[30:33]
	v_mfma_f32_16x16x32_bf16 v[26:29], v[142:145], v[208:211], v[26:29]
	v_mfma_f32_16x16x32_bf16 v[14:17], v[134:137], v[216:219], v[14:17]
	v_mfma_f32_16x16x32_bf16 v[10:13], v[142:145], v[216:219], v[10:13]
	v_mfma_f32_16x16x32_bf16 v[54:57], v[166:169], v[188:191], v[54:57]
	v_mfma_f32_16x16x32_bf16 v[50:53], v[180:183], v[188:191], v[50:53]
	v_mfma_f32_16x16x32_bf16 v[38:41], v[166:169], v[196:199], v[38:41]
	v_mfma_f32_16x16x32_bf16 v[34:37], v[180:183], v[196:199], v[34:37]
	v_mfma_f32_16x16x32_bf16 v[22:25], v[166:169], v[204:207], v[22:25]
	v_mfma_f32_16x16x32_bf16 v[18:21], v[180:183], v[204:207], v[18:21]
	v_mfma_f32_16x16x32_bf16 v[6:9], v[166:169], v[212:215], v[6:9]
	v_mfma_f32_16x16x32_bf16 v[2:5], v[180:183], v[212:215], v[2:5]
	v_mfma_f32_16x16x32_bf16 v[54:57], v[176:179], v[192:195], v[54:57]
	v_mfma_f32_16x16x32_bf16 v[50:53], v[184:187], v[192:195], v[50:53]
	v_mfma_f32_16x16x32_bf16 v[38:41], v[176:179], v[200:203], v[38:41]
	v_mfma_f32_16x16x32_bf16 v[34:37], v[184:187], v[200:203], v[34:37]
	v_mfma_f32_16x16x32_bf16 v[22:25], v[176:179], v[208:211], v[22:25]
	v_mfma_f32_16x16x32_bf16 v[18:21], v[184:187], v[208:211], v[18:21]
	v_mfma_f32_16x16x32_bf16 v[6:9], v[176:179], v[216:219], v[6:9]
	v_mfma_f32_16x16x32_bf16 v[2:5], v[184:187], v[216:219], v[2:5]
	s_setprio 0
	s_barrier
	s_add_i32 s43, 0, 0x18000
	s_add_i32 s45, 0, 0x1c000
	v_add_u32_e32 v142, s43, v170
	v_add_u32_e32 v184, s45, v170
	ds_read_b128 v[130:133], v142
	ds_read_b128 v[134:137], v142 offset:1024
	ds_read_b128 v[138:141], v142 offset:2048
	ds_read_b128 v[142:145], v142 offset:3072
	ds_read_b128 v[166:169], v184
	ds_read_b128 v[176:179], v184 offset:1024
	ds_read_b128 v[180:183], v184 offset:2048
	ds_read_b128 v[184:187], v184 offset:3072
	s_add_u32 s20, s56, 0x80000
	s_addc_u32 s21, s57, 0
	s_mov_b32 m0, s67
	v_lshl_add_u64 v[228:229], s[20:21], 0, v[146:147]
	ds_read_b128 v[188:191], v174 offset:32768
	ds_read_b128 v[192:195], v174 offset:33792
	ds_read_b128 v[196:199], v174 offset:34816
	ds_read_b128 v[200:203], v174 offset:35840
	ds_read_b128 v[204:207], v174 offset:36864
	ds_read_b128 v[208:211], v174 offset:37888
	ds_read_b128 v[212:215], v174 offset:38912
	ds_read_b128 v[216:219], v174 offset:39936
	global_load_lds_dwordx4 v[228:229], off
	v_lshl_add_u64 v[228:229], s[20:21], 0, v[148:149]
	s_mov_b32 m0, s68
	s_nop 0
	global_load_lds_dwordx4 v[228:229], off
	s_waitcnt vmcnt(8) lgkmcnt(0)
	v_mfma_f32_16x16x32_bf16 v[126:129], v[130:133], v[188:191], v[126:129]
	v_mfma_f32_16x16x32_bf16 v[122:125], v[138:141], v[188:191], v[122:125]
	v_mfma_f32_16x16x32_bf16 v[110:113], v[130:133], v[196:199], v[110:113]
	v_mfma_f32_16x16x32_bf16 v[106:109], v[138:141], v[196:199], v[106:109]
	s_barrier
	s_setprio 1
	v_mfma_f32_16x16x32_bf16 v[94:97], v[130:133], v[204:207], v[94:97]
	v_mfma_f32_16x16x32_bf16 v[90:93], v[138:141], v[204:207], v[90:93]
	v_mfma_f32_16x16x32_bf16 v[78:81], v[130:133], v[212:215], v[78:81]
	v_mfma_f32_16x16x32_bf16 v[74:77], v[138:141], v[212:215], v[74:77]
	v_mfma_f32_16x16x32_bf16 v[126:129], v[134:137], v[192:195], v[126:129]
	v_mfma_f32_16x16x32_bf16 v[122:125], v[142:145], v[192:195], v[122:125]
	v_mfma_f32_16x16x32_bf16 v[110:113], v[134:137], v[200:203], v[110:113]
	v_mfma_f32_16x16x32_bf16 v[106:109], v[142:145], v[200:203], v[106:109]
	v_mfma_f32_16x16x32_bf16 v[94:97], v[134:137], v[208:211], v[94:97]
	v_mfma_f32_16x16x32_bf16 v[90:93], v[142:145], v[208:211], v[90:93]
	v_mfma_f32_16x16x32_bf16 v[78:81], v[134:137], v[216:219], v[78:81]
	v_mfma_f32_16x16x32_bf16 v[74:77], v[142:145], v[216:219], v[74:77]
	v_mfma_f32_16x16x32_bf16 v[118:121], v[166:169], v[188:191], v[118:121]
	v_mfma_f32_16x16x32_bf16 v[114:117], v[180:183], v[188:191], v[114:117]
	v_mfma_f32_16x16x32_bf16 v[102:105], v[166:169], v[196:199], v[102:105]
	v_mfma_f32_16x16x32_bf16 v[98:101], v[180:183], v[196:199], v[98:101]
	v_mfma_f32_16x16x32_bf16 v[86:89], v[166:169], v[204:207], v[86:89]
	v_mfma_f32_16x16x32_bf16 v[82:85], v[180:183], v[204:207], v[82:85]
	v_mfma_f32_16x16x32_bf16 v[70:73], v[166:169], v[212:215], v[70:73]
	v_mfma_f32_16x16x32_bf16 v[66:69], v[180:183], v[212:215], v[66:69]
	v_mfma_f32_16x16x32_bf16 v[118:121], v[176:179], v[192:195], v[118:121]
	v_mfma_f32_16x16x32_bf16 v[114:117], v[184:187], v[192:195], v[114:117]
	v_mfma_f32_16x16x32_bf16 v[102:105], v[176:179], v[200:203], v[102:105]
	v_mfma_f32_16x16x32_bf16 v[98:101], v[184:187], v[200:203], v[98:101]
	v_mfma_f32_16x16x32_bf16 v[86:89], v[176:179], v[208:211], v[86:89]
	v_mfma_f32_16x16x32_bf16 v[82:85], v[184:187], v[208:211], v[82:85]
	v_mfma_f32_16x16x32_bf16 v[70:73], v[176:179], v[216:219], v[70:73]
	v_mfma_f32_16x16x32_bf16 v[66:69], v[184:187], v[216:219], v[66:69]
	s_setprio 0
	s_barrier
	s_add_i32 s20, s43, s64
	v_lshl_add_u64 v[220:221], v[220:221], 0, s[26:27]
	s_mov_b32 m0, s20
	ds_read_b128 v[188:191], v174 offset:49152
	ds_read_b128 v[192:195], v174 offset:50176
	ds_read_b128 v[196:199], v174 offset:51200
	ds_read_b128 v[200:203], v174 offset:52224
	ds_read_b128 v[204:207], v174 offset:53248
	ds_read_b128 v[208:211], v174 offset:54272
	ds_read_b128 v[212:215], v174 offset:55296
	ds_read_b128 v[216:219], v174 offset:56320
	global_load_lds_dwordx4 v[220:221], off
	s_add_i32 m0, s20, 0x2000
	s_add_u32 s20, s54, 0x80080
	v_lshl_add_u64 v[220:221], v[222:223], 0, s[26:27]
	s_addc_u32 s21, s55, 0
	s_add_i32 s43, s45, s64
	global_load_lds_dwordx4 v[220:221], off
	v_lshl_add_u64 v[220:221], s[20:21], 0, v[146:147]
	s_mov_b32 m0, s43
	s_nop 0
	global_load_lds_dwordx4 v[220:221], off
	v_lshl_add_u64 v[220:221], s[20:21], 0, v[148:149]
	s_add_i32 m0, s43, 0x2000
	s_nop 0
	global_load_lds_dwordx4 v[220:221], off
	v_lshl_add_u64 v[220:221], v[224:225], 0, s[26:27]
	s_mov_b32 m0, s73
	s_nop 0
	global_load_lds_dwordx4 v[220:221], off
	v_lshl_add_u64 v[220:221], v[226:227], 0, s[26:27]
	s_mov_b32 m0, s74
	s_nop 0
	global_load_lds_dwordx4 v[220:221], off
	s_waitcnt vmcnt(8) lgkmcnt(0)
	v_mfma_f32_16x16x32_bf16 v[62:65], v[130:133], v[188:191], v[62:65]
	v_mfma_f32_16x16x32_bf16 v[58:61], v[138:141], v[188:191], v[58:61]
	v_mfma_f32_16x16x32_bf16 v[46:49], v[130:133], v[196:199], v[46:49]
	v_mfma_f32_16x16x32_bf16 v[42:45], v[138:141], v[196:199], v[42:45]
	s_barrier
	s_setprio 1
	v_mfma_f32_16x16x32_bf16 v[30:33], v[130:133], v[204:207], v[30:33]
	v_mfma_f32_16x16x32_bf16 v[26:29], v[138:141], v[204:207], v[26:29]
	v_mfma_f32_16x16x32_bf16 v[14:17], v[130:133], v[212:215], v[14:17]
	v_mfma_f32_16x16x32_bf16 v[10:13], v[138:141], v[212:215], v[10:13]
	v_mfma_f32_16x16x32_bf16 v[62:65], v[134:137], v[192:195], v[62:65]
	v_mfma_f32_16x16x32_bf16 v[58:61], v[142:145], v[192:195], v[58:61]
	v_mfma_f32_16x16x32_bf16 v[46:49], v[134:137], v[200:203], v[46:49]
	v_mfma_f32_16x16x32_bf16 v[42:45], v[142:145], v[200:203], v[42:45]
	v_mfma_f32_16x16x32_bf16 v[30:33], v[134:137], v[208:211], v[30:33]
	v_mfma_f32_16x16x32_bf16 v[26:29], v[142:145], v[208:211], v[26:29]
	v_mfma_f32_16x16x32_bf16 v[14:17], v[134:137], v[216:219], v[14:17]
	v_mfma_f32_16x16x32_bf16 v[10:13], v[142:145], v[216:219], v[10:13]
	v_mfma_f32_16x16x32_bf16 v[54:57], v[166:169], v[188:191], v[54:57]
	v_mfma_f32_16x16x32_bf16 v[50:53], v[180:183], v[188:191], v[50:53]
	v_mfma_f32_16x16x32_bf16 v[38:41], v[166:169], v[196:199], v[38:41]
	v_mfma_f32_16x16x32_bf16 v[34:37], v[180:183], v[196:199], v[34:37]
	v_mfma_f32_16x16x32_bf16 v[22:25], v[166:169], v[204:207], v[22:25]
	v_mfma_f32_16x16x32_bf16 v[18:21], v[180:183], v[204:207], v[18:21]
	v_mfma_f32_16x16x32_bf16 v[6:9], v[166:169], v[212:215], v[6:9]
	v_mfma_f32_16x16x32_bf16 v[2:5], v[180:183], v[212:215], v[2:5]
	v_mfma_f32_16x16x32_bf16 v[54:57], v[176:179], v[192:195], v[54:57]
	v_mfma_f32_16x16x32_bf16 v[50:53], v[184:187], v[192:195], v[50:53]
	v_mfma_f32_16x16x32_bf16 v[38:41], v[176:179], v[200:203], v[38:41]
	v_mfma_f32_16x16x32_bf16 v[34:37], v[184:187], v[200:203], v[34:37]
	v_mfma_f32_16x16x32_bf16 v[22:25], v[176:179], v[208:211], v[22:25]
	v_mfma_f32_16x16x32_bf16 v[18:21], v[184:187], v[208:211], v[18:21]
	v_mfma_f32_16x16x32_bf16 v[6:9], v[176:179], v[216:219], v[6:9]
	v_mfma_f32_16x16x32_bf16 v[2:5], v[184:187], v[216:219], v[2:5]
	s_setprio 0
	s_barrier
	s_add_i32 s19, s19, 2
	s_add_u32 s52, s52, 0x100
	s_addc_u32 s53, s53, 0
	s_add_u32 s17, s17, 0x100
	s_addc_u32 s18, s18, 0
	s_cmp_gt_u32 s19, 29
	s_cbranch_scc0 .LBB0_986
	s_and_b64 vcc, exec, s[28:29]
	s_cbranch_vccnz .LBB0_991
	v_lshl_add_u32 v166, s50, 8, v163
	s_cmp_gt_i32 s10, 1
	s_mov_b64 s[50:51], -1
	s_cbranch_scc1 .LBB0_992

.LBB0_1213:
	ds_read_b128 v[130:133], v189
	ds_read_b128 v[134:137], v189 offset:1024
	ds_read_b128 v[138:141], v189 offset:2048
	ds_read_b128 v[142:145], v189 offset:3072
	ds_read_b128 v[164:167], v190
	ds_read_b128 v[168:171], v190 offset:1024
	ds_read_b128 v[172:175], v190 offset:2048
	ds_read_b128 v[194:197], v190 offset:3072
	s_add_u32 s20, s52, 0xfff80080
	s_addc_u32 s21, s53, -1
	s_cmp_eq_u32 s19, 28
	s_cselect_b32 s57, s3, s21
	s_cselect_b32 s56, s14, s20
	s_cselect_b32 s55, s15, s18
	s_cselect_b32 s54, s16, s17
	v_lshl_add_u64 v[230:231], s[52:53], 0, v[154:155]
	s_add_i32 m0, s65, 0xc000
	ds_read_b128 v[198:201], v191
	ds_read_b128 v[202:205], v191 offset:1024
	ds_read_b128 v[206:209], v191 offset:2048
	ds_read_b128 v[210:213], v191 offset:3072
	ds_read_b128 v[214:217], v191 offset:4096
	ds_read_b128 v[218:221], v191 offset:5120
	ds_read_b128 v[222:225], v191 offset:6144
	ds_read_b128 v[226:229], v191 offset:7168
	global_load_lds_dwordx4 v[230:231], off
	v_lshl_add_u64 v[230:231], s[52:53], 0, v[156:157]
	s_add_i32 m0, s65, 0xe000
	s_nop 0
	global_load_lds_dwordx4 v[230:231], off
	s_waitcnt vmcnt(8) lgkmcnt(0)
	v_mfma_f32_16x16x32_bf16 v[126:129], v[130:133], v[198:201], v[126:129]
	v_mfma_f32_16x16x32_bf16 v[122:125], v[138:141], v[198:201], v[122:125]
	v_mfma_f32_16x16x32_bf16 v[110:113], v[130:133], v[206:209], v[110:113]
	v_mfma_f32_16x16x32_bf16 v[106:109], v[138:141], v[206:209], v[106:109]
	s_barrier
	s_setprio 1
	v_mfma_f32_16x16x32_bf16 v[94:97], v[130:133], v[214:217], v[94:97]
	v_mfma_f32_16x16x32_bf16 v[90:93], v[138:141], v[214:217], v[90:93]
	v_mfma_f32_16x16x32_bf16 v[78:81], v[130:133], v[222:225], v[78:81]
	v_mfma_f32_16x16x32_bf16 v[74:77], v[138:141], v[222:225], v[74:77]
	v_mfma_f32_16x16x32_bf16 v[126:129], v[134:137], v[202:205], v[126:129]
	v_mfma_f32_16x16x32_bf16 v[122:125], v[142:145], v[202:205], v[122:125]
	v_mfma_f32_16x16x32_bf16 v[110:113], v[134:137], v[210:213], v[110:113]
	v_mfma_f32_16x16x32_bf16 v[106:109], v[142:145], v[210:213], v[106:109]
	v_mfma_f32_16x16x32_bf16 v[94:97], v[134:137], v[218:221], v[94:97]
	v_mfma_f32_16x16x32_bf16 v[90:93], v[142:145], v[218:221], v[90:93]
	v_mfma_f32_16x16x32_bf16 v[78:81], v[134:137], v[226:229], v[78:81]
	v_mfma_f32_16x16x32_bf16 v[74:77], v[142:145], v[226:229], v[74:77]
	v_mfma_f32_16x16x32_bf16 v[118:121], v[164:167], v[198:201], v[118:121]
	v_mfma_f32_16x16x32_bf16 v[114:117], v[172:175], v[198:201], v[114:117]
	v_mfma_f32_16x16x32_bf16 v[102:105], v[164:167], v[206:209], v[102:105]
	v_mfma_f32_16x16x32_bf16 v[98:101], v[172:175], v[206:209], v[98:101]
	v_mfma_f32_16x16x32_bf16 v[86:89], v[164:167], v[214:217], v[86:89]
	v_mfma_f32_16x16x32_bf16 v[82:85], v[172:175], v[214:217], v[82:85]
	v_mfma_f32_16x16x32_bf16 v[70:73], v[164:167], v[222:225], v[70:73]
	v_mfma_f32_16x16x32_bf16 v[66:69], v[172:175], v[222:225], v[66:69]
	v_mfma_f32_16x16x32_bf16 v[118:121], v[168:171], v[202:205], v[118:121]
	v_mfma_f32_16x16x32_bf16 v[114:117], v[194:197], v[202:205], v[114:117]
	v_mfma_f32_16x16x32_bf16 v[102:105], v[168:171], v[210:213], v[102:105]
	v_mfma_f32_16x16x32_bf16 v[98:101], v[194:197], v[210:213], v[98:101]
	v_mfma_f32_16x16x32_bf16 v[86:89], v[168:171], v[218:221], v[86:89]
	v_mfma_f32_16x16x32_bf16 v[82:85], v[194:197], v[218:221], v[82:85]
	v_mfma_f32_16x16x32_bf16 v[70:73], v[168:171], v[226:229], v[70:73]
	v_mfma_f32_16x16x32_bf16 v[66:69], v[194:197], v[226:229], v[66:69]
	s_setprio 0
	s_barrier
	s_add_i32 s20, s77, s64
	v_lshl_add_u64 v[230:231], s[54:55], 0, v[146:147]
	s_mov_b32 m0, s20
	ds_read_b128 v[198:201], v191 offset:16384
	ds_read_b128 v[202:205], v191 offset:17408
	ds_read_b128 v[206:209], v191 offset:18432
	ds_read_b128 v[210:213], v191 offset:19456
	ds_read_b128 v[214:217], v191 offset:20480
	ds_read_b128 v[218:221], v191 offset:21504
	ds_read_b128 v[222:225], v191 offset:22528
	ds_read_b128 v[226:229], v191 offset:23552
	global_load_lds_dwordx4 v[230:231], off
	s_add_i32 m0, s20, 0x2000
	s_add_u32 s20, s54, 0x80000
	v_lshl_add_u64 v[232:233], s[54:55], 0, v[148:149]
	s_addc_u32 s21, s55, 0
	s_add_i32 s43, s78, s64
	global_load_lds_dwordx4 v[232:233], off
	v_lshl_add_u64 v[234:235], s[20:21], 0, v[146:147]
	s_mov_b32 m0, s43
	v_lshl_add_u64 v[236:237], s[56:57], 0, v[148:149]
	global_load_lds_dwordx4 v[234:235], off
	v_lshl_add_u64 v[234:235], s[20:21], 0, v[148:149]
	s_add_i32 m0, s43, 0x2000
	s_nop 0
	global_load_lds_dwordx4 v[234:235], off
	v_lshl_add_u64 v[234:235], s[56:57], 0, v[146:147]
	s_mov_b32 m0, s65
	s_nop 0
	global_load_lds_dwordx4 v[234:235], off
	s_mov_b32 m0, s66
	s_nop 0
	global_load_lds_dwordx4 v[236:237], off
	s_waitcnt vmcnt(8) lgkmcnt(0)
	v_mfma_f32_16x16x32_bf16 v[62:65], v[130:133], v[198:201], v[62:65]
	v_mfma_f32_16x16x32_bf16 v[58:61], v[138:141], v[198:201], v[58:61]
	v_mfma_f32_16x16x32_bf16 v[46:49], v[130:133], v[206:209], v[46:49]
	v_mfma_f32_16x16x32_bf16 v[42:45], v[138:141], v[206:209], v[42:45]
	s_barrier
	s_setprio 1
	v_mfma_f32_16x16x32_bf16 v[30:33], v[130:133], v[214:217], v[30:33]
	v_mfma_f32_16x16x32_bf16 v[26:29], v[138:141], v[214:217], v[26:29]
	v_mfma_f32_16x16x32_bf16 v[14:17], v[130:133], v[222:225], v[14:17]
	v_mfma_f32_16x16x32_bf16 v[10:13], v[138:141], v[222:225], v[10:13]
	v_mfma_f32_16x16x32_bf16 v[62:65], v[134:137], v[202:205], v[62:65]
	v_mfma_f32_16x16x32_bf16 v[58:61], v[142:145], v[202:205], v[58:61]
	v_mfma_f32_16x16x32_bf16 v[46:49], v[134:137], v[210:213], v[46:49]
	v_mfma_f32_16x16x32_bf16 v[42:45], v[142:145], v[210:213], v[42:45]
	v_mfma_f32_16x16x32_bf16 v[30:33], v[134:137], v[218:221], v[30:33]
	v_mfma_f32_16x16x32_bf16 v[26:29], v[142:145], v[218:221], v[26:29]
	v_mfma_f32_16x16x32_bf16 v[14:17], v[134:137], v[226:229], v[14:17]
	v_mfma_f32_16x16x32_bf16 v[10:13], v[142:145], v[226:229], v[10:13]
	v_mfma_f32_16x16x32_bf16 v[54:57], v[164:167], v[198:201], v[54:57]
	v_mfma_f32_16x16x32_bf16 v[50:53], v[172:175], v[198:201], v[50:53]
	v_mfma_f32_16x16x32_bf16 v[38:41], v[164:167], v[206:209], v[38:41]
	v_mfma_f32_16x16x32_bf16 v[34:37], v[172:175], v[206:209], v[34:37]
	v_mfma_f32_16x16x32_bf16 v[22:25], v[164:167], v[214:217], v[22:25]
	v_mfma_f32_16x16x32_bf16 v[18:21], v[172:175], v[214:217], v[18:21]
	v_mfma_f32_16x16x32_bf16 v[6:9], v[164:167], v[222:225], v[6:9]
	v_mfma_f32_16x16x32_bf16 v[2:5], v[172:175], v[222:225], v[2:5]
	v_mfma_f32_16x16x32_bf16 v[54:57], v[168:171], v[202:205], v[54:57]
	v_mfma_f32_16x16x32_bf16 v[50:53], v[194:197], v[202:205], v[50:53]
	v_mfma_f32_16x16x32_bf16 v[38:41], v[168:171], v[210:213], v[38:41]
	v_mfma_f32_16x16x32_bf16 v[34:37], v[194:197], v[210:213], v[34:37]
	v_mfma_f32_16x16x32_bf16 v[22:25], v[168:171], v[218:221], v[22:25]
	v_mfma_f32_16x16x32_bf16 v[18:21], v[194:197], v[218:221], v[18:21]
	v_mfma_f32_16x16x32_bf16 v[6:9], v[168:171], v[226:229], v[6:9]
	v_mfma_f32_16x16x32_bf16 v[2:5], v[194:197], v[226:229], v[2:5]
	s_setprio 0
	s_barrier
	s_add_i32 s43, 0, 0x18000
	s_add_i32 s45, 0, 0x1c000
	v_add_u32_e32 v142, s43, v187
	v_add_u32_e32 v193, s45, v187
	ds_read_b128 v[130:133], v142
	ds_read_b128 v[134:137], v142 offset:1024
	ds_read_b128 v[138:141], v142 offset:2048
	ds_read_b128 v[142:145], v142 offset:3072
	ds_read_b128 v[164:167], v193
	ds_read_b128 v[168:171], v193 offset:1024
	ds_read_b128 v[172:175], v193 offset:2048
	ds_read_b128 v[194:197], v193 offset:3072
	s_add_u32 s20, s56, 0x80000
	s_addc_u32 s21, s57, 0
	s_mov_b32 m0, s67
	v_lshl_add_u64 v[238:239], s[20:21], 0, v[146:147]
	ds_read_b128 v[198:201], v191 offset:32768
	ds_read_b128 v[202:205], v191 offset:33792
	ds_read_b128 v[206:209], v191 offset:34816
	ds_read_b128 v[210:213], v191 offset:35840
	ds_read_b128 v[214:217], v191 offset:36864
	ds_read_b128 v[218:221], v191 offset:37888
	ds_read_b128 v[222:225], v191 offset:38912
	ds_read_b128 v[226:229], v191 offset:39936
	global_load_lds_dwordx4 v[238:239], off
	v_lshl_add_u64 v[238:239], s[20:21], 0, v[148:149]
	s_mov_b32 m0, s68
	s_nop 0
	global_load_lds_dwordx4 v[238:239], off
	s_waitcnt vmcnt(8) lgkmcnt(0)
	v_mfma_f32_16x16x32_bf16 v[126:129], v[130:133], v[198:201], v[126:129]
	v_mfma_f32_16x16x32_bf16 v[122:125], v[138:141], v[198:201], v[122:125]
	v_mfma_f32_16x16x32_bf16 v[110:113], v[130:133], v[206:209], v[110:113]
	v_mfma_f32_16x16x32_bf16 v[106:109], v[138:141], v[206:209], v[106:109]
	s_barrier
	s_setprio 1
	v_mfma_f32_16x16x32_bf16 v[94:97], v[130:133], v[214:217], v[94:97]
	v_mfma_f32_16x16x32_bf16 v[90:93], v[138:141], v[214:217], v[90:93]
	v_mfma_f32_16x16x32_bf16 v[78:81], v[130:133], v[222:225], v[78:81]
	v_mfma_f32_16x16x32_bf16 v[74:77], v[138:141], v[222:225], v[74:77]
	v_mfma_f32_16x16x32_bf16 v[126:129], v[134:137], v[202:205], v[126:129]
	v_mfma_f32_16x16x32_bf16 v[122:125], v[142:145], v[202:205], v[122:125]
	v_mfma_f32_16x16x32_bf16 v[110:113], v[134:137], v[210:213], v[110:113]
	v_mfma_f32_16x16x32_bf16 v[106:109], v[142:145], v[210:213], v[106:109]
	v_mfma_f32_16x16x32_bf16 v[94:97], v[134:137], v[218:221], v[94:97]
	v_mfma_f32_16x16x32_bf16 v[90:93], v[142:145], v[218:221], v[90:93]
	v_mfma_f32_16x16x32_bf16 v[78:81], v[134:137], v[226:229], v[78:81]
	v_mfma_f32_16x16x32_bf16 v[74:77], v[142:145], v[226:229], v[74:77]
	v_mfma_f32_16x16x32_bf16 v[118:121], v[164:167], v[198:201], v[118:121]
	v_mfma_f32_16x16x32_bf16 v[114:117], v[172:175], v[198:201], v[114:117]
	v_mfma_f32_16x16x32_bf16 v[102:105], v[164:167], v[206:209], v[102:105]
	v_mfma_f32_16x16x32_bf16 v[98:101], v[172:175], v[206:209], v[98:101]
	v_mfma_f32_16x16x32_bf16 v[86:89], v[164:167], v[214:217], v[86:89]
	v_mfma_f32_16x16x32_bf16 v[82:85], v[172:175], v[214:217], v[82:85]
	v_mfma_f32_16x16x32_bf16 v[70:73], v[164:167], v[222:225], v[70:73]
	v_mfma_f32_16x16x32_bf16 v[66:69], v[172:175], v[222:225], v[66:69]
	v_mfma_f32_16x16x32_bf16 v[118:121], v[168:171], v[202:205], v[118:121]
	v_mfma_f32_16x16x32_bf16 v[114:117], v[194:197], v[202:205], v[114:117]
	v_mfma_f32_16x16x32_bf16 v[102:105], v[168:171], v[210:213], v[102:105]
	v_mfma_f32_16x16x32_bf16 v[98:101], v[194:197], v[210:213], v[98:101]
	v_mfma_f32_16x16x32_bf16 v[86:89], v[168:171], v[218:221], v[86:89]
	v_mfma_f32_16x16x32_bf16 v[82:85], v[194:197], v[218:221], v[82:85]
	v_mfma_f32_16x16x32_bf16 v[70:73], v[168:171], v[226:229], v[70:73]
	v_mfma_f32_16x16x32_bf16 v[66:69], v[194:197], v[226:229], v[66:69]
	s_setprio 0
	s_barrier
	s_add_i32 s20, s43, s64
	v_lshl_add_u64 v[230:231], v[230:231], 0, s[26:27]
	s_mov_b32 m0, s20
	ds_read_b128 v[198:201], v191 offset:49152
	ds_read_b128 v[202:205], v191 offset:50176
	ds_read_b128 v[206:209], v191 offset:51200
	ds_read_b128 v[210:213], v191 offset:52224
	ds_read_b128 v[214:217], v191 offset:53248
	ds_read_b128 v[218:221], v191 offset:54272
	ds_read_b128 v[222:225], v191 offset:55296
	ds_read_b128 v[226:229], v191 offset:56320
	global_load_lds_dwordx4 v[230:231], off
	s_add_i32 m0, s20, 0x2000
	s_add_u32 s20, s54, 0x80080
	v_lshl_add_u64 v[230:231], v[232:233], 0, s[26:27]
	s_addc_u32 s21, s55, 0
	s_add_i32 s43, s45, s64
	global_load_lds_dwordx4 v[230:231], off
	v_lshl_add_u64 v[230:231], s[20:21], 0, v[146:147]
	s_mov_b32 m0, s43
	s_nop 0
	global_load_lds_dwordx4 v[230:231], off
	v_lshl_add_u64 v[230:231], s[20:21], 0, v[148:149]
	s_add_i32 m0, s43, 0x2000
	s_nop 0
	global_load_lds_dwordx4 v[230:231], off
	v_lshl_add_u64 v[230:231], v[234:235], 0, s[26:27]
	s_mov_b32 m0, s73
	s_nop 0
	global_load_lds_dwordx4 v[230:231], off
	v_lshl_add_u64 v[230:231], v[236:237], 0, s[26:27]
	s_mov_b32 m0, s74
	s_nop 0
	global_load_lds_dwordx4 v[230:231], off
	s_waitcnt vmcnt(8) lgkmcnt(0)
	v_mfma_f32_16x16x32_bf16 v[62:65], v[130:133], v[198:201], v[62:65]
	v_mfma_f32_16x16x32_bf16 v[58:61], v[138:141], v[198:201], v[58:61]
	v_mfma_f32_16x16x32_bf16 v[46:49], v[130:133], v[206:209], v[46:49]
	v_mfma_f32_16x16x32_bf16 v[42:45], v[138:141], v[206:209], v[42:45]
	s_barrier
	s_setprio 1
	v_mfma_f32_16x16x32_bf16 v[30:33], v[130:133], v[214:217], v[30:33]
	v_mfma_f32_16x16x32_bf16 v[26:29], v[138:141], v[214:217], v[26:29]
	v_mfma_f32_16x16x32_bf16 v[14:17], v[130:133], v[222:225], v[14:17]
	v_mfma_f32_16x16x32_bf16 v[10:13], v[138:141], v[222:225], v[10:13]
	v_mfma_f32_16x16x32_bf16 v[62:65], v[134:137], v[202:205], v[62:65]
	v_mfma_f32_16x16x32_bf16 v[58:61], v[142:145], v[202:205], v[58:61]
	v_mfma_f32_16x16x32_bf16 v[46:49], v[134:137], v[210:213], v[46:49]
	v_mfma_f32_16x16x32_bf16 v[42:45], v[142:145], v[210:213], v[42:45]
	v_mfma_f32_16x16x32_bf16 v[30:33], v[134:137], v[218:221], v[30:33]
	v_mfma_f32_16x16x32_bf16 v[26:29], v[142:145], v[218:221], v[26:29]
	v_mfma_f32_16x16x32_bf16 v[14:17], v[134:137], v[226:229], v[14:17]
	v_mfma_f32_16x16x32_bf16 v[10:13], v[142:145], v[226:229], v[10:13]
	v_mfma_f32_16x16x32_bf16 v[54:57], v[164:167], v[198:201], v[54:57]
	v_mfma_f32_16x16x32_bf16 v[50:53], v[172:175], v[198:201], v[50:53]
	v_mfma_f32_16x16x32_bf16 v[38:41], v[164:167], v[206:209], v[38:41]
	v_mfma_f32_16x16x32_bf16 v[34:37], v[172:175], v[206:209], v[34:37]
	v_mfma_f32_16x16x32_bf16 v[22:25], v[164:167], v[214:217], v[22:25]
	v_mfma_f32_16x16x32_bf16 v[18:21], v[172:175], v[214:217], v[18:21]
	v_mfma_f32_16x16x32_bf16 v[6:9], v[164:167], v[222:225], v[6:9]
	v_mfma_f32_16x16x32_bf16 v[2:5], v[172:175], v[222:225], v[2:5]
	v_mfma_f32_16x16x32_bf16 v[54:57], v[168:171], v[202:205], v[54:57]
	v_mfma_f32_16x16x32_bf16 v[50:53], v[194:197], v[202:205], v[50:53]
	v_mfma_f32_16x16x32_bf16 v[38:41], v[168:171], v[210:213], v[38:41]
	v_mfma_f32_16x16x32_bf16 v[34:37], v[194:197], v[210:213], v[34:37]
	v_mfma_f32_16x16x32_bf16 v[22:25], v[168:171], v[218:221], v[22:25]
	v_mfma_f32_16x16x32_bf16 v[18:21], v[194:197], v[218:221], v[18:21]
	v_mfma_f32_16x16x32_bf16 v[6:9], v[168:171], v[226:229], v[6:9]
	v_mfma_f32_16x16x32_bf16 v[2:5], v[194:197], v[226:229], v[2:5]
	s_setprio 0
	s_barrier
	s_add_i32 s19, s19, 2
	s_add_u32 s52, s52, 0x100
	s_addc_u32 s53, s53, 0
	s_add_u32 s17, s17, 0x100
	s_addc_u32 s18, s18, 0
	s_cmp_gt_u32 s19, 29
	s_cbranch_scc0 .LBB0_1213
	s_and_b64 vcc, exec, s[28:29]
	s_cbranch_vccnz .LBB0_1218
	v_lshl_add_u32 v164, s50, 8, v186
	s_cmp_gt_i32 s10, 1
	s_mov_b64 s[50:51], -1
	s_cbranch_scc1 .LBB0_1219

.LBB0_1264:
	ds_read_b128 v[142:145], v163
	ds_read_b128 v[146:149], v163 offset:1024
	ds_read_b128 v[150:153], v163 offset:2048
	ds_read_b128 v[154:157], v163 offset:3072
	ds_read_b128 v[170:173], v166
	ds_read_b128 v[174:177], v166 offset:1024
	ds_read_b128 v[178:181], v166 offset:2048
	ds_read_b128 v[182:185], v166 offset:3072
	s_add_u32 s44, s42, 0xfffe0080
	s_addc_u32 s45, s43, -1
	s_cmp_eq_u32 s29, 4
	s_cselect_b32 s47, s3, s45
	s_cselect_b32 s46, s16, s44
	s_cselect_b32 s45, s17, s27
	s_cselect_b32 s44, s18, s19
	v_lshl_add_u64 v[218:219], s[42:43], 0, v[138:139]
	s_add_i32 m0, s39, 0xc000
	ds_read_b128 v[186:189], v167
	ds_read_b128 v[190:193], v167 offset:1024
	ds_read_b128 v[194:197], v167 offset:2048
	ds_read_b128 v[198:201], v167 offset:3072
	ds_read_b128 v[202:205], v167 offset:4096
	ds_read_b128 v[206:209], v167 offset:5120
	ds_read_b128 v[210:213], v167 offset:6144
	ds_read_b128 v[214:217], v167 offset:7168
	global_load_lds_dwordx4 v[218:219], off
	v_lshl_add_u64 v[218:219], s[42:43], 0, v[140:141]
	s_add_i32 m0, s39, 0xe000
	s_nop 0
	global_load_lds_dwordx4 v[218:219], off
	s_waitcnt vmcnt(8) lgkmcnt(0)
	v_mfma_f32_16x16x32_bf16 v[126:129], v[142:145], v[186:189], v[126:129]
	v_mfma_f32_16x16x32_bf16 v[122:125], v[150:153], v[186:189], v[122:125]
	v_mfma_f32_16x16x32_bf16 v[118:121], v[142:145], v[194:197], v[118:121]
	v_mfma_f32_16x16x32_bf16 v[110:113], v[150:153], v[194:197], v[110:113]
	s_barrier
	s_setprio 1
	v_mfma_f32_16x16x32_bf16 v[102:105], v[142:145], v[202:205], v[102:105]
	v_mfma_f32_16x16x32_bf16 v[94:97], v[150:153], v[202:205], v[94:97]
	v_mfma_f32_16x16x32_bf16 v[86:89], v[142:145], v[210:213], v[86:89]
	v_mfma_f32_16x16x32_bf16 v[78:81], v[150:153], v[210:213], v[78:81]
	v_mfma_f32_16x16x32_bf16 v[126:129], v[146:149], v[190:193], v[126:129]
	v_mfma_f32_16x16x32_bf16 v[122:125], v[154:157], v[190:193], v[122:125]
	v_mfma_f32_16x16x32_bf16 v[118:121], v[146:149], v[198:201], v[118:121]
	v_mfma_f32_16x16x32_bf16 v[110:113], v[154:157], v[198:201], v[110:113]
	v_mfma_f32_16x16x32_bf16 v[102:105], v[146:149], v[206:209], v[102:105]
	v_mfma_f32_16x16x32_bf16 v[94:97], v[154:157], v[206:209], v[94:97]
	v_mfma_f32_16x16x32_bf16 v[86:89], v[146:149], v[214:217], v[86:89]
	v_mfma_f32_16x16x32_bf16 v[78:81], v[154:157], v[214:217], v[78:81]
	v_mfma_f32_16x16x32_bf16 v[114:117], v[170:173], v[186:189], v[114:117]
	v_mfma_f32_16x16x32_bf16 v[106:109], v[178:181], v[186:189], v[106:109]
	v_mfma_f32_16x16x32_bf16 v[98:101], v[170:173], v[194:197], v[98:101]
	v_mfma_f32_16x16x32_bf16 v[90:93], v[178:181], v[194:197], v[90:93]
	v_mfma_f32_16x16x32_bf16 v[82:85], v[170:173], v[202:205], v[82:85]
	v_mfma_f32_16x16x32_bf16 v[74:77], v[178:181], v[202:205], v[74:77]
	v_mfma_f32_16x16x32_bf16 v[70:73], v[170:173], v[210:213], v[70:73]
	v_mfma_f32_16x16x32_bf16 v[66:69], v[178:181], v[210:213], v[66:69]
	v_mfma_f32_16x16x32_bf16 v[114:117], v[174:177], v[190:193], v[114:117]
	v_mfma_f32_16x16x32_bf16 v[106:109], v[182:185], v[190:193], v[106:109]
	v_mfma_f32_16x16x32_bf16 v[98:101], v[174:177], v[198:201], v[98:101]
	v_mfma_f32_16x16x32_bf16 v[90:93], v[182:185], v[198:201], v[90:93]
	v_mfma_f32_16x16x32_bf16 v[82:85], v[174:177], v[206:209], v[82:85]
	v_mfma_f32_16x16x32_bf16 v[74:77], v[182:185], v[206:209], v[74:77]
	v_mfma_f32_16x16x32_bf16 v[70:73], v[174:177], v[214:217], v[70:73]
	v_mfma_f32_16x16x32_bf16 v[66:69], v[182:185], v[214:217], v[66:69]
	s_setprio 0
	s_barrier
	s_add_i32 s62, s60, s54
	v_lshl_add_u64 v[218:219], s[44:45], 0, v[132:133]
	s_mov_b32 m0, s62
	ds_read_b128 v[186:189], v167 offset:16384
	ds_read_b128 v[190:193], v167 offset:17408
	ds_read_b128 v[194:197], v167 offset:18432
	ds_read_b128 v[198:201], v167 offset:19456
	ds_read_b128 v[202:205], v167 offset:20480
	ds_read_b128 v[206:209], v167 offset:21504
	ds_read_b128 v[210:213], v167 offset:22528
	ds_read_b128 v[214:217], v167 offset:23552
	global_load_lds_dwordx4 v[218:219], off
	s_add_i32 m0, s62, 0x2000
	s_add_u32 s62, s44, 0x20000
	v_lshl_add_u64 v[220:221], s[44:45], 0, v[136:137]
	s_addc_u32 s63, s45, 0
	s_add_i32 s64, s61, s54
	global_load_lds_dwordx4 v[220:221], off
	v_lshl_add_u64 v[222:223], s[62:63], 0, v[132:133]
	s_mov_b32 m0, s64
	v_lshl_add_u64 v[224:225], s[46:47], 0, v[134:135]
	global_load_lds_dwordx4 v[222:223], off
	v_lshl_add_u64 v[222:223], s[62:63], 0, v[136:137]
	s_add_i32 m0, s64, 0x2000
	s_nop 0
	global_load_lds_dwordx4 v[222:223], off
	v_lshl_add_u64 v[222:223], s[46:47], 0, v[130:131]
	s_mov_b32 m0, s39
	s_nop 0
	global_load_lds_dwordx4 v[222:223], off
	s_mov_b32 m0, s41
	s_nop 0
	global_load_lds_dwordx4 v[224:225], off
	s_waitcnt vmcnt(8) lgkmcnt(0)
	v_mfma_f32_16x16x32_bf16 v[62:65], v[142:145], v[186:189], v[62:65]
	v_mfma_f32_16x16x32_bf16 v[58:61], v[150:153], v[186:189], v[58:61]
	v_mfma_f32_16x16x32_bf16 v[54:57], v[142:145], v[194:197], v[54:57]
	v_mfma_f32_16x16x32_bf16 v[46:49], v[150:153], v[194:197], v[46:49]
	s_barrier
	s_setprio 1
	v_mfma_f32_16x16x32_bf16 v[38:41], v[142:145], v[202:205], v[38:41]
	v_mfma_f32_16x16x32_bf16 v[30:33], v[150:153], v[202:205], v[30:33]
	v_mfma_f32_16x16x32_bf16 v[22:25], v[142:145], v[210:213], v[22:25]
	v_mfma_f32_16x16x32_bf16 v[14:17], v[150:153], v[210:213], v[14:17]
	v_mfma_f32_16x16x32_bf16 v[62:65], v[146:149], v[190:193], v[62:65]
	v_mfma_f32_16x16x32_bf16 v[58:61], v[154:157], v[190:193], v[58:61]
	v_mfma_f32_16x16x32_bf16 v[54:57], v[146:149], v[198:201], v[54:57]
	v_mfma_f32_16x16x32_bf16 v[46:49], v[154:157], v[198:201], v[46:49]
	v_mfma_f32_16x16x32_bf16 v[38:41], v[146:149], v[206:209], v[38:41]
	v_mfma_f32_16x16x32_bf16 v[30:33], v[154:157], v[206:209], v[30:33]
	v_mfma_f32_16x16x32_bf16 v[22:25], v[146:149], v[214:217], v[22:25]
	v_mfma_f32_16x16x32_bf16 v[14:17], v[154:157], v[214:217], v[14:17]
	v_mfma_f32_16x16x32_bf16 v[50:53], v[170:173], v[186:189], v[50:53]
	v_mfma_f32_16x16x32_bf16 v[42:45], v[178:181], v[186:189], v[42:45]
	v_mfma_f32_16x16x32_bf16 v[34:37], v[170:173], v[194:197], v[34:37]
	v_mfma_f32_16x16x32_bf16 v[26:29], v[178:181], v[194:197], v[26:29]
	v_mfma_f32_16x16x32_bf16 v[18:21], v[170:173], v[202:205], v[18:21]
	v_mfma_f32_16x16x32_bf16 v[10:13], v[178:181], v[202:205], v[10:13]
	v_mfma_f32_16x16x32_bf16 v[6:9], v[170:173], v[210:213], v[6:9]
	v_mfma_f32_16x16x32_bf16 v[2:5], v[178:181], v[210:213], v[2:5]
	v_mfma_f32_16x16x32_bf16 v[50:53], v[174:177], v[190:193], v[50:53]
	v_mfma_f32_16x16x32_bf16 v[42:45], v[182:185], v[190:193], v[42:45]
	v_mfma_f32_16x16x32_bf16 v[34:37], v[174:177], v[198:201], v[34:37]
	v_mfma_f32_16x16x32_bf16 v[26:29], v[182:185], v[198:201], v[26:29]
	v_mfma_f32_16x16x32_bf16 v[18:21], v[174:177], v[206:209], v[18:21]
	v_mfma_f32_16x16x32_bf16 v[10:13], v[182:185], v[206:209], v[10:13]
	v_mfma_f32_16x16x32_bf16 v[6:9], v[174:177], v[214:217], v[6:9]
	v_mfma_f32_16x16x32_bf16 v[2:5], v[182:185], v[214:217], v[2:5]
	s_setprio 0
	s_barrier
	s_add_i32 s62, 0, 0x18000
	s_add_i32 s63, 0, 0x1c000
	v_add_u32_e32 v154, s62, v161
	v_add_u32_e32 v158, s63, v161
	ds_read_b128 v[142:145], v154
	ds_read_b128 v[146:149], v154 offset:1024
	ds_read_b128 v[150:153], v154 offset:2048
	ds_read_b128 v[154:157], v154 offset:3072
	ds_read_b128 v[170:173], v158
	ds_read_b128 v[174:177], v158 offset:1024
	ds_read_b128 v[178:181], v158 offset:2048
	ds_read_b128 v[182:185], v158 offset:3072
	s_add_u32 s46, s46, 0x20000
	s_addc_u32 s47, s47, 0
	s_mov_b32 m0, s55
	v_lshl_add_u64 v[226:227], s[46:47], 0, v[130:131]
	ds_read_b128 v[186:189], v167 offset:32768
	ds_read_b128 v[190:193], v167 offset:33792
	ds_read_b128 v[194:197], v167 offset:34816
	ds_read_b128 v[198:201], v167 offset:35840
	ds_read_b128 v[202:205], v167 offset:36864
	ds_read_b128 v[206:209], v167 offset:37888
	ds_read_b128 v[210:213], v167 offset:38912
	ds_read_b128 v[214:217], v167 offset:39936
	global_load_lds_dwordx4 v[226:227], off
	v_lshl_add_u64 v[226:227], s[46:47], 0, v[134:135]
	s_mov_b32 m0, s56
	s_nop 0
	global_load_lds_dwordx4 v[226:227], off
	s_waitcnt vmcnt(8) lgkmcnt(0)
	v_mfma_f32_16x16x32_bf16 v[126:129], v[142:145], v[186:189], v[126:129]
	v_mfma_f32_16x16x32_bf16 v[122:125], v[150:153], v[186:189], v[122:125]
	v_mfma_f32_16x16x32_bf16 v[118:121], v[142:145], v[194:197], v[118:121]
	v_mfma_f32_16x16x32_bf16 v[110:113], v[150:153], v[194:197], v[110:113]
	s_barrier
	s_setprio 1
	v_mfma_f32_16x16x32_bf16 v[102:105], v[142:145], v[202:205], v[102:105]
	v_mfma_f32_16x16x32_bf16 v[94:97], v[150:153], v[202:205], v[94:97]
	v_mfma_f32_16x16x32_bf16 v[86:89], v[142:145], v[210:213], v[86:89]
	v_mfma_f32_16x16x32_bf16 v[78:81], v[150:153], v[210:213], v[78:81]
	v_mfma_f32_16x16x32_bf16 v[126:129], v[146:149], v[190:193], v[126:129]
	v_mfma_f32_16x16x32_bf16 v[122:125], v[154:157], v[190:193], v[122:125]
	v_mfma_f32_16x16x32_bf16 v[118:121], v[146:149], v[198:201], v[118:121]
	v_mfma_f32_16x16x32_bf16 v[110:113], v[154:157], v[198:201], v[110:113]
	v_mfma_f32_16x16x32_bf16 v[102:105], v[146:149], v[206:209], v[102:105]
	v_mfma_f32_16x16x32_bf16 v[94:97], v[154:157], v[206:209], v[94:97]
	v_mfma_f32_16x16x32_bf16 v[86:89], v[146:149], v[214:217], v[86:89]
	v_mfma_f32_16x16x32_bf16 v[78:81], v[154:157], v[214:217], v[78:81]
	v_mfma_f32_16x16x32_bf16 v[114:117], v[170:173], v[186:189], v[114:117]
	v_mfma_f32_16x16x32_bf16 v[106:109], v[178:181], v[186:189], v[106:109]
	v_mfma_f32_16x16x32_bf16 v[98:101], v[170:173], v[194:197], v[98:101]
	v_mfma_f32_16x16x32_bf16 v[90:93], v[178:181], v[194:197], v[90:93]
	v_mfma_f32_16x16x32_bf16 v[82:85], v[170:173], v[202:205], v[82:85]
	v_mfma_f32_16x16x32_bf16 v[74:77], v[178:181], v[202:205], v[74:77]
	v_mfma_f32_16x16x32_bf16 v[70:73], v[170:173], v[210:213], v[70:73]
	v_mfma_f32_16x16x32_bf16 v[66:69], v[178:181], v[210:213], v[66:69]
	v_mfma_f32_16x16x32_bf16 v[114:117], v[174:177], v[190:193], v[114:117]
	v_mfma_f32_16x16x32_bf16 v[106:109], v[182:185], v[190:193], v[106:109]
	v_mfma_f32_16x16x32_bf16 v[98:101], v[174:177], v[198:201], v[98:101]
	v_mfma_f32_16x16x32_bf16 v[90:93], v[182:185], v[198:201], v[90:93]
	v_mfma_f32_16x16x32_bf16 v[82:85], v[174:177], v[206:209], v[82:85]
	v_mfma_f32_16x16x32_bf16 v[74:77], v[182:185], v[206:209], v[74:77]
	v_mfma_f32_16x16x32_bf16 v[70:73], v[174:177], v[214:217], v[70:73]
	v_mfma_f32_16x16x32_bf16 v[66:69], v[182:185], v[214:217], v[66:69]
	s_setprio 0
	s_barrier
	s_add_i32 s46, s62, s54
	v_lshl_add_u64 v[218:219], v[218:219], 0, s[22:23]
	s_mov_b32 m0, s46
	ds_read_b128 v[186:189], v167 offset:49152
	ds_read_b128 v[190:193], v167 offset:50176
	ds_read_b128 v[194:197], v167 offset:51200
	ds_read_b128 v[198:201], v167 offset:52224
	ds_read_b128 v[202:205], v167 offset:53248
	ds_read_b128 v[206:209], v167 offset:54272
	ds_read_b128 v[210:213], v167 offset:55296
	ds_read_b128 v[214:217], v167 offset:56320
	global_load_lds_dwordx4 v[218:219], off
	s_add_i32 m0, s46, 0x2000
	s_add_u32 s44, s44, 0x20080
	v_lshl_add_u64 v[218:219], v[220:221], 0, s[22:23]
	s_addc_u32 s45, s45, 0
	s_add_i32 s46, s63, s54
	global_load_lds_dwordx4 v[218:219], off
	v_lshl_add_u64 v[218:219], s[44:45], 0, v[132:133]
	s_mov_b32 m0, s46
	s_nop 0
	global_load_lds_dwordx4 v[218:219], off
	v_lshl_add_u64 v[218:219], s[44:45], 0, v[136:137]
	s_add_i32 m0, s46, 0x2000
	s_nop 0
	global_load_lds_dwordx4 v[218:219], off
	v_lshl_add_u64 v[218:219], v[222:223], 0, s[22:23]
	s_mov_b32 m0, s14
	s_nop 0
	global_load_lds_dwordx4 v[218:219], off
	v_lshl_add_u64 v[218:219], v[224:225], 0, s[22:23]
	s_mov_b32 m0, s15
	s_nop 0
	global_load_lds_dwordx4 v[218:219], off
	s_waitcnt vmcnt(8) lgkmcnt(0)
	v_mfma_f32_16x16x32_bf16 v[62:65], v[142:145], v[186:189], v[62:65]
	v_mfma_f32_16x16x32_bf16 v[58:61], v[150:153], v[186:189], v[58:61]
	v_mfma_f32_16x16x32_bf16 v[54:57], v[142:145], v[194:197], v[54:57]
	v_mfma_f32_16x16x32_bf16 v[46:49], v[150:153], v[194:197], v[46:49]
	s_barrier
	s_setprio 1
	v_mfma_f32_16x16x32_bf16 v[38:41], v[142:145], v[202:205], v[38:41]
	v_mfma_f32_16x16x32_bf16 v[30:33], v[150:153], v[202:205], v[30:33]
	v_mfma_f32_16x16x32_bf16 v[22:25], v[142:145], v[210:213], v[22:25]
	v_mfma_f32_16x16x32_bf16 v[14:17], v[150:153], v[210:213], v[14:17]
	v_mfma_f32_16x16x32_bf16 v[62:65], v[146:149], v[190:193], v[62:65]
	v_mfma_f32_16x16x32_bf16 v[58:61], v[154:157], v[190:193], v[58:61]
	v_mfma_f32_16x16x32_bf16 v[54:57], v[146:149], v[198:201], v[54:57]
	v_mfma_f32_16x16x32_bf16 v[46:49], v[154:157], v[198:201], v[46:49]
	v_mfma_f32_16x16x32_bf16 v[38:41], v[146:149], v[206:209], v[38:41]
	v_mfma_f32_16x16x32_bf16 v[30:33], v[154:157], v[206:209], v[30:33]
	v_mfma_f32_16x16x32_bf16 v[22:25], v[146:149], v[214:217], v[22:25]
	v_mfma_f32_16x16x32_bf16 v[14:17], v[154:157], v[214:217], v[14:17]
	v_mfma_f32_16x16x32_bf16 v[50:53], v[170:173], v[186:189], v[50:53]
	v_mfma_f32_16x16x32_bf16 v[42:45], v[178:181], v[186:189], v[42:45]
	v_mfma_f32_16x16x32_bf16 v[34:37], v[170:173], v[194:197], v[34:37]
	v_mfma_f32_16x16x32_bf16 v[26:29], v[178:181], v[194:197], v[26:29]
	v_mfma_f32_16x16x32_bf16 v[18:21], v[170:173], v[202:205], v[18:21]
	v_mfma_f32_16x16x32_bf16 v[10:13], v[178:181], v[202:205], v[10:13]
	v_mfma_f32_16x16x32_bf16 v[6:9], v[170:173], v[210:213], v[6:9]
	v_mfma_f32_16x16x32_bf16 v[2:5], v[178:181], v[210:213], v[2:5]
	v_mfma_f32_16x16x32_bf16 v[50:53], v[174:177], v[190:193], v[50:53]
	v_mfma_f32_16x16x32_bf16 v[42:45], v[182:185], v[190:193], v[42:45]
	v_mfma_f32_16x16x32_bf16 v[34:37], v[174:177], v[198:201], v[34:37]
	v_mfma_f32_16x16x32_bf16 v[26:29], v[182:185], v[198:201], v[26:29]
	v_mfma_f32_16x16x32_bf16 v[18:21], v[174:177], v[206:209], v[18:21]
	v_mfma_f32_16x16x32_bf16 v[10:13], v[182:185], v[206:209], v[10:13]
	v_mfma_f32_16x16x32_bf16 v[6:9], v[174:177], v[214:217], v[6:9]
	v_mfma_f32_16x16x32_bf16 v[2:5], v[182:185], v[214:217], v[2:5]
	s_setprio 0
	s_barrier
	s_add_i32 s29, s29, 2
	s_add_u32 s42, s42, 0x100
	s_addc_u32 s43, s43, 0
	s_add_u32 s19, s19, 0x100
	s_addc_u32 s27, s27, 0
	s_cmp_gt_u32 s29, 5
	s_cbranch_scc0 .LBB0_1264
	s_and_b64 vcc, exec, s[24:25]
	s_cbranch_vccz .LBB0_1267
	s_barrier

.LBB0_1336:
	ds_read_b128 v[154:157], v175
	ds_read_b128 v[158:161], v175 offset:1024
	ds_read_b128 v[164:167], v175 offset:2048
	ds_read_b128 v[168:171], v175 offset:3072
	ds_read_b128 v[180:183], v176
	ds_read_b128 v[184:187], v176 offset:1024
	ds_read_b128 v[188:191], v176 offset:2048
	ds_read_b128 v[192:195], v176 offset:3072
	s_add_u32 s20, s36, 0xfffe0080
	s_addc_u32 s21, s37, -1
	s_cmp_eq_u32 s19, 4
	s_cselect_b32 s41, s3, s21
	s_cselect_b32 s40, s14, s20
	s_cselect_b32 s39, s15, s18
	s_cselect_b32 s38, s16, s17
	v_lshl_add_u64 v[228:229], s[36:37], 0, v[144:145]
	s_add_i32 m0, s49, 0xc000
	ds_read_b128 v[196:199], v177
	ds_read_b128 v[200:203], v177 offset:1024
	ds_read_b128 v[204:207], v177 offset:2048
	ds_read_b128 v[208:211], v177 offset:3072
	ds_read_b128 v[212:215], v177 offset:4096
	ds_read_b128 v[216:219], v177 offset:5120
	ds_read_b128 v[220:223], v177 offset:6144
	ds_read_b128 v[224:227], v177 offset:7168
	global_load_lds_dwordx4 v[228:229], off
	v_lshl_add_u64 v[228:229], s[36:37], 0, v[146:147]
	s_add_i32 m0, s49, 0xe000
	s_nop 0
	global_load_lds_dwordx4 v[228:229], off
	s_waitcnt vmcnt(8) lgkmcnt(0)
	v_mfma_f32_16x16x32_bf16 v[126:129], v[154:157], v[196:199], v[126:129]
	v_mfma_f32_16x16x32_bf16 v[122:125], v[164:167], v[196:199], v[122:125]
	v_mfma_f32_16x16x32_bf16 v[118:121], v[154:157], v[204:207], v[118:121]
	v_mfma_f32_16x16x32_bf16 v[110:113], v[164:167], v[204:207], v[110:113]
	s_barrier
	s_setprio 1
	v_mfma_f32_16x16x32_bf16 v[102:105], v[154:157], v[212:215], v[102:105]
	v_mfma_f32_16x16x32_bf16 v[94:97], v[164:167], v[212:215], v[94:97]
	v_mfma_f32_16x16x32_bf16 v[86:89], v[154:157], v[220:223], v[86:89]
	v_mfma_f32_16x16x32_bf16 v[78:81], v[164:167], v[220:223], v[78:81]
	v_mfma_f32_16x16x32_bf16 v[126:129], v[158:161], v[200:203], v[126:129]
	v_mfma_f32_16x16x32_bf16 v[122:125], v[168:171], v[200:203], v[122:125]
	v_mfma_f32_16x16x32_bf16 v[118:121], v[158:161], v[208:211], v[118:121]
	v_mfma_f32_16x16x32_bf16 v[110:113], v[168:171], v[208:211], v[110:113]
	v_mfma_f32_16x16x32_bf16 v[102:105], v[158:161], v[216:219], v[102:105]
	v_mfma_f32_16x16x32_bf16 v[94:97], v[168:171], v[216:219], v[94:97]
	v_mfma_f32_16x16x32_bf16 v[86:89], v[158:161], v[224:227], v[86:89]
	v_mfma_f32_16x16x32_bf16 v[78:81], v[168:171], v[224:227], v[78:81]
	v_mfma_f32_16x16x32_bf16 v[114:117], v[180:183], v[196:199], v[114:117]
	v_mfma_f32_16x16x32_bf16 v[106:109], v[188:191], v[196:199], v[106:109]
	v_mfma_f32_16x16x32_bf16 v[98:101], v[180:183], v[204:207], v[98:101]
	v_mfma_f32_16x16x32_bf16 v[90:93], v[188:191], v[204:207], v[90:93]
	v_mfma_f32_16x16x32_bf16 v[82:85], v[180:183], v[212:215], v[82:85]
	v_mfma_f32_16x16x32_bf16 v[74:77], v[188:191], v[212:215], v[74:77]
	v_mfma_f32_16x16x32_bf16 v[70:73], v[180:183], v[220:223], v[70:73]
	v_mfma_f32_16x16x32_bf16 v[66:69], v[188:191], v[220:223], v[66:69]
	v_mfma_f32_16x16x32_bf16 v[114:117], v[184:187], v[200:203], v[114:117]
	v_mfma_f32_16x16x32_bf16 v[106:109], v[192:195], v[200:203], v[106:109]
	v_mfma_f32_16x16x32_bf16 v[98:101], v[184:187], v[208:211], v[98:101]
	v_mfma_f32_16x16x32_bf16 v[90:93], v[192:195], v[208:211], v[90:93]
	v_mfma_f32_16x16x32_bf16 v[82:85], v[184:187], v[216:219], v[82:85]
	v_mfma_f32_16x16x32_bf16 v[74:77], v[192:195], v[216:219], v[74:77]
	v_mfma_f32_16x16x32_bf16 v[70:73], v[184:187], v[224:227], v[70:73]
	v_mfma_f32_16x16x32_bf16 v[66:69], v[192:195], v[224:227], v[66:69]
	s_setprio 0
	s_barrier
	s_add_i32 s20, s57, s46
	v_lshl_add_u64 v[228:229], s[38:39], 0, v[134:135]
	s_mov_b32 m0, s20
	ds_read_b128 v[196:199], v177 offset:16384
	ds_read_b128 v[200:203], v177 offset:17408
	ds_read_b128 v[204:207], v177 offset:18432
	ds_read_b128 v[208:211], v177 offset:19456
	ds_read_b128 v[212:215], v177 offset:20480
	ds_read_b128 v[216:219], v177 offset:21504
	ds_read_b128 v[220:223], v177 offset:22528
	ds_read_b128 v[224:227], v177 offset:23552
	global_load_lds_dwordx4 v[228:229], off
	s_add_i32 m0, s20, 0x2000
	s_add_u32 s20, s38, 0x20000
	v_lshl_add_u64 v[230:231], s[38:39], 0, v[130:131]
	s_addc_u32 s21, s39, 0
	s_add_i32 s27, s60, s46
	global_load_lds_dwordx4 v[230:231], off
	v_lshl_add_u64 v[232:233], s[20:21], 0, v[134:135]
	s_mov_b32 m0, s27
	v_lshl_add_u64 v[234:235], s[40:41], 0, v[132:133]
	global_load_lds_dwordx4 v[232:233], off
	v_lshl_add_u64 v[232:233], s[20:21], 0, v[130:131]
	s_add_i32 m0, s27, 0x2000
	s_nop 0
	global_load_lds_dwordx4 v[232:233], off
	v_lshl_add_u64 v[232:233], s[40:41], 0, v[136:137]
	s_mov_b32 m0, s49
	s_nop 0
	global_load_lds_dwordx4 v[232:233], off
	s_mov_b32 m0, s50
	s_nop 0
	global_load_lds_dwordx4 v[234:235], off
	s_waitcnt vmcnt(8) lgkmcnt(0)
	v_mfma_f32_16x16x32_bf16 v[62:65], v[154:157], v[196:199], v[62:65]
	v_mfma_f32_16x16x32_bf16 v[58:61], v[164:167], v[196:199], v[58:61]
	v_mfma_f32_16x16x32_bf16 v[54:57], v[154:157], v[204:207], v[54:57]
	v_mfma_f32_16x16x32_bf16 v[46:49], v[164:167], v[204:207], v[46:49]
	s_barrier
	s_setprio 1
	v_mfma_f32_16x16x32_bf16 v[38:41], v[154:157], v[212:215], v[38:41]
	v_mfma_f32_16x16x32_bf16 v[30:33], v[164:167], v[212:215], v[30:33]
	v_mfma_f32_16x16x32_bf16 v[22:25], v[154:157], v[220:223], v[22:25]
	v_mfma_f32_16x16x32_bf16 v[14:17], v[164:167], v[220:223], v[14:17]
	v_mfma_f32_16x16x32_bf16 v[62:65], v[158:161], v[200:203], v[62:65]
	v_mfma_f32_16x16x32_bf16 v[58:61], v[168:171], v[200:203], v[58:61]
	v_mfma_f32_16x16x32_bf16 v[54:57], v[158:161], v[208:211], v[54:57]
	v_mfma_f32_16x16x32_bf16 v[46:49], v[168:171], v[208:211], v[46:49]
	v_mfma_f32_16x16x32_bf16 v[38:41], v[158:161], v[216:219], v[38:41]
	v_mfma_f32_16x16x32_bf16 v[30:33], v[168:171], v[216:219], v[30:33]
	v_mfma_f32_16x16x32_bf16 v[22:25], v[158:161], v[224:227], v[22:25]
	v_mfma_f32_16x16x32_bf16 v[14:17], v[168:171], v[224:227], v[14:17]
	v_mfma_f32_16x16x32_bf16 v[50:53], v[180:183], v[196:199], v[50:53]
	v_mfma_f32_16x16x32_bf16 v[42:45], v[188:191], v[196:199], v[42:45]
	v_mfma_f32_16x16x32_bf16 v[34:37], v[180:183], v[204:207], v[34:37]
	v_mfma_f32_16x16x32_bf16 v[26:29], v[188:191], v[204:207], v[26:29]
	v_mfma_f32_16x16x32_bf16 v[18:21], v[180:183], v[212:215], v[18:21]
	v_mfma_f32_16x16x32_bf16 v[10:13], v[188:191], v[212:215], v[10:13]
	v_mfma_f32_16x16x32_bf16 v[6:9], v[180:183], v[220:223], v[6:9]
	v_mfma_f32_16x16x32_bf16 v[2:5], v[188:191], v[220:223], v[2:5]
	v_mfma_f32_16x16x32_bf16 v[50:53], v[184:187], v[200:203], v[50:53]
	v_mfma_f32_16x16x32_bf16 v[42:45], v[192:195], v[200:203], v[42:45]
	v_mfma_f32_16x16x32_bf16 v[34:37], v[184:187], v[208:211], v[34:37]
	v_mfma_f32_16x16x32_bf16 v[26:29], v[192:195], v[208:211], v[26:29]
	v_mfma_f32_16x16x32_bf16 v[18:21], v[184:187], v[216:219], v[18:21]
	v_mfma_f32_16x16x32_bf16 v[10:13], v[192:195], v[216:219], v[10:13]
	v_mfma_f32_16x16x32_bf16 v[6:9], v[184:187], v[224:227], v[6:9]
	v_mfma_f32_16x16x32_bf16 v[2:5], v[192:195], v[224:227], v[2:5]
	s_setprio 0
	s_barrier
	s_add_i32 s27, 0, 0x18000
	v_add_u32_e32 v153, s27, v173
	s_add_i32 s29, 0, 0x1c000
	ds_read_b128 v[154:157], v153
	ds_read_b128 v[158:161], v153 offset:1024
	ds_read_b128 v[164:167], v153 offset:2048
	ds_read_b128 v[168:171], v153 offset:3072
	v_add_u32_e32 v153, s29, v173
	ds_read_b128 v[180:183], v153
	ds_read_b128 v[184:187], v153 offset:1024
	ds_read_b128 v[188:191], v153 offset:2048
	ds_read_b128 v[192:195], v153 offset:3072
	s_add_u32 s20, s40, 0x20000
	s_addc_u32 s21, s41, 0
	s_mov_b32 m0, s51
	v_lshl_add_u64 v[236:237], s[20:21], 0, v[136:137]
	ds_read_b128 v[196:199], v177 offset:32768
	ds_read_b128 v[200:203], v177 offset:33792
	ds_read_b128 v[204:207], v177 offset:34816
	ds_read_b128 v[208:211], v177 offset:35840
	ds_read_b128 v[212:215], v177 offset:36864
	ds_read_b128 v[216:219], v177 offset:37888
	ds_read_b128 v[220:223], v177 offset:38912
	ds_read_b128 v[224:227], v177 offset:39936
	global_load_lds_dwordx4 v[236:237], off
	v_lshl_add_u64 v[236:237], s[20:21], 0, v[132:133]
	s_mov_b32 m0, s52
	s_nop 0
	global_load_lds_dwordx4 v[236:237], off
	s_waitcnt vmcnt(8) lgkmcnt(0)
	v_mfma_f32_16x16x32_bf16 v[126:129], v[154:157], v[196:199], v[126:129]
	v_mfma_f32_16x16x32_bf16 v[122:125], v[164:167], v[196:199], v[122:125]
	v_mfma_f32_16x16x32_bf16 v[118:121], v[154:157], v[204:207], v[118:121]
	v_mfma_f32_16x16x32_bf16 v[110:113], v[164:167], v[204:207], v[110:113]
	s_barrier
	s_setprio 1
	v_mfma_f32_16x16x32_bf16 v[102:105], v[154:157], v[212:215], v[102:105]
	v_mfma_f32_16x16x32_bf16 v[94:97], v[164:167], v[212:215], v[94:97]
	v_mfma_f32_16x16x32_bf16 v[86:89], v[154:157], v[220:223], v[86:89]
	v_mfma_f32_16x16x32_bf16 v[78:81], v[164:167], v[220:223], v[78:81]
	v_mfma_f32_16x16x32_bf16 v[126:129], v[158:161], v[200:203], v[126:129]
	v_mfma_f32_16x16x32_bf16 v[122:125], v[168:171], v[200:203], v[122:125]
	v_mfma_f32_16x16x32_bf16 v[118:121], v[158:161], v[208:211], v[118:121]
	v_mfma_f32_16x16x32_bf16 v[110:113], v[168:171], v[208:211], v[110:113]
	v_mfma_f32_16x16x32_bf16 v[102:105], v[158:161], v[216:219], v[102:105]
	v_mfma_f32_16x16x32_bf16 v[94:97], v[168:171], v[216:219], v[94:97]
	v_mfma_f32_16x16x32_bf16 v[86:89], v[158:161], v[224:227], v[86:89]
	v_mfma_f32_16x16x32_bf16 v[78:81], v[168:171], v[224:227], v[78:81]
	v_mfma_f32_16x16x32_bf16 v[114:117], v[180:183], v[196:199], v[114:117]
	v_mfma_f32_16x16x32_bf16 v[106:109], v[188:191], v[196:199], v[106:109]
	v_mfma_f32_16x16x32_bf16 v[98:101], v[180:183], v[204:207], v[98:101]
	v_mfma_f32_16x16x32_bf16 v[90:93], v[188:191], v[204:207], v[90:93]
	v_mfma_f32_16x16x32_bf16 v[82:85], v[180:183], v[212:215], v[82:85]
	v_mfma_f32_16x16x32_bf16 v[74:77], v[188:191], v[212:215], v[74:77]
	v_mfma_f32_16x16x32_bf16 v[70:73], v[180:183], v[220:223], v[70:73]
	v_mfma_f32_16x16x32_bf16 v[66:69], v[188:191], v[220:223], v[66:69]
	v_mfma_f32_16x16x32_bf16 v[114:117], v[184:187], v[200:203], v[114:117]
	v_mfma_f32_16x16x32_bf16 v[106:109], v[192:195], v[200:203], v[106:109]
	v_mfma_f32_16x16x32_bf16 v[98:101], v[184:187], v[208:211], v[98:101]
	v_mfma_f32_16x16x32_bf16 v[90:93], v[192:195], v[208:211], v[90:93]
	v_mfma_f32_16x16x32_bf16 v[82:85], v[184:187], v[216:219], v[82:85]
	v_mfma_f32_16x16x32_bf16 v[74:77], v[192:195], v[216:219], v[74:77]
	v_mfma_f32_16x16x32_bf16 v[70:73], v[184:187], v[224:227], v[70:73]
	v_mfma_f32_16x16x32_bf16 v[66:69], v[192:195], v[224:227], v[66:69]
	s_setprio 0
	s_barrier
	s_add_i32 s20, s27, s46
	v_lshl_add_u64 v[228:229], v[228:229], 0, s[22:23]
	s_mov_b32 m0, s20
	ds_read_b128 v[196:199], v177 offset:49152
	ds_read_b128 v[200:203], v177 offset:50176
	ds_read_b128 v[204:207], v177 offset:51200
	ds_read_b128 v[208:211], v177 offset:52224
	ds_read_b128 v[212:215], v177 offset:53248
	ds_read_b128 v[216:219], v177 offset:54272
	ds_read_b128 v[220:223], v177 offset:55296
	ds_read_b128 v[224:227], v177 offset:56320
	global_load_lds_dwordx4 v[228:229], off
	s_add_i32 m0, s20, 0x2000
	s_add_u32 s20, s38, 0x20080
	v_lshl_add_u64 v[228:229], v[230:231], 0, s[22:23]
	s_addc_u32 s21, s39, 0
	s_add_i32 s27, s29, s46
	global_load_lds_dwordx4 v[228:229], off
	v_lshl_add_u64 v[228:229], s[20:21], 0, v[134:135]
	s_mov_b32 m0, s27
	s_nop 0
	global_load_lds_dwordx4 v[228:229], off
	v_lshl_add_u64 v[228:229], s[20:21], 0, v[130:131]
	s_add_i32 m0, s27, 0x2000
	s_nop 0
	global_load_lds_dwordx4 v[228:229], off
	v_lshl_add_u64 v[228:229], v[232:233], 0, s[22:23]
	s_mov_b32 m0, s53
	s_nop 0
	global_load_lds_dwordx4 v[228:229], off
	v_lshl_add_u64 v[228:229], v[234:235], 0, s[22:23]
	s_mov_b32 m0, s54
	s_nop 0
	global_load_lds_dwordx4 v[228:229], off
	s_waitcnt vmcnt(8) lgkmcnt(0)
	v_mfma_f32_16x16x32_bf16 v[62:65], v[154:157], v[196:199], v[62:65]
	v_mfma_f32_16x16x32_bf16 v[58:61], v[164:167], v[196:199], v[58:61]
	v_mfma_f32_16x16x32_bf16 v[54:57], v[154:157], v[204:207], v[54:57]
	v_mfma_f32_16x16x32_bf16 v[46:49], v[164:167], v[204:207], v[46:49]
	s_barrier
	s_setprio 1
	v_mfma_f32_16x16x32_bf16 v[38:41], v[154:157], v[212:215], v[38:41]
	v_mfma_f32_16x16x32_bf16 v[30:33], v[164:167], v[212:215], v[30:33]
	v_mfma_f32_16x16x32_bf16 v[22:25], v[154:157], v[220:223], v[22:25]
	v_mfma_f32_16x16x32_bf16 v[14:17], v[164:167], v[220:223], v[14:17]
	v_mfma_f32_16x16x32_bf16 v[62:65], v[158:161], v[200:203], v[62:65]
	v_mfma_f32_16x16x32_bf16 v[58:61], v[168:171], v[200:203], v[58:61]
	v_mfma_f32_16x16x32_bf16 v[54:57], v[158:161], v[208:211], v[54:57]
	v_mfma_f32_16x16x32_bf16 v[46:49], v[168:171], v[208:211], v[46:49]
	v_mfma_f32_16x16x32_bf16 v[38:41], v[158:161], v[216:219], v[38:41]
	v_mfma_f32_16x16x32_bf16 v[30:33], v[168:171], v[216:219], v[30:33]
	v_mfma_f32_16x16x32_bf16 v[22:25], v[158:161], v[224:227], v[22:25]
	v_mfma_f32_16x16x32_bf16 v[14:17], v[168:171], v[224:227], v[14:17]
	v_mfma_f32_16x16x32_bf16 v[50:53], v[180:183], v[196:199], v[50:53]
	v_mfma_f32_16x16x32_bf16 v[42:45], v[188:191], v[196:199], v[42:45]
	v_mfma_f32_16x16x32_bf16 v[34:37], v[180:183], v[204:207], v[34:37]
	v_mfma_f32_16x16x32_bf16 v[26:29], v[188:191], v[204:207], v[26:29]
	v_mfma_f32_16x16x32_bf16 v[18:21], v[180:183], v[212:215], v[18:21]
	v_mfma_f32_16x16x32_bf16 v[10:13], v[188:191], v[212:215], v[10:13]
	v_mfma_f32_16x16x32_bf16 v[6:9], v[180:183], v[220:223], v[6:9]
	v_mfma_f32_16x16x32_bf16 v[2:5], v[188:191], v[220:223], v[2:5]
	v_mfma_f32_16x16x32_bf16 v[50:53], v[184:187], v[200:203], v[50:53]
	v_mfma_f32_16x16x32_bf16 v[42:45], v[192:195], v[200:203], v[42:45]
	v_mfma_f32_16x16x32_bf16 v[34:37], v[184:187], v[208:211], v[34:37]
	v_mfma_f32_16x16x32_bf16 v[26:29], v[192:195], v[208:211], v[26:29]
	v_mfma_f32_16x16x32_bf16 v[18:21], v[184:187], v[216:219], v[18:21]
	v_mfma_f32_16x16x32_bf16 v[10:13], v[192:195], v[216:219], v[10:13]
	v_mfma_f32_16x16x32_bf16 v[6:9], v[184:187], v[224:227], v[6:9]
	v_mfma_f32_16x16x32_bf16 v[2:5], v[192:195], v[224:227], v[2:5]
	s_setprio 0
	s_barrier
	s_add_i32 s19, s19, 2
	s_add_u32 s36, s36, 0x100
	s_addc_u32 s37, s37, 0
	s_add_u32 s17, s17, 0x100
	s_addc_u32 s18, s18, 0
	s_cmp_gt_u32 s19, 5
	s_cbranch_scc0 .LBB0_1336
	s_and_b64 vcc, exec, s[24:25]
	s_cbranch_vccz .LBB0_1339
	s_barrier

.LBB0_1497:
	ds_read_b128 v[134:137], v214
	ds_read_b128 v[138:141], v214 offset:1024
	ds_read_b128 v[142:145], v214 offset:2048
	ds_read_b128 v[178:181], v214 offset:3072
	ds_read_b128 v[182:185], v215
	ds_read_b128 v[186:189], v215 offset:1024
	ds_read_b128 v[190:193], v215 offset:2048
	ds_read_b128 v[194:197], v215 offset:3072
	s_add_u32 s40, s38, 0x100
	s_addc_u32 s41, s39, 0
	s_add_u32 s0, s15, s38
	s_addc_u32 s1, s16, s39
	s_cmp_eq_u32 s17, 28
	s_cselect_b32 s45, s3, s1
	s_cselect_b32 s1, 0, s40
	s_cselect_b32 s44, s14, s0
	s_cselect_b32 s0, 0, s41
	s_add_u32 s42, s10, s1
	s_addc_u32 s43, s11, s0
	s_mov_b32 m0, s64
	v_lshl_add_u64 v[244:245], v[130:131], 0, s[38:39]
	ds_read_b128 v[198:201], v216
	ds_read_b128 v[202:205], v216 offset:1024
	ds_read_b128 v[206:209], v216 offset:2048
	ds_read_b128 v[224:227], v216 offset:3072
	ds_read_b128 v[228:231], v216 offset:4096
	ds_read_b128 v[232:235], v216 offset:5120
	ds_read_b128 v[236:239], v216 offset:6144
	ds_read_b128 v[240:243], v216 offset:7168
	global_load_lds_dwordx4 v[244:245], off
	v_lshl_add_u64 v[244:245], v[132:133], 0, s[38:39]
	s_mov_b32 m0, s65
	s_nop 0
	global_load_lds_dwordx4 v[244:245], off
	s_waitcnt vmcnt(8) lgkmcnt(0)
	v_mfma_f32_16x16x32_bf16 v[82:85], v[134:137], v[198:201], v[82:85]
	v_mfma_f32_16x16x32_bf16 v[78:81], v[142:145], v[198:201], v[78:81]
	v_mfma_f32_16x16x32_bf16 v[110:113], v[134:137], v[206:209], v[110:113]
	v_mfma_f32_16x16x32_bf16 v[106:109], v[142:145], v[206:209], v[106:109]
	s_barrier
	s_setprio 1
	v_mfma_f32_16x16x32_bf16 v[118:121], v[134:137], v[228:231], v[118:121]
	v_mfma_f32_16x16x32_bf16 v[114:117], v[142:145], v[228:231], v[114:117]
	v_mfma_f32_16x16x32_bf16 v[126:129], v[134:137], v[236:239], v[126:129]
	v_mfma_f32_16x16x32_bf16 v[122:125], v[142:145], v[236:239], v[122:125]
	v_mfma_f32_16x16x32_bf16 v[82:85], v[138:141], v[202:205], v[82:85]
	v_mfma_f32_16x16x32_bf16 v[78:81], v[178:181], v[202:205], v[78:81]
	v_mfma_f32_16x16x32_bf16 v[110:113], v[138:141], v[224:227], v[110:113]
	v_mfma_f32_16x16x32_bf16 v[106:109], v[178:181], v[224:227], v[106:109]
	v_mfma_f32_16x16x32_bf16 v[118:121], v[138:141], v[232:235], v[118:121]
	v_mfma_f32_16x16x32_bf16 v[114:117], v[178:181], v[232:235], v[114:117]
	v_mfma_f32_16x16x32_bf16 v[126:129], v[138:141], v[240:243], v[126:129]
	v_mfma_f32_16x16x32_bf16 v[122:125], v[178:181], v[240:243], v[122:125]
	v_mfma_f32_16x16x32_bf16 v[22:25], v[182:185], v[198:201], v[22:25]
	v_mfma_f32_16x16x32_bf16 v[26:29], v[190:193], v[198:201], v[26:29]
	v_mfma_f32_16x16x32_bf16 v[42:45], v[182:185], v[206:209], v[42:45]
	v_mfma_f32_16x16x32_bf16 v[46:49], v[190:193], v[206:209], v[46:49]
	v_mfma_f32_16x16x32_bf16 v[62:65], v[182:185], v[228:231], v[62:65]
	v_mfma_f32_16x16x32_bf16 v[70:73], v[190:193], v[228:231], v[70:73]
	v_mfma_f32_16x16x32_bf16 v[90:93], v[182:185], v[236:239], v[90:93]
	v_mfma_f32_16x16x32_bf16 v[94:97], v[190:193], v[236:239], v[94:97]
	v_mfma_f32_16x16x32_bf16 v[22:25], v[186:189], v[202:205], v[22:25]
	v_mfma_f32_16x16x32_bf16 v[26:29], v[194:197], v[202:205], v[26:29]
	v_mfma_f32_16x16x32_bf16 v[42:45], v[186:189], v[224:227], v[42:45]
	v_mfma_f32_16x16x32_bf16 v[46:49], v[194:197], v[224:227], v[46:49]
	v_mfma_f32_16x16x32_bf16 v[62:65], v[186:189], v[232:235], v[62:65]
	v_mfma_f32_16x16x32_bf16 v[70:73], v[194:197], v[232:235], v[70:73]
	v_mfma_f32_16x16x32_bf16 v[90:93], v[186:189], v[240:243], v[90:93]
	v_mfma_f32_16x16x32_bf16 v[94:97], v[194:197], v[240:243], v[94:97]
	s_setprio 0
	s_barrier
	s_mov_b32 m0, s66
	v_lshl_add_u64 v[244:245], s[42:43], 0, v[150:151]
	s_add_u32 s18, s42, 0x80000
	ds_read_b128 v[198:201], v216 offset:16384
	ds_read_b128 v[202:205], v216 offset:17408
	ds_read_b128 v[206:209], v216 offset:18432
	ds_read_b128 v[224:227], v216 offset:19456
	ds_read_b128 v[228:231], v216 offset:20480
	ds_read_b128 v[232:235], v216 offset:21504
	ds_read_b128 v[236:239], v216 offset:22528
	ds_read_b128 v[240:243], v216 offset:23552
	global_load_lds_dwordx4 v[244:245], off
	v_lshl_add_u64 v[246:247], s[42:43], 0, v[146:147]
	s_mov_b32 m0, s67
	s_addc_u32 s19, s43, 0
	global_load_lds_dwordx4 v[246:247], off
	v_lshl_add_u64 v[248:249], s[18:19], 0, v[150:151]
	s_mov_b32 m0, s68
	v_lshl_add_u64 v[250:251], s[44:45], 0, v[148:149]
	global_load_lds_dwordx4 v[248:249], off
	v_lshl_add_u64 v[248:249], s[18:19], 0, v[146:147]
	s_mov_b32 m0, s69
	s_nop 0
	global_load_lds_dwordx4 v[248:249], off
	v_lshl_add_u64 v[248:249], s[44:45], 0, v[152:153]
	s_mov_b32 m0, s9
	s_nop 0
	global_load_lds_dwordx4 v[248:249], off
	s_mov_b32 m0, s55
	s_nop 0
	global_load_lds_dwordx4 v[250:251], off
	s_waitcnt vmcnt(8) lgkmcnt(0)
	v_mfma_f32_16x16x32_bf16 v[102:105], v[134:137], v[198:201], v[102:105]
	v_mfma_f32_16x16x32_bf16 v[98:101], v[142:145], v[198:201], v[98:101]
	v_mfma_f32_16x16x32_bf16 v[66:69], v[134:137], v[206:209], v[66:69]
	v_mfma_f32_16x16x32_bf16 v[58:61], v[142:145], v[206:209], v[58:61]
	s_barrier
	s_setprio 1
	v_mfma_f32_16x16x32_bf16 v[38:41], v[134:137], v[228:231], v[38:41]
	v_mfma_f32_16x16x32_bf16 v[34:37], v[142:145], v[228:231], v[34:37]
	v_mfma_f32_16x16x32_bf16 v[14:17], v[134:137], v[236:239], v[14:17]
	v_mfma_f32_16x16x32_bf16 v[10:13], v[142:145], v[236:239], v[10:13]
	v_mfma_f32_16x16x32_bf16 v[102:105], v[138:141], v[202:205], v[102:105]
	v_mfma_f32_16x16x32_bf16 v[98:101], v[178:181], v[202:205], v[98:101]
	v_mfma_f32_16x16x32_bf16 v[66:69], v[138:141], v[224:227], v[66:69]
	v_mfma_f32_16x16x32_bf16 v[58:61], v[178:181], v[224:227], v[58:61]
	v_mfma_f32_16x16x32_bf16 v[38:41], v[138:141], v[232:235], v[38:41]
	v_mfma_f32_16x16x32_bf16 v[34:37], v[178:181], v[232:235], v[34:37]
	v_mfma_f32_16x16x32_bf16 v[14:17], v[138:141], v[240:243], v[14:17]
	v_mfma_f32_16x16x32_bf16 v[10:13], v[178:181], v[240:243], v[10:13]
	v_mfma_f32_16x16x32_bf16 v[86:89], v[182:185], v[198:201], v[86:89]
	v_mfma_f32_16x16x32_bf16 v[74:77], v[190:193], v[198:201], v[74:77]
	v_mfma_f32_16x16x32_bf16 v[54:57], v[182:185], v[206:209], v[54:57]
	v_mfma_f32_16x16x32_bf16 v[50:53], v[190:193], v[206:209], v[50:53]
	v_mfma_f32_16x16x32_bf16 v[30:33], v[182:185], v[228:231], v[30:33]
	v_mfma_f32_16x16x32_bf16 v[18:21], v[190:193], v[228:231], v[18:21]
	v_mfma_f32_16x16x32_bf16 v[6:9], v[182:185], v[236:239], v[6:9]
	v_mfma_f32_16x16x32_bf16 v[2:5], v[190:193], v[236:239], v[2:5]
	v_mfma_f32_16x16x32_bf16 v[86:89], v[186:189], v[202:205], v[86:89]
	v_mfma_f32_16x16x32_bf16 v[74:77], v[194:197], v[202:205], v[74:77]
	v_mfma_f32_16x16x32_bf16 v[54:57], v[186:189], v[224:227], v[54:57]
	v_mfma_f32_16x16x32_bf16 v[50:53], v[194:197], v[224:227], v[50:53]
	v_mfma_f32_16x16x32_bf16 v[30:33], v[186:189], v[232:235], v[30:33]
	v_mfma_f32_16x16x32_bf16 v[18:21], v[194:197], v[232:235], v[18:21]
	v_mfma_f32_16x16x32_bf16 v[6:9], v[186:189], v[240:243], v[6:9]
	v_mfma_f32_16x16x32_bf16 v[2:5], v[194:197], v[240:243], v[2:5]
	s_setprio 0
	s_barrier
	s_add_i32 s0, 0, 0x1c000
	v_add_u32_e32 v194, s0, v212
	ds_read_b128 v[134:137], v220
	ds_read_b128 v[138:141], v220 offset:1024
	ds_read_b128 v[142:145], v220 offset:2048
	ds_read_b128 v[178:181], v220 offset:3072
	ds_read_b128 v[182:185], v194
	ds_read_b128 v[186:189], v194 offset:1024
	ds_read_b128 v[190:193], v194 offset:2048
	ds_read_b128 v[194:197], v194 offset:3072
	s_add_u32 s18, s44, 0x80000
	s_addc_u32 s19, s45, 0
	s_mov_b32 m0, s56
	v_lshl_add_u64 v[252:253], s[18:19], 0, v[152:153]
	ds_read_b128 v[198:201], v216 offset:32768
	ds_read_b128 v[202:205], v216 offset:33792
	ds_read_b128 v[206:209], v216 offset:34816
	ds_read_b128 v[224:227], v216 offset:35840
	ds_read_b128 v[228:231], v216 offset:36864
	ds_read_b128 v[232:235], v216 offset:37888
	ds_read_b128 v[236:239], v216 offset:38912
	ds_read_b128 v[240:243], v216 offset:39936
	global_load_lds_dwordx4 v[252:253], off
	v_lshl_add_u64 v[252:253], s[18:19], 0, v[148:149]
	s_mov_b32 m0, s57
	s_nop 0
	global_load_lds_dwordx4 v[252:253], off
	s_waitcnt vmcnt(8) lgkmcnt(0)
	v_mfma_f32_16x16x32_bf16 v[82:85], v[134:137], v[198:201], v[82:85]
	v_mfma_f32_16x16x32_bf16 v[78:81], v[142:145], v[198:201], v[78:81]
	v_mfma_f32_16x16x32_bf16 v[110:113], v[134:137], v[206:209], v[110:113]
	v_mfma_f32_16x16x32_bf16 v[106:109], v[142:145], v[206:209], v[106:109]
	s_barrier
	s_setprio 1
	v_mfma_f32_16x16x32_bf16 v[118:121], v[134:137], v[228:231], v[118:121]
	v_mfma_f32_16x16x32_bf16 v[114:117], v[142:145], v[228:231], v[114:117]
	v_mfma_f32_16x16x32_bf16 v[126:129], v[134:137], v[236:239], v[126:129]
	v_mfma_f32_16x16x32_bf16 v[122:125], v[142:145], v[236:239], v[122:125]
	v_mfma_f32_16x16x32_bf16 v[82:85], v[138:141], v[202:205], v[82:85]
	v_mfma_f32_16x16x32_bf16 v[78:81], v[178:181], v[202:205], v[78:81]
	v_mfma_f32_16x16x32_bf16 v[110:113], v[138:141], v[224:227], v[110:113]
	v_mfma_f32_16x16x32_bf16 v[106:109], v[178:181], v[224:227], v[106:109]
	v_mfma_f32_16x16x32_bf16 v[118:121], v[138:141], v[232:235], v[118:121]
	v_mfma_f32_16x16x32_bf16 v[114:117], v[178:181], v[232:235], v[114:117]
	v_mfma_f32_16x16x32_bf16 v[126:129], v[138:141], v[240:243], v[126:129]
	v_mfma_f32_16x16x32_bf16 v[122:125], v[178:181], v[240:243], v[122:125]
	v_mfma_f32_16x16x32_bf16 v[22:25], v[182:185], v[198:201], v[22:25]
	v_mfma_f32_16x16x32_bf16 v[26:29], v[190:193], v[198:201], v[26:29]
	v_mfma_f32_16x16x32_bf16 v[42:45], v[182:185], v[206:209], v[42:45]
	v_mfma_f32_16x16x32_bf16 v[46:49], v[190:193], v[206:209], v[46:49]
	v_mfma_f32_16x16x32_bf16 v[62:65], v[182:185], v[228:231], v[62:65]
	v_mfma_f32_16x16x32_bf16 v[70:73], v[190:193], v[228:231], v[70:73]
	v_mfma_f32_16x16x32_bf16 v[90:93], v[182:185], v[236:239], v[90:93]
	v_mfma_f32_16x16x32_bf16 v[94:97], v[190:193], v[236:239], v[94:97]
	v_mfma_f32_16x16x32_bf16 v[22:25], v[186:189], v[202:205], v[22:25]
	v_mfma_f32_16x16x32_bf16 v[26:29], v[194:197], v[202:205], v[26:29]
	v_mfma_f32_16x16x32_bf16 v[42:45], v[186:189], v[224:227], v[42:45]
	v_mfma_f32_16x16x32_bf16 v[46:49], v[194:197], v[224:227], v[46:49]
	v_mfma_f32_16x16x32_bf16 v[62:65], v[186:189], v[232:235], v[62:65]
	v_mfma_f32_16x16x32_bf16 v[70:73], v[194:197], v[232:235], v[70:73]
	v_mfma_f32_16x16x32_bf16 v[90:93], v[186:189], v[240:243], v[90:93]
	v_mfma_f32_16x16x32_bf16 v[94:97], v[194:197], v[240:243], v[94:97]
	s_setprio 0
	s_barrier
	s_add_i32 s1, s72, s54
	v_lshl_add_u64 v[244:245], v[244:245], 0, s[26:27]
	s_mov_b32 m0, s1
	ds_read_b128 v[198:201], v216 offset:49152
	ds_read_b128 v[202:205], v216 offset:50176
	ds_read_b128 v[206:209], v216 offset:51200
	ds_read_b128 v[224:227], v216 offset:52224
	ds_read_b128 v[228:231], v216 offset:53248
	ds_read_b128 v[232:235], v216 offset:54272
	ds_read_b128 v[236:239], v216 offset:55296
	ds_read_b128 v[240:243], v216 offset:56320
	global_load_lds_dwordx4 v[244:245], off
	s_add_i32 m0, s1, 0x2000
	s_add_u32 s18, s42, 0x80080
	v_lshl_add_u64 v[244:245], v[246:247], 0, s[26:27]
	s_addc_u32 s19, s43, 0
	s_add_i32 s0, s0, s54
	global_load_lds_dwordx4 v[244:245], off
	v_lshl_add_u64 v[244:245], s[18:19], 0, v[150:151]
	s_mov_b32 m0, s0
	s_nop 0
	global_load_lds_dwordx4 v[244:245], off
	v_lshl_add_u64 v[244:245], s[18:19], 0, v[146:147]
	s_add_i32 m0, s0, 0x2000
	s_nop 0
	global_load_lds_dwordx4 v[244:245], off
	v_lshl_add_u64 v[244:245], v[248:249], 0, s[26:27]
	s_mov_b32 m0, s61
	s_nop 0
	global_load_lds_dwordx4 v[244:245], off
	v_lshl_add_u64 v[244:245], v[250:251], 0, s[26:27]
	s_mov_b32 m0, s62
	s_nop 0
	global_load_lds_dwordx4 v[244:245], off
	s_waitcnt vmcnt(8) lgkmcnt(0)
	v_mfma_f32_16x16x32_bf16 v[102:105], v[134:137], v[198:201], v[102:105]
	v_mfma_f32_16x16x32_bf16 v[98:101], v[142:145], v[198:201], v[98:101]
	v_mfma_f32_16x16x32_bf16 v[66:69], v[134:137], v[206:209], v[66:69]
	v_mfma_f32_16x16x32_bf16 v[58:61], v[142:145], v[206:209], v[58:61]
	s_barrier
	s_setprio 1
	v_mfma_f32_16x16x32_bf16 v[38:41], v[134:137], v[228:231], v[38:41]
	v_mfma_f32_16x16x32_bf16 v[34:37], v[142:145], v[228:231], v[34:37]
	v_mfma_f32_16x16x32_bf16 v[14:17], v[134:137], v[236:239], v[14:17]
	v_mfma_f32_16x16x32_bf16 v[10:13], v[142:145], v[236:239], v[10:13]
	v_mfma_f32_16x16x32_bf16 v[102:105], v[138:141], v[202:205], v[102:105]
	v_mfma_f32_16x16x32_bf16 v[98:101], v[178:181], v[202:205], v[98:101]
	v_mfma_f32_16x16x32_bf16 v[66:69], v[138:141], v[224:227], v[66:69]
	v_mfma_f32_16x16x32_bf16 v[58:61], v[178:181], v[224:227], v[58:61]
	v_mfma_f32_16x16x32_bf16 v[38:41], v[138:141], v[232:235], v[38:41]
	v_mfma_f32_16x16x32_bf16 v[34:37], v[178:181], v[232:235], v[34:37]
	v_mfma_f32_16x16x32_bf16 v[14:17], v[138:141], v[240:243], v[14:17]
	v_mfma_f32_16x16x32_bf16 v[10:13], v[178:181], v[240:243], v[10:13]
	v_mfma_f32_16x16x32_bf16 v[86:89], v[182:185], v[198:201], v[86:89]
	v_mfma_f32_16x16x32_bf16 v[74:77], v[190:193], v[198:201], v[74:77]
	v_mfma_f32_16x16x32_bf16 v[54:57], v[182:185], v[206:209], v[54:57]
	v_mfma_f32_16x16x32_bf16 v[50:53], v[190:193], v[206:209], v[50:53]
	v_mfma_f32_16x16x32_bf16 v[30:33], v[182:185], v[228:231], v[30:33]
	v_mfma_f32_16x16x32_bf16 v[18:21], v[190:193], v[228:231], v[18:21]
	v_mfma_f32_16x16x32_bf16 v[6:9], v[182:185], v[236:239], v[6:9]
	v_mfma_f32_16x16x32_bf16 v[2:5], v[190:193], v[236:239], v[2:5]
	v_mfma_f32_16x16x32_bf16 v[86:89], v[186:189], v[202:205], v[86:89]
	v_mfma_f32_16x16x32_bf16 v[74:77], v[194:197], v[202:205], v[74:77]
	v_mfma_f32_16x16x32_bf16 v[54:57], v[186:189], v[224:227], v[54:57]
	v_mfma_f32_16x16x32_bf16 v[50:53], v[194:197], v[224:227], v[50:53]
	v_mfma_f32_16x16x32_bf16 v[30:33], v[186:189], v[232:235], v[30:33]
	v_mfma_f32_16x16x32_bf16 v[18:21], v[194:197], v[232:235], v[18:21]
	v_mfma_f32_16x16x32_bf16 v[6:9], v[186:189], v[240:243], v[6:9]
	v_mfma_f32_16x16x32_bf16 v[2:5], v[194:197], v[240:243], v[2:5]
	s_setprio 0
	s_barrier
	s_add_i32 s17, s17, 2
	s_cmp_gt_u32 s17, 29
	s_mov_b64 s[38:39], s[40:41]
	s_cbranch_scc0 .LBB0_1497
	s_and_b64 vcc, exec, s[28:29]
	s_cbranch_vccz .LBB0_1500
	s_barrier

.LBB0_1604:
	ds_read_b128 v[154:157], v151
	ds_read_b128 v[158:161], v151 offset:1024
	ds_read_b128 v[164:167], v151 offset:2048
	ds_read_b128 v[168:171], v151 offset:3072
	ds_read_b128 v[172:175], v152
	ds_read_b128 v[176:179], v152 offset:1024
	ds_read_b128 v[180:183], v152 offset:2048
	ds_read_b128 v[184:187], v152 offset:3072
	s_add_u32 s0, s34, 0xfff80080
	s_addc_u32 s1, s35, -1
	s_cmp_eq_u32 s53, 28
	s_cselect_b32 s39, s16, s1
	s_cselect_b32 s38, s17, s0
	s_cselect_b32 s37, s18, s25
	s_cselect_b32 s36, s19, s23
	v_lshl_add_u64 v[146:147], s[34:35], 0, v[138:139]
	s_add_i32 m0, s31, 0xc000
	ds_read_b128 v[188:191], v153
	ds_read_b128 v[192:195], v153 offset:1024
	ds_read_b128 v[196:199], v153 offset:2048
	ds_read_b128 v[200:203], v153 offset:3072
	ds_read_b128 v[204:207], v153 offset:4096
	ds_read_b128 v[208:211], v153 offset:5120
	ds_read_b128 v[212:215], v153 offset:6144
	ds_read_b128 v[216:219], v153 offset:7168
	global_load_lds_dwordx4 v[146:147], off
	v_lshl_add_u64 v[146:147], s[34:35], 0, v[140:141]
	s_add_i32 m0, s31, 0xe000
	s_nop 0
	global_load_lds_dwordx4 v[146:147], off
	s_waitcnt vmcnt(8) lgkmcnt(0)
	v_mfma_f32_16x16x32_bf16 v[126:129], v[154:157], v[188:191], v[126:129]
	v_mfma_f32_16x16x32_bf16 v[122:125], v[164:167], v[188:191], v[122:125]
	v_mfma_f32_16x16x32_bf16 v[110:113], v[154:157], v[196:199], v[110:113]
	v_mfma_f32_16x16x32_bf16 v[106:109], v[164:167], v[196:199], v[106:109]
	s_barrier
	s_setprio 1
	v_mfma_f32_16x16x32_bf16 v[94:97], v[154:157], v[204:207], v[94:97]
	v_mfma_f32_16x16x32_bf16 v[90:93], v[164:167], v[204:207], v[90:93]
	v_mfma_f32_16x16x32_bf16 v[78:81], v[154:157], v[212:215], v[78:81]
	v_mfma_f32_16x16x32_bf16 v[74:77], v[164:167], v[212:215], v[74:77]
	v_mfma_f32_16x16x32_bf16 v[126:129], v[158:161], v[192:195], v[126:129]
	v_mfma_f32_16x16x32_bf16 v[122:125], v[168:171], v[192:195], v[122:125]
	v_mfma_f32_16x16x32_bf16 v[110:113], v[158:161], v[200:203], v[110:113]
	v_mfma_f32_16x16x32_bf16 v[106:109], v[168:171], v[200:203], v[106:109]
	v_mfma_f32_16x16x32_bf16 v[94:97], v[158:161], v[208:211], v[94:97]
	v_mfma_f32_16x16x32_bf16 v[90:93], v[168:171], v[208:211], v[90:93]
	v_mfma_f32_16x16x32_bf16 v[78:81], v[158:161], v[216:219], v[78:81]
	v_mfma_f32_16x16x32_bf16 v[74:77], v[168:171], v[216:219], v[74:77]
	v_mfma_f32_16x16x32_bf16 v[118:121], v[172:175], v[188:191], v[118:121]
	v_mfma_f32_16x16x32_bf16 v[114:117], v[180:183], v[188:191], v[114:117]
	v_mfma_f32_16x16x32_bf16 v[102:105], v[172:175], v[196:199], v[102:105]
	v_mfma_f32_16x16x32_bf16 v[98:101], v[180:183], v[196:199], v[98:101]
	v_mfma_f32_16x16x32_bf16 v[86:89], v[172:175], v[204:207], v[86:89]
	v_mfma_f32_16x16x32_bf16 v[82:85], v[180:183], v[204:207], v[82:85]
	v_mfma_f32_16x16x32_bf16 v[70:73], v[172:175], v[212:215], v[70:73]
	v_mfma_f32_16x16x32_bf16 v[66:69], v[180:183], v[212:215], v[66:69]
	v_mfma_f32_16x16x32_bf16 v[118:121], v[176:179], v[192:195], v[118:121]
	v_mfma_f32_16x16x32_bf16 v[114:117], v[184:187], v[192:195], v[114:117]
	v_mfma_f32_16x16x32_bf16 v[102:105], v[176:179], v[200:203], v[102:105]
	v_mfma_f32_16x16x32_bf16 v[98:101], v[184:187], v[200:203], v[98:101]
	v_mfma_f32_16x16x32_bf16 v[86:89], v[176:179], v[208:211], v[86:89]
	v_mfma_f32_16x16x32_bf16 v[82:85], v[184:187], v[208:211], v[82:85]
	v_mfma_f32_16x16x32_bf16 v[70:73], v[176:179], v[216:219], v[70:73]
	v_mfma_f32_16x16x32_bf16 v[66:69], v[184:187], v[216:219], v[66:69]
	s_setprio 0
	s_barrier
	s_add_i32 s0, s15, s44
	v_lshl_add_u64 v[146:147], s[36:37], 0, v[134:135]
	s_mov_b32 m0, s0
	ds_read_b128 v[188:191], v153 offset:16384
	ds_read_b128 v[192:195], v153 offset:17408
	ds_read_b128 v[196:199], v153 offset:18432
	ds_read_b128 v[200:203], v153 offset:19456
	ds_read_b128 v[204:207], v153 offset:20480
	ds_read_b128 v[208:211], v153 offset:21504
	ds_read_b128 v[212:215], v153 offset:22528
	ds_read_b128 v[216:219], v153 offset:23552
	global_load_lds_dwordx4 v[146:147], off
	s_add_i32 m0, s0, 0x2000
	s_add_u32 s54, s36, 0x80000
	v_lshl_add_u64 v[220:221], s[36:37], 0, v[130:131]
	s_addc_u32 s55, s37, 0
	s_add_i32 s0, s51, s44
	global_load_lds_dwordx4 v[220:221], off
	v_lshl_add_u64 v[222:223], s[54:55], 0, v[134:135]
	s_mov_b32 m0, s0
	v_lshl_add_u64 v[224:225], s[38:39], 0, v[132:133]
	global_load_lds_dwordx4 v[222:223], off
	v_lshl_add_u64 v[222:223], s[54:55], 0, v[130:131]
	s_add_i32 m0, s0, 0x2000
	s_nop 0
	global_load_lds_dwordx4 v[222:223], off
	v_lshl_add_u64 v[222:223], s[38:39], 0, v[136:137]
	s_mov_b32 m0, s31
	s_nop 0
	global_load_lds_dwordx4 v[222:223], off
	s_mov_b32 m0, s47
	s_nop 0
	global_load_lds_dwordx4 v[224:225], off
	s_waitcnt vmcnt(8) lgkmcnt(0)
	v_mfma_f32_16x16x32_bf16 v[62:65], v[154:157], v[188:191], v[62:65]
	v_mfma_f32_16x16x32_bf16 v[58:61], v[164:167], v[188:191], v[58:61]
	v_mfma_f32_16x16x32_bf16 v[46:49], v[154:157], v[196:199], v[46:49]
	v_mfma_f32_16x16x32_bf16 v[42:45], v[164:167], v[196:199], v[42:45]
	s_barrier
	s_setprio 1
	v_mfma_f32_16x16x32_bf16 v[30:33], v[154:157], v[204:207], v[30:33]
	v_mfma_f32_16x16x32_bf16 v[26:29], v[164:167], v[204:207], v[26:29]
	v_mfma_f32_16x16x32_bf16 v[14:17], v[154:157], v[212:215], v[14:17]
	v_mfma_f32_16x16x32_bf16 v[10:13], v[164:167], v[212:215], v[10:13]
	v_mfma_f32_16x16x32_bf16 v[62:65], v[158:161], v[192:195], v[62:65]
	v_mfma_f32_16x16x32_bf16 v[58:61], v[168:171], v[192:195], v[58:61]
	v_mfma_f32_16x16x32_bf16 v[46:49], v[158:161], v[200:203], v[46:49]
	v_mfma_f32_16x16x32_bf16 v[42:45], v[168:171], v[200:203], v[42:45]
	v_mfma_f32_16x16x32_bf16 v[30:33], v[158:161], v[208:211], v[30:33]
	v_mfma_f32_16x16x32_bf16 v[26:29], v[168:171], v[208:211], v[26:29]
	v_mfma_f32_16x16x32_bf16 v[14:17], v[158:161], v[216:219], v[14:17]
	v_mfma_f32_16x16x32_bf16 v[10:13], v[168:171], v[216:219], v[10:13]
	v_mfma_f32_16x16x32_bf16 v[54:57], v[172:175], v[188:191], v[54:57]
	v_mfma_f32_16x16x32_bf16 v[50:53], v[180:183], v[188:191], v[50:53]
	v_mfma_f32_16x16x32_bf16 v[38:41], v[172:175], v[196:199], v[38:41]
	v_mfma_f32_16x16x32_bf16 v[34:37], v[180:183], v[196:199], v[34:37]
	v_mfma_f32_16x16x32_bf16 v[22:25], v[172:175], v[204:207], v[22:25]
	v_mfma_f32_16x16x32_bf16 v[18:21], v[180:183], v[204:207], v[18:21]
	v_mfma_f32_16x16x32_bf16 v[6:9], v[172:175], v[212:215], v[6:9]
	v_mfma_f32_16x16x32_bf16 v[2:5], v[180:183], v[212:215], v[2:5]
	v_mfma_f32_16x16x32_bf16 v[54:57], v[176:179], v[192:195], v[54:57]
	v_mfma_f32_16x16x32_bf16 v[50:53], v[184:187], v[192:195], v[50:53]
	v_mfma_f32_16x16x32_bf16 v[38:41], v[176:179], v[200:203], v[38:41]
	v_mfma_f32_16x16x32_bf16 v[34:37], v[184:187], v[200:203], v[34:37]
	v_mfma_f32_16x16x32_bf16 v[22:25], v[176:179], v[208:211], v[22:25]
	v_mfma_f32_16x16x32_bf16 v[18:21], v[184:187], v[208:211], v[18:21]
	v_mfma_f32_16x16x32_bf16 v[6:9], v[176:179], v[216:219], v[6:9]
	v_mfma_f32_16x16x32_bf16 v[2:5], v[184:187], v[216:219], v[2:5]
	s_setprio 0
	s_barrier
	s_add_i32 s0, 0, 0x18000
	v_add_u32_e32 v163, s0, v149
	s_add_i32 s1, 0, 0x1c000
	ds_read_b128 v[154:157], v163
	ds_read_b128 v[158:161], v163 offset:1024
	ds_read_b128 v[164:167], v163 offset:2048
	ds_read_b128 v[168:171], v163 offset:3072
	v_add_u32_e32 v163, s1, v149
	ds_read_b128 v[172:175], v163
	ds_read_b128 v[176:179], v163 offset:1024
	ds_read_b128 v[180:183], v163 offset:2048
	ds_read_b128 v[184:187], v163 offset:3072
	s_add_u32 s38, s38, 0x80000
	s_addc_u32 s39, s39, 0
	s_mov_b32 m0, s48
	v_lshl_add_u64 v[226:227], s[38:39], 0, v[136:137]
	ds_read_b128 v[188:191], v153 offset:32768
	ds_read_b128 v[192:195], v153 offset:33792
	ds_read_b128 v[196:199], v153 offset:34816
	ds_read_b128 v[200:203], v153 offset:35840
	ds_read_b128 v[204:207], v153 offset:36864
	ds_read_b128 v[208:211], v153 offset:37888
	ds_read_b128 v[212:215], v153 offset:38912
	ds_read_b128 v[216:219], v153 offset:39936
	global_load_lds_dwordx4 v[226:227], off
	v_lshl_add_u64 v[226:227], s[38:39], 0, v[132:133]
	s_mov_b32 m0, s49
	s_nop 0
	global_load_lds_dwordx4 v[226:227], off
	s_waitcnt vmcnt(8) lgkmcnt(0)
	v_mfma_f32_16x16x32_bf16 v[126:129], v[154:157], v[188:191], v[126:129]
	v_mfma_f32_16x16x32_bf16 v[122:125], v[164:167], v[188:191], v[122:125]
	v_mfma_f32_16x16x32_bf16 v[110:113], v[154:157], v[196:199], v[110:113]
	v_mfma_f32_16x16x32_bf16 v[106:109], v[164:167], v[196:199], v[106:109]
	s_barrier
	s_setprio 1
	v_mfma_f32_16x16x32_bf16 v[94:97], v[154:157], v[204:207], v[94:97]
	v_mfma_f32_16x16x32_bf16 v[90:93], v[164:167], v[204:207], v[90:93]
	v_mfma_f32_16x16x32_bf16 v[78:81], v[154:157], v[212:215], v[78:81]
	v_mfma_f32_16x16x32_bf16 v[74:77], v[164:167], v[212:215], v[74:77]
	v_mfma_f32_16x16x32_bf16 v[126:129], v[158:161], v[192:195], v[126:129]
	v_mfma_f32_16x16x32_bf16 v[122:125], v[168:171], v[192:195], v[122:125]
	v_mfma_f32_16x16x32_bf16 v[110:113], v[158:161], v[200:203], v[110:113]
	v_mfma_f32_16x16x32_bf16 v[106:109], v[168:171], v[200:203], v[106:109]
	v_mfma_f32_16x16x32_bf16 v[94:97], v[158:161], v[208:211], v[94:97]
	v_mfma_f32_16x16x32_bf16 v[90:93], v[168:171], v[208:211], v[90:93]
	v_mfma_f32_16x16x32_bf16 v[78:81], v[158:161], v[216:219], v[78:81]
	v_mfma_f32_16x16x32_bf16 v[74:77], v[168:171], v[216:219], v[74:77]
	v_mfma_f32_16x16x32_bf16 v[118:121], v[172:175], v[188:191], v[118:121]
	v_mfma_f32_16x16x32_bf16 v[114:117], v[180:183], v[188:191], v[114:117]
	v_mfma_f32_16x16x32_bf16 v[102:105], v[172:175], v[196:199], v[102:105]
	v_mfma_f32_16x16x32_bf16 v[98:101], v[180:183], v[196:199], v[98:101]
	v_mfma_f32_16x16x32_bf16 v[86:89], v[172:175], v[204:207], v[86:89]
	v_mfma_f32_16x16x32_bf16 v[82:85], v[180:183], v[204:207], v[82:85]
	v_mfma_f32_16x16x32_bf16 v[70:73], v[172:175], v[212:215], v[70:73]
	v_mfma_f32_16x16x32_bf16 v[66:69], v[180:183], v[212:215], v[66:69]
	v_mfma_f32_16x16x32_bf16 v[118:121], v[176:179], v[192:195], v[118:121]
	v_mfma_f32_16x16x32_bf16 v[114:117], v[184:187], v[192:195], v[114:117]
	v_mfma_f32_16x16x32_bf16 v[102:105], v[176:179], v[200:203], v[102:105]
	v_mfma_f32_16x16x32_bf16 v[98:101], v[184:187], v[200:203], v[98:101]
	v_mfma_f32_16x16x32_bf16 v[86:89], v[176:179], v[208:211], v[86:89]
	v_mfma_f32_16x16x32_bf16 v[82:85], v[184:187], v[208:211], v[82:85]
	v_mfma_f32_16x16x32_bf16 v[70:73], v[176:179], v[216:219], v[70:73]
	v_mfma_f32_16x16x32_bf16 v[66:69], v[184:187], v[216:219], v[66:69]
	s_setprio 0
	s_barrier
	s_add_i32 s0, s0, s44
	v_lshl_add_u64 v[146:147], v[146:147], 0, s[10:11]
	s_mov_b32 m0, s0
	ds_read_b128 v[188:191], v153 offset:49152
	ds_read_b128 v[192:195], v153 offset:50176
	ds_read_b128 v[196:199], v153 offset:51200
	ds_read_b128 v[200:203], v153 offset:52224
	ds_read_b128 v[204:207], v153 offset:53248
	ds_read_b128 v[208:211], v153 offset:54272
	ds_read_b128 v[212:215], v153 offset:55296
	ds_read_b128 v[216:219], v153 offset:56320
	global_load_lds_dwordx4 v[146:147], off
	s_add_i32 m0, s0, 0x2000
	s_add_u32 s36, s36, 0x80080
	v_lshl_add_u64 v[146:147], v[220:221], 0, s[10:11]
	s_addc_u32 s37, s37, 0
	s_add_i32 s0, s1, s44
	global_load_lds_dwordx4 v[146:147], off
	v_lshl_add_u64 v[146:147], s[36:37], 0, v[134:135]
	s_mov_b32 m0, s0
	s_nop 0
	global_load_lds_dwordx4 v[146:147], off
	v_lshl_add_u64 v[146:147], s[36:37], 0, v[130:131]
	s_add_i32 m0, s0, 0x2000
	s_nop 0
	global_load_lds_dwordx4 v[146:147], off
	v_lshl_add_u64 v[146:147], v[222:223], 0, s[10:11]
	s_mov_b32 m0, s20
	s_nop 0
	global_load_lds_dwordx4 v[146:147], off
	v_lshl_add_u64 v[146:147], v[224:225], 0, s[10:11]
	s_mov_b32 m0, s21
	s_nop 0
	global_load_lds_dwordx4 v[146:147], off
	s_waitcnt vmcnt(8) lgkmcnt(0)
	v_mfma_f32_16x16x32_bf16 v[62:65], v[154:157], v[188:191], v[62:65]
	v_mfma_f32_16x16x32_bf16 v[58:61], v[164:167], v[188:191], v[58:61]
	v_mfma_f32_16x16x32_bf16 v[46:49], v[154:157], v[196:199], v[46:49]
	v_mfma_f32_16x16x32_bf16 v[42:45], v[164:167], v[196:199], v[42:45]
	s_barrier
	s_setprio 1
	v_mfma_f32_16x16x32_bf16 v[30:33], v[154:157], v[204:207], v[30:33]
	v_mfma_f32_16x16x32_bf16 v[26:29], v[164:167], v[204:207], v[26:29]
	v_mfma_f32_16x16x32_bf16 v[14:17], v[154:157], v[212:215], v[14:17]
	v_mfma_f32_16x16x32_bf16 v[10:13], v[164:167], v[212:215], v[10:13]
	v_mfma_f32_16x16x32_bf16 v[62:65], v[158:161], v[192:195], v[62:65]
	v_mfma_f32_16x16x32_bf16 v[58:61], v[168:171], v[192:195], v[58:61]
	v_mfma_f32_16x16x32_bf16 v[46:49], v[158:161], v[200:203], v[46:49]
	v_mfma_f32_16x16x32_bf16 v[42:45], v[168:171], v[200:203], v[42:45]
	v_mfma_f32_16x16x32_bf16 v[30:33], v[158:161], v[208:211], v[30:33]
	v_mfma_f32_16x16x32_bf16 v[26:29], v[168:171], v[208:211], v[26:29]
	v_mfma_f32_16x16x32_bf16 v[14:17], v[158:161], v[216:219], v[14:17]
	v_mfma_f32_16x16x32_bf16 v[10:13], v[168:171], v[216:219], v[10:13]
	v_mfma_f32_16x16x32_bf16 v[54:57], v[172:175], v[188:191], v[54:57]
	v_mfma_f32_16x16x32_bf16 v[50:53], v[180:183], v[188:191], v[50:53]
	v_mfma_f32_16x16x32_bf16 v[38:41], v[172:175], v[196:199], v[38:41]
	v_mfma_f32_16x16x32_bf16 v[34:37], v[180:183], v[196:199], v[34:37]
	v_mfma_f32_16x16x32_bf16 v[22:25], v[172:175], v[204:207], v[22:25]
	v_mfma_f32_16x16x32_bf16 v[18:21], v[180:183], v[204:207], v[18:21]
	v_mfma_f32_16x16x32_bf16 v[6:9], v[172:175], v[212:215], v[6:9]
	v_mfma_f32_16x16x32_bf16 v[2:5], v[180:183], v[212:215], v[2:5]
	v_mfma_f32_16x16x32_bf16 v[54:57], v[176:179], v[192:195], v[54:57]
	v_mfma_f32_16x16x32_bf16 v[50:53], v[184:187], v[192:195], v[50:53]
	v_mfma_f32_16x16x32_bf16 v[38:41], v[176:179], v[200:203], v[38:41]
	v_mfma_f32_16x16x32_bf16 v[34:37], v[184:187], v[200:203], v[34:37]
	v_mfma_f32_16x16x32_bf16 v[22:25], v[176:179], v[208:211], v[22:25]
	v_mfma_f32_16x16x32_bf16 v[18:21], v[184:187], v[208:211], v[18:21]
	v_mfma_f32_16x16x32_bf16 v[6:9], v[176:179], v[216:219], v[6:9]
	v_mfma_f32_16x16x32_bf16 v[2:5], v[184:187], v[216:219], v[2:5]
	s_setprio 0
	s_barrier
	s_add_i32 s53, s53, 2
	s_add_u32 s34, s34, 0x100
	s_addc_u32 s35, s35, 0
	s_add_u32 s23, s23, 0x100
	s_addc_u32 s25, s25, 0
	s_cmp_gt_u32 s53, 29
	s_cbranch_scc0 .LBB0_1604
	s_and_b64 vcc, exec, s[12:13]
	s_cbranch_vccz .LBB0_1607
	s_barrier

.LBB0_1675:
	ds_read_b128 v[156:159], v191
	ds_read_b128 v[160:163], v191 offset:1024
	ds_read_b128 v[164:167], v191 offset:2048
	ds_read_b128 v[168:171], v191 offset:3072
	ds_read_b128 v[172:175], v192
	ds_read_b128 v[176:179], v192 offset:1024
	ds_read_b128 v[180:183], v192 offset:2048
	ds_read_b128 v[184:187], v192 offset:3072
	s_add_u32 s36, s30, 0xffea0080
	s_addc_u32 s37, s31, -1
	s_cmpk_eq_i32 s29, 0x54
	s_cselect_b32 s39, s25, s37
	s_cselect_b32 s38, s24, s36
	s_cselect_b32 s37, s5, s35
	s_cselect_b32 s36, s4, s34
	s_mov_b32 m0, s57
	v_lshl_add_u64 v[234:235], s[30:31], 0, v[150:151]
	ds_read_b128 v[202:205], v193
	ds_read_b128 v[206:209], v193 offset:1024
	ds_read_b128 v[210:213], v193 offset:2048
	ds_read_b128 v[214:217], v193 offset:3072
	ds_read_b128 v[218:221], v193 offset:4096
	ds_read_b128 v[222:225], v193 offset:5120
	ds_read_b128 v[226:229], v193 offset:6144
	ds_read_b128 v[230:233], v193 offset:7168
	global_load_lds_dwordx4 v[234:235], off
	v_lshl_add_u64 v[234:235], s[30:31], 0, v[152:153]
	s_mov_b32 m0, s58
	s_nop 0
	global_load_lds_dwordx4 v[234:235], off
	s_waitcnt vmcnt(8) lgkmcnt(0)
	v_mfma_f32_16x16x32_bf16 v[126:129], v[156:159], v[202:205], v[126:129]
	v_mfma_f32_16x16x32_bf16 v[122:125], v[164:167], v[202:205], v[122:125]
	v_mfma_f32_16x16x32_bf16 v[110:113], v[156:159], v[210:213], v[110:113]
	v_mfma_f32_16x16x32_bf16 v[106:109], v[164:167], v[210:213], v[106:109]
	s_barrier
	s_setprio 1
	v_mfma_f32_16x16x32_bf16 v[94:97], v[156:159], v[218:221], v[94:97]
	v_mfma_f32_16x16x32_bf16 v[90:93], v[164:167], v[218:221], v[90:93]
	v_mfma_f32_16x16x32_bf16 v[78:81], v[156:159], v[226:229], v[78:81]
	v_mfma_f32_16x16x32_bf16 v[74:77], v[164:167], v[226:229], v[74:77]
	v_mfma_f32_16x16x32_bf16 v[126:129], v[160:163], v[206:209], v[126:129]
	v_mfma_f32_16x16x32_bf16 v[122:125], v[168:171], v[206:209], v[122:125]
	v_mfma_f32_16x16x32_bf16 v[110:113], v[160:163], v[214:217], v[110:113]
	v_mfma_f32_16x16x32_bf16 v[106:109], v[168:171], v[214:217], v[106:109]
	v_mfma_f32_16x16x32_bf16 v[94:97], v[160:163], v[222:225], v[94:97]
	v_mfma_f32_16x16x32_bf16 v[90:93], v[168:171], v[222:225], v[90:93]
	v_mfma_f32_16x16x32_bf16 v[78:81], v[160:163], v[230:233], v[78:81]
	v_mfma_f32_16x16x32_bf16 v[74:77], v[168:171], v[230:233], v[74:77]
	v_mfma_f32_16x16x32_bf16 v[118:121], v[172:175], v[202:205], v[118:121]
	v_mfma_f32_16x16x32_bf16 v[114:117], v[180:183], v[202:205], v[114:117]
	v_mfma_f32_16x16x32_bf16 v[102:105], v[172:175], v[210:213], v[102:105]
	v_mfma_f32_16x16x32_bf16 v[98:101], v[180:183], v[210:213], v[98:101]
	v_mfma_f32_16x16x32_bf16 v[86:89], v[172:175], v[218:221], v[86:89]
	v_mfma_f32_16x16x32_bf16 v[82:85], v[180:183], v[218:221], v[82:85]
	v_mfma_f32_16x16x32_bf16 v[70:73], v[172:175], v[226:229], v[70:73]
	v_mfma_f32_16x16x32_bf16 v[66:69], v[180:183], v[226:229], v[66:69]
	v_mfma_f32_16x16x32_bf16 v[118:121], v[176:179], v[206:209], v[118:121]
	v_mfma_f32_16x16x32_bf16 v[114:117], v[184:187], v[206:209], v[114:117]
	v_mfma_f32_16x16x32_bf16 v[102:105], v[176:179], v[214:217], v[102:105]
	v_mfma_f32_16x16x32_bf16 v[98:101], v[184:187], v[214:217], v[98:101]
	v_mfma_f32_16x16x32_bf16 v[86:89], v[176:179], v[222:225], v[86:89]
	v_mfma_f32_16x16x32_bf16 v[82:85], v[184:187], v[222:225], v[82:85]
	v_mfma_f32_16x16x32_bf16 v[70:73], v[176:179], v[230:233], v[70:73]
	v_mfma_f32_16x16x32_bf16 v[66:69], v[184:187], v[230:233], v[66:69]
	s_setprio 0
	s_barrier
	s_mov_b32 m0, s59
	v_lshl_add_u64 v[234:235], s[36:37], 0, v[134:135]
	s_add_u32 s40, s36, 0x160000
	ds_read_b128 v[202:205], v193 offset:16384
	ds_read_b128 v[206:209], v193 offset:17408
	ds_read_b128 v[210:213], v193 offset:18432
	ds_read_b128 v[214:217], v193 offset:19456
	ds_read_b128 v[218:221], v193 offset:20480
	ds_read_b128 v[222:225], v193 offset:21504
	ds_read_b128 v[226:229], v193 offset:22528
	ds_read_b128 v[230:233], v193 offset:23552
	global_load_lds_dwordx4 v[234:235], off
	v_lshl_add_u64 v[236:237], s[36:37], 0, v[130:131]
	s_mov_b32 m0, s60
	s_addc_u32 s41, s37, 0
	global_load_lds_dwordx4 v[236:237], off
	v_lshl_add_u64 v[238:239], s[40:41], 0, v[134:135]
	s_mov_b32 m0, s61
	v_lshl_add_u64 v[240:241], s[38:39], 0, v[132:133]
	global_load_lds_dwordx4 v[238:239], off
	v_lshl_add_u64 v[238:239], s[40:41], 0, v[130:131]
	s_mov_b32 m0, s62
	s_nop 0
	global_load_lds_dwordx4 v[238:239], off
	v_lshl_add_u64 v[238:239], s[38:39], 0, v[136:137]
	s_mov_b32 m0, s48
	s_nop 0
	global_load_lds_dwordx4 v[238:239], off
	s_mov_b32 m0, s49
	s_nop 0
	global_load_lds_dwordx4 v[240:241], off
	s_waitcnt vmcnt(8) lgkmcnt(0)
	v_mfma_f32_16x16x32_bf16 v[62:65], v[156:159], v[202:205], v[62:65]
	v_mfma_f32_16x16x32_bf16 v[58:61], v[164:167], v[202:205], v[58:61]
	v_mfma_f32_16x16x32_bf16 v[46:49], v[156:159], v[210:213], v[46:49]
	v_mfma_f32_16x16x32_bf16 v[42:45], v[164:167], v[210:213], v[42:45]
	s_barrier
	s_setprio 1
	v_mfma_f32_16x16x32_bf16 v[30:33], v[156:159], v[218:221], v[30:33]
	v_mfma_f32_16x16x32_bf16 v[26:29], v[164:167], v[218:221], v[26:29]
	v_mfma_f32_16x16x32_bf16 v[14:17], v[156:159], v[226:229], v[14:17]
	v_mfma_f32_16x16x32_bf16 v[10:13], v[164:167], v[226:229], v[10:13]
	v_mfma_f32_16x16x32_bf16 v[62:65], v[160:163], v[206:209], v[62:65]
	v_mfma_f32_16x16x32_bf16 v[58:61], v[168:171], v[206:209], v[58:61]
	v_mfma_f32_16x16x32_bf16 v[46:49], v[160:163], v[214:217], v[46:49]
	v_mfma_f32_16x16x32_bf16 v[42:45], v[168:171], v[214:217], v[42:45]
	v_mfma_f32_16x16x32_bf16 v[30:33], v[160:163], v[222:225], v[30:33]
	v_mfma_f32_16x16x32_bf16 v[26:29], v[168:171], v[222:225], v[26:29]
	v_mfma_f32_16x16x32_bf16 v[14:17], v[160:163], v[230:233], v[14:17]
	v_mfma_f32_16x16x32_bf16 v[10:13], v[168:171], v[230:233], v[10:13]
	v_mfma_f32_16x16x32_bf16 v[54:57], v[172:175], v[202:205], v[54:57]
	v_mfma_f32_16x16x32_bf16 v[50:53], v[180:183], v[202:205], v[50:53]
	v_mfma_f32_16x16x32_bf16 v[38:41], v[172:175], v[210:213], v[38:41]
	v_mfma_f32_16x16x32_bf16 v[34:37], v[180:183], v[210:213], v[34:37]
	v_mfma_f32_16x16x32_bf16 v[22:25], v[172:175], v[218:221], v[22:25]
	v_mfma_f32_16x16x32_bf16 v[18:21], v[180:183], v[218:221], v[18:21]
	v_mfma_f32_16x16x32_bf16 v[6:9], v[172:175], v[226:229], v[6:9]
	v_mfma_f32_16x16x32_bf16 v[2:5], v[180:183], v[226:229], v[2:5]
	v_mfma_f32_16x16x32_bf16 v[54:57], v[176:179], v[206:209], v[54:57]
	v_mfma_f32_16x16x32_bf16 v[50:53], v[184:187], v[206:209], v[50:53]
	v_mfma_f32_16x16x32_bf16 v[38:41], v[176:179], v[214:217], v[38:41]
	v_mfma_f32_16x16x32_bf16 v[34:37], v[184:187], v[214:217], v[34:37]
	v_mfma_f32_16x16x32_bf16 v[22:25], v[176:179], v[222:225], v[22:25]
	v_mfma_f32_16x16x32_bf16 v[18:21], v[184:187], v[222:225], v[18:21]
	v_mfma_f32_16x16x32_bf16 v[6:9], v[176:179], v[230:233], v[6:9]
	v_mfma_f32_16x16x32_bf16 v[2:5], v[184:187], v[230:233], v[2:5]
	s_setprio 0
	s_barrier
	ds_read_b128 v[156:159], v197
	ds_read_b128 v[160:163], v197 offset:1024
	ds_read_b128 v[164:167], v197 offset:2048
	ds_read_b128 v[168:171], v197 offset:3072
	ds_read_b128 v[172:175], v198
	ds_read_b128 v[176:179], v198 offset:1024
	ds_read_b128 v[180:183], v198 offset:2048
	ds_read_b128 v[184:187], v198 offset:3072
	s_add_u32 s38, s38, 0x160000
	s_addc_u32 s39, s39, 0
	s_mov_b32 m0, s50
	v_lshl_add_u64 v[242:243], s[38:39], 0, v[136:137]
	ds_read_b128 v[202:205], v193 offset:32768
	ds_read_b128 v[206:209], v193 offset:33792
	ds_read_b128 v[210:213], v193 offset:34816
	ds_read_b128 v[214:217], v193 offset:35840
	ds_read_b128 v[218:221], v193 offset:36864
	ds_read_b128 v[222:225], v193 offset:37888
	ds_read_b128 v[226:229], v193 offset:38912
	ds_read_b128 v[230:233], v193 offset:39936
	global_load_lds_dwordx4 v[242:243], off
	v_lshl_add_u64 v[242:243], s[38:39], 0, v[132:133]
	s_mov_b32 m0, s51
	s_nop 0
	global_load_lds_dwordx4 v[242:243], off
	s_waitcnt vmcnt(8) lgkmcnt(0)
	v_mfma_f32_16x16x32_bf16 v[126:129], v[156:159], v[202:205], v[126:129]
	v_mfma_f32_16x16x32_bf16 v[122:125], v[164:167], v[202:205], v[122:125]
	v_mfma_f32_16x16x32_bf16 v[110:113], v[156:159], v[210:213], v[110:113]
	v_mfma_f32_16x16x32_bf16 v[106:109], v[164:167], v[210:213], v[106:109]
	s_barrier
	s_setprio 1
	v_mfma_f32_16x16x32_bf16 v[94:97], v[156:159], v[218:221], v[94:97]
	v_mfma_f32_16x16x32_bf16 v[90:93], v[164:167], v[218:221], v[90:93]
	v_mfma_f32_16x16x32_bf16 v[78:81], v[156:159], v[226:229], v[78:81]
	v_mfma_f32_16x16x32_bf16 v[74:77], v[164:167], v[226:229], v[74:77]
	v_mfma_f32_16x16x32_bf16 v[126:129], v[160:163], v[206:209], v[126:129]
	v_mfma_f32_16x16x32_bf16 v[122:125], v[168:171], v[206:209], v[122:125]
	v_mfma_f32_16x16x32_bf16 v[110:113], v[160:163], v[214:217], v[110:113]
	v_mfma_f32_16x16x32_bf16 v[106:109], v[168:171], v[214:217], v[106:109]
	v_mfma_f32_16x16x32_bf16 v[94:97], v[160:163], v[222:225], v[94:97]
	v_mfma_f32_16x16x32_bf16 v[90:93], v[168:171], v[222:225], v[90:93]
	v_mfma_f32_16x16x32_bf16 v[78:81], v[160:163], v[230:233], v[78:81]
	v_mfma_f32_16x16x32_bf16 v[74:77], v[168:171], v[230:233], v[74:77]
	v_mfma_f32_16x16x32_bf16 v[118:121], v[172:175], v[202:205], v[118:121]
	v_mfma_f32_16x16x32_bf16 v[114:117], v[180:183], v[202:205], v[114:117]
	v_mfma_f32_16x16x32_bf16 v[102:105], v[172:175], v[210:213], v[102:105]
	v_mfma_f32_16x16x32_bf16 v[98:101], v[180:183], v[210:213], v[98:101]
	v_mfma_f32_16x16x32_bf16 v[86:89], v[172:175], v[218:221], v[86:89]
	v_mfma_f32_16x16x32_bf16 v[82:85], v[180:183], v[218:221], v[82:85]
	v_mfma_f32_16x16x32_bf16 v[70:73], v[172:175], v[226:229], v[70:73]
	v_mfma_f32_16x16x32_bf16 v[66:69], v[180:183], v[226:229], v[66:69]
	v_mfma_f32_16x16x32_bf16 v[118:121], v[176:179], v[206:209], v[118:121]
	v_mfma_f32_16x16x32_bf16 v[114:117], v[184:187], v[206:209], v[114:117]
	v_mfma_f32_16x16x32_bf16 v[102:105], v[176:179], v[214:217], v[102:105]
	v_mfma_f32_16x16x32_bf16 v[98:101], v[184:187], v[214:217], v[98:101]
	v_mfma_f32_16x16x32_bf16 v[86:89], v[176:179], v[222:225], v[86:89]
	v_mfma_f32_16x16x32_bf16 v[82:85], v[184:187], v[222:225], v[82:85]
	v_mfma_f32_16x16x32_bf16 v[70:73], v[176:179], v[230:233], v[70:73]
	v_mfma_f32_16x16x32_bf16 v[66:69], v[184:187], v[230:233], v[66:69]
	s_setprio 0
	s_barrier
	s_mov_b32 m0, s64
	v_lshl_add_u64 v[234:235], v[234:235], 0, s[12:13]
	s_add_u32 s36, s36, 0x160080
	ds_read_b128 v[202:205], v193 offset:49152
	ds_read_b128 v[206:209], v193 offset:50176
	ds_read_b128 v[210:213], v193 offset:51200
	ds_read_b128 v[214:217], v193 offset:52224
	ds_read_b128 v[218:221], v193 offset:53248
	ds_read_b128 v[222:225], v193 offset:54272
	ds_read_b128 v[226:229], v193 offset:55296
	ds_read_b128 v[230:233], v193 offset:56320
	global_load_lds_dwordx4 v[234:235], off
	v_lshl_add_u64 v[234:235], v[236:237], 0, s[12:13]
	s_mov_b32 m0, s65
	s_addc_u32 s37, s37, 0
	s_add_i32 s38, s63, s47
	global_load_lds_dwordx4 v[234:235], off
	v_lshl_add_u64 v[234:235], s[36:37], 0, v[134:135]
	s_mov_b32 m0, s38
	s_nop 0
	global_load_lds_dwordx4 v[234:235], off
	v_lshl_add_u64 v[234:235], s[36:37], 0, v[130:131]
	s_add_i32 m0, s38, 0x2000
	s_nop 0
	global_load_lds_dwordx4 v[234:235], off
	v_lshl_add_u64 v[234:235], v[238:239], 0, s[12:13]
	s_mov_b32 m0, s55
	s_nop 0
	global_load_lds_dwordx4 v[234:235], off
	v_lshl_add_u64 v[234:235], v[240:241], 0, s[12:13]
	s_mov_b32 m0, s56
	s_nop 0
	global_load_lds_dwordx4 v[234:235], off
	s_waitcnt vmcnt(8) lgkmcnt(0)
	v_mfma_f32_16x16x32_bf16 v[62:65], v[156:159], v[202:205], v[62:65]
	v_mfma_f32_16x16x32_bf16 v[58:61], v[164:167], v[202:205], v[58:61]
	v_mfma_f32_16x16x32_bf16 v[46:49], v[156:159], v[210:213], v[46:49]
	v_mfma_f32_16x16x32_bf16 v[42:45], v[164:167], v[210:213], v[42:45]
	s_barrier
	s_setprio 1
	v_mfma_f32_16x16x32_bf16 v[30:33], v[156:159], v[218:221], v[30:33]
	v_mfma_f32_16x16x32_bf16 v[26:29], v[164:167], v[218:221], v[26:29]
	v_mfma_f32_16x16x32_bf16 v[14:17], v[156:159], v[226:229], v[14:17]
	v_mfma_f32_16x16x32_bf16 v[10:13], v[164:167], v[226:229], v[10:13]
	v_mfma_f32_16x16x32_bf16 v[62:65], v[160:163], v[206:209], v[62:65]
	v_mfma_f32_16x16x32_bf16 v[58:61], v[168:171], v[206:209], v[58:61]
	v_mfma_f32_16x16x32_bf16 v[46:49], v[160:163], v[214:217], v[46:49]
	v_mfma_f32_16x16x32_bf16 v[42:45], v[168:171], v[214:217], v[42:45]
	v_mfma_f32_16x16x32_bf16 v[30:33], v[160:163], v[222:225], v[30:33]
	v_mfma_f32_16x16x32_bf16 v[26:29], v[168:171], v[222:225], v[26:29]
	v_mfma_f32_16x16x32_bf16 v[14:17], v[160:163], v[230:233], v[14:17]
	v_mfma_f32_16x16x32_bf16 v[10:13], v[168:171], v[230:233], v[10:13]
	v_mfma_f32_16x16x32_bf16 v[54:57], v[172:175], v[202:205], v[54:57]
	v_mfma_f32_16x16x32_bf16 v[50:53], v[180:183], v[202:205], v[50:53]
	v_mfma_f32_16x16x32_bf16 v[38:41], v[172:175], v[210:213], v[38:41]
	v_mfma_f32_16x16x32_bf16 v[34:37], v[180:183], v[210:213], v[34:37]
	v_mfma_f32_16x16x32_bf16 v[22:25], v[172:175], v[218:221], v[22:25]
	v_mfma_f32_16x16x32_bf16 v[18:21], v[180:183], v[218:221], v[18:21]
	v_mfma_f32_16x16x32_bf16 v[6:9], v[172:175], v[226:229], v[6:9]
	v_mfma_f32_16x16x32_bf16 v[2:5], v[180:183], v[226:229], v[2:5]
	v_mfma_f32_16x16x32_bf16 v[54:57], v[176:179], v[206:209], v[54:57]
	v_mfma_f32_16x16x32_bf16 v[50:53], v[184:187], v[206:209], v[50:53]
	v_mfma_f32_16x16x32_bf16 v[38:41], v[176:179], v[214:217], v[38:41]
	v_mfma_f32_16x16x32_bf16 v[34:37], v[184:187], v[214:217], v[34:37]
	v_mfma_f32_16x16x32_bf16 v[22:25], v[176:179], v[222:225], v[22:25]
	v_mfma_f32_16x16x32_bf16 v[18:21], v[184:187], v[222:225], v[18:21]
	v_mfma_f32_16x16x32_bf16 v[6:9], v[176:179], v[230:233], v[6:9]
	v_mfma_f32_16x16x32_bf16 v[2:5], v[184:187], v[230:233], v[2:5]
	s_setprio 0
	s_barrier
	s_add_i32 s29, s29, 2
	s_add_u32 s30, s30, 0x100
	s_addc_u32 s31, s31, 0
	s_add_u32 s34, s34, 0x100
	s_addc_u32 s35, s35, 0
	s_cmpk_gt_u32 s29, 0x55
	s_cbranch_scc0 .LBB0_1675
	s_and_b64 vcc, exec, s[14:15]
	s_cbranch_vccz .LBB0_1678
	s_barrier
